# GLA/retention: LDS reads issued in first-use order with staged lgkmcnt waits
# speedup vs baseline: 1.0095x; 1.0095x over previous
.Lret2_loop:
	global_load_dword v84, v32, s[10:11]
	global_load_dword v85, v32, s[10:11] offset:-1024
	global_load_dword v86, v33, s[10:11]
	global_load_dword v87, v33, s[10:11] offset:-1024
	global_load_dword v88, v34, s[10:11]
	global_load_dword v90, v35, s[12:13]
	global_load_dword v91, v35, s[12:13] offset:4
	s_add_u32 s10, s10, 0x18000
	s_addc_u32 s11, s11, 0
	s_add_u32 s12, s12, 0x4000
	s_addc_u32 s13, s13, 0
	s_waitcnt lgkmcnt(4)
	v_pk_mul_f32 v[40:41], v[40:41], v[42:43]
	v_rcp_f32_e32 v40, v41
	s_nop 0
	v_pk_mul_f32 v[44:45], v[64:65], v[40:41] op_sel_hi:[1,0]
	s_waitcnt lgkmcnt(3)
	v_pk_fma_f32 v[6:7], v[44:45], v[48:49], v[6:7] op_sel_hi:[1,0,1]
	v_pk_mul_f32 v[38:39], v[6:7], v[48:49] op_sel:[0,1] op_sel_hi:[1,1]
	v_pk_fma_f32 v[8:9], v[44:45], v[50:51], v[8:9] op_sel_hi:[1,0,1]
	v_pk_fma_f32 v[38:39], v[8:9], v[50:51], v[38:39] op_sel:[0,1,0] op_sel_hi:[1,1,1]
	s_waitcnt lgkmcnt(2)
	v_pk_fma_f32 v[10:11], v[44:45], v[52:53], v[10:11] op_sel_hi:[1,0,1]
	v_pk_fma_f32 v[38:39], v[10:11], v[52:53], v[38:39] op_sel:[0,1,0] op_sel_hi:[1,1,1]
	v_pk_fma_f32 v[12:13], v[44:45], v[54:55], v[12:13] op_sel_hi:[1,0,1]
	v_pk_fma_f32 v[38:39], v[12:13], v[54:55], v[38:39] op_sel:[0,1,0] op_sel_hi:[1,1,1]
	s_waitcnt lgkmcnt(1)
	v_pk_fma_f32 v[14:15], v[44:45], v[56:57], v[14:15] op_sel_hi:[1,0,1]
	v_pk_fma_f32 v[38:39], v[14:15], v[56:57], v[38:39] op_sel:[0,1,0] op_sel_hi:[1,1,1]
	v_pk_fma_f32 v[16:17], v[44:45], v[58:59], v[16:17] op_sel_hi:[1,0,1]
	v_pk_fma_f32 v[38:39], v[16:17], v[58:59], v[38:39] op_sel:[0,1,0] op_sel_hi:[1,1,1]
	s_waitcnt lgkmcnt(0)
	v_pk_fma_f32 v[18:19], v[44:45], v[60:61], v[18:19] op_sel_hi:[1,0,1]
	v_pk_fma_f32 v[38:39], v[18:19], v[60:61], v[38:39] op_sel:[0,1,0] op_sel_hi:[1,1,1]
	v_pk_fma_f32 v[20:21], v[44:45], v[62:63], v[20:21] op_sel_hi:[1,0,1]
	v_pk_fma_f32 v[38:39], v[20:21], v[62:63], v[38:39] op_sel:[0,1,0] op_sel_hi:[1,1,1]
	s_add_u32 s14, s14, 0x1000
	s_addc_u32 s15, s15, 0
	v_add_f32_dpp v38, v38, v38 row_ror:8 row_mask:0xf bank_mask:0x3 bound_ctrl:1
	v_add_f32_dpp v38, v39, v39 row_ror:8 row_mask:0xf bank_mask:0xc bound_ctrl:1
	ds_read_b64 v[82:83], v3 offset:20992
	ds_read_b128 v[66:69], v2 offset:9472
	v_add_f32_dpp v38, v38, v38 row_half_mirror row_mask:0xf bank_mask:0xf bound_ctrl:1
	ds_read_b128 v[70:73], v2 offset:9728
	ds_read_b128 v[74:77], v2 offset:9984
	v_add_f32_dpp v38, v38, v38 quad_perm:[1,0,3,2] row_mask:0xf bank_mask:0xf bound_ctrl:1
	ds_read_b128 v[78:81], v2 offset:10240
	s_nop 0
	v_add_f32_dpp v38, v38, v38 quad_perm:[2,3,0,1] row_mask:0xf bank_mask:0xf bound_ctrl:1
	s_nop 1
	v_mov_b32_dpp v39, v38 row_ror:8 row_mask:0xf bank_mask:0xf bound_ctrl:1
	v_pk_mul_f32 v[38:39], v[38:39], v[40:41] op_sel:[0,1] op_sel_hi:[1,1]
	v_cvt_pk_bf16_f32 v47, v38, v39
	s_mov_b64 exec, s[2:3]
	global_store_dword v46, v47, s[14:15] offset:-4096
	s_mov_b64 exec, -1
	s_waitcnt lgkmcnt(4)
	v_pk_mul_f32 v[40:41], v[40:41], v[42:43]
	v_pk_mul_f32 v[44:45], v[82:83], v[40:41] op_sel_hi:[1,0]
	s_waitcnt lgkmcnt(3)
	v_pk_fma_f32 v[6:7], v[44:45], v[66:67], v[6:7] op_sel_hi:[1,0,1]
	v_pk_mul_f32 v[38:39], v[6:7], v[66:67] op_sel:[0,1] op_sel_hi:[1,1]
	v_pk_fma_f32 v[8:9], v[44:45], v[68:69], v[8:9] op_sel_hi:[1,0,1]
	v_pk_fma_f32 v[38:39], v[8:9], v[68:69], v[38:39] op_sel:[0,1,0] op_sel_hi:[1,1,1]
	s_waitcnt lgkmcnt(2)
	v_pk_fma_f32 v[10:11], v[44:45], v[70:71], v[10:11] op_sel_hi:[1,0,1]
	v_pk_fma_f32 v[38:39], v[10:11], v[70:71], v[38:39] op_sel:[0,1,0] op_sel_hi:[1,1,1]
	v_pk_fma_f32 v[12:13], v[44:45], v[72:73], v[12:13] op_sel_hi:[1,0,1]
	v_pk_fma_f32 v[38:39], v[12:13], v[72:73], v[38:39] op_sel:[0,1,0] op_sel_hi:[1,1,1]
	s_waitcnt lgkmcnt(1)
	v_pk_fma_f32 v[14:15], v[44:45], v[74:75], v[14:15] op_sel_hi:[1,0,1]
	v_pk_fma_f32 v[38:39], v[14:15], v[74:75], v[38:39] op_sel:[0,1,0] op_sel_hi:[1,1,1]
	v_pk_fma_f32 v[16:17], v[44:45], v[76:77], v[16:17] op_sel_hi:[1,0,1]
	v_pk_fma_f32 v[38:39], v[16:17], v[76:77], v[38:39] op_sel:[0,1,0] op_sel_hi:[1,1,1]
	s_waitcnt lgkmcnt(0)
	v_pk_fma_f32 v[18:19], v[44:45], v[78:79], v[18:19] op_sel_hi:[1,0,1]
	v_pk_fma_f32 v[38:39], v[18:19], v[78:79], v[38:39] op_sel:[0,1,0] op_sel_hi:[1,1,1]
	v_pk_fma_f32 v[20:21], v[44:45], v[80:81], v[20:21] op_sel_hi:[1,0,1]
	v_pk_fma_f32 v[38:39], v[20:21], v[80:81], v[38:39] op_sel:[0,1,0] op_sel_hi:[1,1,1]
	s_add_u32 s14, s14, 0x1000
	s_addc_u32 s15, s15, 0
	v_add_f32_dpp v38, v38, v38 row_ror:8 row_mask:0xf bank_mask:0x3 bound_ctrl:1
	v_add_f32_dpp v38, v39, v39 row_ror:8 row_mask:0xf bank_mask:0xc bound_ctrl:1
	ds_read_b64 v[64:65], v3 offset:21248
	ds_read_b128 v[48:51], v2 offset:10496
	v_add_f32_dpp v38, v38, v38 row_half_mirror row_mask:0xf bank_mask:0xf bound_ctrl:1
	ds_read_b128 v[52:55], v2 offset:10752
	ds_read_b128 v[56:59], v2 offset:11008
	v_add_f32_dpp v38, v38, v38 quad_perm:[1,0,3,2] row_mask:0xf bank_mask:0xf bound_ctrl:1
	ds_read_b128 v[60:63], v2 offset:11264
	s_nop 0
	v_add_f32_dpp v38, v38, v38 quad_perm:[2,3,0,1] row_mask:0xf bank_mask:0xf bound_ctrl:1
	s_nop 1
	v_mov_b32_dpp v39, v38 row_ror:8 row_mask:0xf bank_mask:0xf bound_ctrl:1
	v_pk_mul_f32 v[38:39], v[38:39], v[40:41] op_sel:[0,1] op_sel_hi:[1,1]
	v_cvt_pk_bf16_f32 v47, v38, v39
	s_mov_b64 exec, s[2:3]
	global_store_dword v46, v47, s[14:15] offset:-4096
	s_mov_b64 exec, -1
	s_waitcnt lgkmcnt(4)
	v_pk_mul_f32 v[40:41], v[40:41], v[42:43]
	v_pk_mul_f32 v[44:45], v[64:65], v[40:41] op_sel_hi:[1,0]
	s_waitcnt lgkmcnt(3)
	v_pk_fma_f32 v[6:7], v[44:45], v[48:49], v[6:7] op_sel_hi:[1,0,1]
	v_pk_mul_f32 v[38:39], v[6:7], v[48:49] op_sel:[0,1] op_sel_hi:[1,1]
	v_pk_fma_f32 v[8:9], v[44:45], v[50:51], v[8:9] op_sel_hi:[1,0,1]
	v_pk_fma_f32 v[38:39], v[8:9], v[50:51], v[38:39] op_sel:[0,1,0] op_sel_hi:[1,1,1]
	s_waitcnt lgkmcnt(2)
	v_pk_fma_f32 v[10:11], v[44:45], v[52:53], v[10:11] op_sel_hi:[1,0,1]
	v_pk_fma_f32 v[38:39], v[10:11], v[52:53], v[38:39] op_sel:[0,1,0] op_sel_hi:[1,1,1]
	v_pk_fma_f32 v[12:13], v[44:45], v[54:55], v[12:13] op_sel_hi:[1,0,1]
	v_pk_fma_f32 v[38:39], v[12:13], v[54:55], v[38:39] op_sel:[0,1,0] op_sel_hi:[1,1,1]
	s_waitcnt lgkmcnt(1)
	v_pk_fma_f32 v[14:15], v[44:45], v[56:57], v[14:15] op_sel_hi:[1,0,1]
	v_pk_fma_f32 v[38:39], v[14:15], v[56:57], v[38:39] op_sel:[0,1,0] op_sel_hi:[1,1,1]
	v_pk_fma_f32 v[16:17], v[44:45], v[58:59], v[16:17] op_sel_hi:[1,0,1]
	v_pk_fma_f32 v[38:39], v[16:17], v[58:59], v[38:39] op_sel:[0,1,0] op_sel_hi:[1,1,1]
	s_waitcnt lgkmcnt(0)
	v_pk_fma_f32 v[18:19], v[44:45], v[60:61], v[18:19] op_sel_hi:[1,0,1]
	v_pk_fma_f32 v[38:39], v[18:19], v[60:61], v[38:39] op_sel:[0,1,0] op_sel_hi:[1,1,1]
	v_pk_fma_f32 v[20:21], v[44:45], v[62:63], v[20:21] op_sel_hi:[1,0,1]
	v_pk_fma_f32 v[38:39], v[20:21], v[62:63], v[38:39] op_sel:[0,1,0] op_sel_hi:[1,1,1]
	s_add_u32 s14, s14, 0x1000
	s_addc_u32 s15, s15, 0
	v_add_f32_dpp v38, v38, v38 row_ror:8 row_mask:0xf bank_mask:0x3 bound_ctrl:1
	v_add_f32_dpp v38, v39, v39 row_ror:8 row_mask:0xf bank_mask:0xc bound_ctrl:1
	ds_read_b64 v[82:83], v3 offset:21504
	ds_read_b128 v[66:69], v2 offset:11520
	v_add_f32_dpp v38, v38, v38 row_half_mirror row_mask:0xf bank_mask:0xf bound_ctrl:1
	ds_read_b128 v[70:73], v2 offset:11776
	ds_read_b128 v[74:77], v2 offset:12032
	v_add_f32_dpp v38, v38, v38 quad_perm:[1,0,3,2] row_mask:0xf bank_mask:0xf bound_ctrl:1
	ds_read_b128 v[78:81], v2 offset:12288
	s_nop 0
	v_add_f32_dpp v38, v38, v38 quad_perm:[2,3,0,1] row_mask:0xf bank_mask:0xf bound_ctrl:1
	s_nop 1
	v_mov_b32_dpp v39, v38 row_ror:8 row_mask:0xf bank_mask:0xf bound_ctrl:1
	v_pk_mul_f32 v[38:39], v[38:39], v[40:41] op_sel:[0,1] op_sel_hi:[1,1]
	v_cvt_pk_bf16_f32 v47, v38, v39
	s_mov_b64 exec, s[2:3]
	global_store_dword v46, v47, s[14:15] offset:-4096
	s_mov_b64 exec, -1
	s_waitcnt lgkmcnt(4)
	v_pk_mul_f32 v[40:41], v[40:41], v[42:43]
	v_pk_mul_f32 v[44:45], v[82:83], v[40:41] op_sel_hi:[1,0]
	s_waitcnt lgkmcnt(3)
	v_pk_fma_f32 v[6:7], v[44:45], v[66:67], v[6:7] op_sel_hi:[1,0,1]
	v_pk_mul_f32 v[38:39], v[6:7], v[66:67] op_sel:[0,1] op_sel_hi:[1,1]
	v_pk_fma_f32 v[8:9], v[44:45], v[68:69], v[8:9] op_sel_hi:[1,0,1]
	v_pk_fma_f32 v[38:39], v[8:9], v[68:69], v[38:39] op_sel:[0,1,0] op_sel_hi:[1,1,1]
	s_waitcnt lgkmcnt(2)
	v_pk_fma_f32 v[10:11], v[44:45], v[70:71], v[10:11] op_sel_hi:[1,0,1]
	v_pk_fma_f32 v[38:39], v[10:11], v[70:71], v[38:39] op_sel:[0,1,0] op_sel_hi:[1,1,1]
	v_pk_fma_f32 v[12:13], v[44:45], v[72:73], v[12:13] op_sel_hi:[1,0,1]
	v_pk_fma_f32 v[38:39], v[12:13], v[72:73], v[38:39] op_sel:[0,1,0] op_sel_hi:[1,1,1]
	s_waitcnt lgkmcnt(1)
	v_pk_fma_f32 v[14:15], v[44:45], v[74:75], v[14:15] op_sel_hi:[1,0,1]
	v_pk_fma_f32 v[38:39], v[14:15], v[74:75], v[38:39] op_sel:[0,1,0] op_sel_hi:[1,1,1]
	v_pk_fma_f32 v[16:17], v[44:45], v[76:77], v[16:17] op_sel_hi:[1,0,1]
	v_pk_fma_f32 v[38:39], v[16:17], v[76:77], v[38:39] op_sel:[0,1,0] op_sel_hi:[1,1,1]
	s_waitcnt lgkmcnt(0)
	v_pk_fma_f32 v[18:19], v[44:45], v[78:79], v[18:19] op_sel_hi:[1,0,1]
	v_pk_fma_f32 v[38:39], v[18:19], v[78:79], v[38:39] op_sel:[0,1,0] op_sel_hi:[1,1,1]
	v_pk_fma_f32 v[20:21], v[44:45], v[80:81], v[20:21] op_sel_hi:[1,0,1]
	v_pk_fma_f32 v[38:39], v[20:21], v[80:81], v[38:39] op_sel:[0,1,0] op_sel_hi:[1,1,1]
	s_add_u32 s14, s14, 0x1000
	s_addc_u32 s15, s15, 0
	v_add_f32_dpp v38, v38, v38 row_ror:8 row_mask:0xf bank_mask:0x3 bound_ctrl:1
	v_add_f32_dpp v38, v39, v39 row_ror:8 row_mask:0xf bank_mask:0xc bound_ctrl:1
	ds_read_b64 v[64:65], v3 offset:21760
	ds_read_b128 v[48:51], v2 offset:12544
	v_add_f32_dpp v38, v38, v38 row_half_mirror row_mask:0xf bank_mask:0xf bound_ctrl:1
	ds_read_b128 v[52:55], v2 offset:12800
	ds_read_b128 v[56:59], v2 offset:13056
	v_add_f32_dpp v38, v38, v38 quad_perm:[1,0,3,2] row_mask:0xf bank_mask:0xf bound_ctrl:1
	ds_read_b128 v[60:63], v2 offset:13312
	s_nop 0
	v_add_f32_dpp v38, v38, v38 quad_perm:[2,3,0,1] row_mask:0xf bank_mask:0xf bound_ctrl:1
	s_nop 1
	v_mov_b32_dpp v39, v38 row_ror:8 row_mask:0xf bank_mask:0xf bound_ctrl:1
	v_pk_mul_f32 v[38:39], v[38:39], v[40:41] op_sel:[0,1] op_sel_hi:[1,1]
	v_cvt_pk_bf16_f32 v47, v38, v39
	s_mov_b64 exec, s[2:3]
	global_store_dword v46, v47, s[14:15] offset:-4096
	s_mov_b64 exec, -1
	s_waitcnt lgkmcnt(4)
	v_pk_mul_f32 v[40:41], v[40:41], v[42:43]
	v_pk_mul_f32 v[44:45], v[64:65], v[40:41] op_sel_hi:[1,0]
	s_waitcnt lgkmcnt(3)
	v_pk_fma_f32 v[6:7], v[44:45], v[48:49], v[6:7] op_sel_hi:[1,0,1]
	v_pk_mul_f32 v[38:39], v[6:7], v[48:49] op_sel:[0,1] op_sel_hi:[1,1]
	v_pk_fma_f32 v[8:9], v[44:45], v[50:51], v[8:9] op_sel_hi:[1,0,1]
	v_pk_fma_f32 v[38:39], v[8:9], v[50:51], v[38:39] op_sel:[0,1,0] op_sel_hi:[1,1,1]
	s_waitcnt lgkmcnt(2)
	v_pk_fma_f32 v[10:11], v[44:45], v[52:53], v[10:11] op_sel_hi:[1,0,1]
	v_pk_fma_f32 v[38:39], v[10:11], v[52:53], v[38:39] op_sel:[0,1,0] op_sel_hi:[1,1,1]
	v_pk_fma_f32 v[12:13], v[44:45], v[54:55], v[12:13] op_sel_hi:[1,0,1]
	v_pk_fma_f32 v[38:39], v[12:13], v[54:55], v[38:39] op_sel:[0,1,0] op_sel_hi:[1,1,1]
	s_waitcnt lgkmcnt(1)
	v_pk_fma_f32 v[14:15], v[44:45], v[56:57], v[14:15] op_sel_hi:[1,0,1]
	v_pk_fma_f32 v[38:39], v[14:15], v[56:57], v[38:39] op_sel:[0,1,0] op_sel_hi:[1,1,1]
	v_pk_fma_f32 v[16:17], v[44:45], v[58:59], v[16:17] op_sel_hi:[1,0,1]
	v_pk_fma_f32 v[38:39], v[16:17], v[58:59], v[38:39] op_sel:[0,1,0] op_sel_hi:[1,1,1]
	s_waitcnt lgkmcnt(0)
	v_pk_fma_f32 v[18:19], v[44:45], v[60:61], v[18:19] op_sel_hi:[1,0,1]
	v_pk_fma_f32 v[38:39], v[18:19], v[60:61], v[38:39] op_sel:[0,1,0] op_sel_hi:[1,1,1]
	v_pk_fma_f32 v[20:21], v[44:45], v[62:63], v[20:21] op_sel_hi:[1,0,1]
	v_pk_fma_f32 v[38:39], v[20:21], v[62:63], v[38:39] op_sel:[0,1,0] op_sel_hi:[1,1,1]
	s_add_u32 s14, s14, 0x1000
	s_addc_u32 s15, s15, 0
	v_add_f32_dpp v38, v38, v38 row_ror:8 row_mask:0xf bank_mask:0x3 bound_ctrl:1
	v_add_f32_dpp v38, v39, v39 row_ror:8 row_mask:0xf bank_mask:0xc bound_ctrl:1
	ds_read_b64 v[82:83], v3 offset:22016
	ds_read_b128 v[66:69], v2 offset:13568
	v_add_f32_dpp v38, v38, v38 row_half_mirror row_mask:0xf bank_mask:0xf bound_ctrl:1
	ds_read_b128 v[70:73], v2 offset:13824
	ds_read_b128 v[74:77], v2 offset:14080
	v_add_f32_dpp v38, v38, v38 quad_perm:[1,0,3,2] row_mask:0xf bank_mask:0xf bound_ctrl:1
	ds_read_b128 v[78:81], v2 offset:14336
	s_nop 0
	v_add_f32_dpp v38, v38, v38 quad_perm:[2,3,0,1] row_mask:0xf bank_mask:0xf bound_ctrl:1
	s_nop 1
	v_mov_b32_dpp v39, v38 row_ror:8 row_mask:0xf bank_mask:0xf bound_ctrl:1
	v_pk_mul_f32 v[38:39], v[38:39], v[40:41] op_sel:[0,1] op_sel_hi:[1,1]
	v_cvt_pk_bf16_f32 v47, v38, v39
	s_mov_b64 exec, s[2:3]
	global_store_dword v46, v47, s[14:15] offset:-4096
	s_mov_b64 exec, -1
	s_waitcnt lgkmcnt(4)
	v_pk_mul_f32 v[40:41], v[40:41], v[42:43]
	v_pk_mul_f32 v[44:45], v[82:83], v[40:41] op_sel_hi:[1,0]
	s_waitcnt lgkmcnt(3)
	v_pk_fma_f32 v[6:7], v[44:45], v[66:67], v[6:7] op_sel_hi:[1,0,1]
	v_pk_mul_f32 v[38:39], v[6:7], v[66:67] op_sel:[0,1] op_sel_hi:[1,1]
	v_pk_fma_f32 v[8:9], v[44:45], v[68:69], v[8:9] op_sel_hi:[1,0,1]
	v_pk_fma_f32 v[38:39], v[8:9], v[68:69], v[38:39] op_sel:[0,1,0] op_sel_hi:[1,1,1]
	s_waitcnt lgkmcnt(2)
	v_pk_fma_f32 v[10:11], v[44:45], v[70:71], v[10:11] op_sel_hi:[1,0,1]
	v_pk_fma_f32 v[38:39], v[10:11], v[70:71], v[38:39] op_sel:[0,1,0] op_sel_hi:[1,1,1]
	v_pk_fma_f32 v[12:13], v[44:45], v[72:73], v[12:13] op_sel_hi:[1,0,1]
	v_pk_fma_f32 v[38:39], v[12:13], v[72:73], v[38:39] op_sel:[0,1,0] op_sel_hi:[1,1,1]
	s_waitcnt lgkmcnt(1)
	v_pk_fma_f32 v[14:15], v[44:45], v[74:75], v[14:15] op_sel_hi:[1,0,1]
	v_pk_fma_f32 v[38:39], v[14:15], v[74:75], v[38:39] op_sel:[0,1,0] op_sel_hi:[1,1,1]
	v_pk_fma_f32 v[16:17], v[44:45], v[76:77], v[16:17] op_sel_hi:[1,0,1]
	v_pk_fma_f32 v[38:39], v[16:17], v[76:77], v[38:39] op_sel:[0,1,0] op_sel_hi:[1,1,1]
	s_waitcnt lgkmcnt(0)
	v_pk_fma_f32 v[18:19], v[44:45], v[78:79], v[18:19] op_sel_hi:[1,0,1]
	v_pk_fma_f32 v[38:39], v[18:19], v[78:79], v[38:39] op_sel:[0,1,0] op_sel_hi:[1,1,1]
	v_pk_fma_f32 v[20:21], v[44:45], v[80:81], v[20:21] op_sel_hi:[1,0,1]
	v_pk_fma_f32 v[38:39], v[20:21], v[80:81], v[38:39] op_sel:[0,1,0] op_sel_hi:[1,1,1]
	s_add_u32 s14, s14, 0x1000
	s_addc_u32 s15, s15, 0
	v_add_f32_dpp v38, v38, v38 row_ror:8 row_mask:0xf bank_mask:0x3 bound_ctrl:1
	v_add_f32_dpp v38, v39, v39 row_ror:8 row_mask:0xf bank_mask:0xc bound_ctrl:1
	ds_read_b64 v[64:65], v3 offset:22272
	ds_read_b128 v[48:51], v2 offset:14592
	v_add_f32_dpp v38, v38, v38 row_half_mirror row_mask:0xf bank_mask:0xf bound_ctrl:1
	ds_read_b128 v[52:55], v2 offset:14848
	ds_read_b128 v[56:59], v2 offset:15104
	v_add_f32_dpp v38, v38, v38 quad_perm:[1,0,3,2] row_mask:0xf bank_mask:0xf bound_ctrl:1
	ds_read_b128 v[60:63], v2 offset:15360
	s_nop 0
	v_add_f32_dpp v38, v38, v38 quad_perm:[2,3,0,1] row_mask:0xf bank_mask:0xf bound_ctrl:1
	s_nop 1
	v_mov_b32_dpp v39, v38 row_ror:8 row_mask:0xf bank_mask:0xf bound_ctrl:1
	v_pk_mul_f32 v[38:39], v[38:39], v[40:41] op_sel:[0,1] op_sel_hi:[1,1]
	v_cvt_pk_bf16_f32 v47, v38, v39
	s_mov_b64 exec, s[2:3]
	global_store_dword v46, v47, s[14:15] offset:-4096
	s_mov_b64 exec, -1
	s_waitcnt lgkmcnt(4)
	v_pk_mul_f32 v[40:41], v[40:41], v[42:43]
	v_pk_mul_f32 v[44:45], v[64:65], v[40:41] op_sel_hi:[1,0]
	s_waitcnt lgkmcnt(3)
	v_pk_fma_f32 v[6:7], v[44:45], v[48:49], v[6:7] op_sel_hi:[1,0,1]
	v_pk_mul_f32 v[38:39], v[6:7], v[48:49] op_sel:[0,1] op_sel_hi:[1,1]
	v_pk_fma_f32 v[8:9], v[44:45], v[50:51], v[8:9] op_sel_hi:[1,0,1]
	v_pk_fma_f32 v[38:39], v[8:9], v[50:51], v[38:39] op_sel:[0,1,0] op_sel_hi:[1,1,1]
	s_waitcnt lgkmcnt(2)
	v_pk_fma_f32 v[10:11], v[44:45], v[52:53], v[10:11] op_sel_hi:[1,0,1]
	v_pk_fma_f32 v[38:39], v[10:11], v[52:53], v[38:39] op_sel:[0,1,0] op_sel_hi:[1,1,1]
	v_pk_fma_f32 v[12:13], v[44:45], v[54:55], v[12:13] op_sel_hi:[1,0,1]
	v_pk_fma_f32 v[38:39], v[12:13], v[54:55], v[38:39] op_sel:[0,1,0] op_sel_hi:[1,1,1]
	s_waitcnt lgkmcnt(1)
	v_pk_fma_f32 v[14:15], v[44:45], v[56:57], v[14:15] op_sel_hi:[1,0,1]
	v_pk_fma_f32 v[38:39], v[14:15], v[56:57], v[38:39] op_sel:[0,1,0] op_sel_hi:[1,1,1]
	v_pk_fma_f32 v[16:17], v[44:45], v[58:59], v[16:17] op_sel_hi:[1,0,1]
	v_pk_fma_f32 v[38:39], v[16:17], v[58:59], v[38:39] op_sel:[0,1,0] op_sel_hi:[1,1,1]
	s_waitcnt lgkmcnt(0)
	v_pk_fma_f32 v[18:19], v[44:45], v[60:61], v[18:19] op_sel_hi:[1,0,1]
	v_pk_fma_f32 v[38:39], v[18:19], v[60:61], v[38:39] op_sel:[0,1,0] op_sel_hi:[1,1,1]
	v_pk_fma_f32 v[20:21], v[44:45], v[62:63], v[20:21] op_sel_hi:[1,0,1]
	v_pk_fma_f32 v[38:39], v[20:21], v[62:63], v[38:39] op_sel:[0,1,0] op_sel_hi:[1,1,1]
	s_add_u32 s14, s14, 0x1000
	s_addc_u32 s15, s15, 0
	v_add_f32_dpp v38, v38, v38 row_ror:8 row_mask:0xf bank_mask:0x3 bound_ctrl:1
	v_add_f32_dpp v38, v39, v39 row_ror:8 row_mask:0xf bank_mask:0xc bound_ctrl:1
	ds_read_b64 v[82:83], v3 offset:22528
	ds_read_b128 v[66:69], v2 offset:15616
	v_add_f32_dpp v38, v38, v38 row_half_mirror row_mask:0xf bank_mask:0xf bound_ctrl:1
	ds_read_b128 v[70:73], v2 offset:15872
	ds_read_b128 v[74:77], v2 offset:16128
	v_add_f32_dpp v38, v38, v38 quad_perm:[1,0,3,2] row_mask:0xf bank_mask:0xf bound_ctrl:1
	ds_read_b128 v[78:81], v2 offset:16384
	s_nop 0
	v_add_f32_dpp v38, v38, v38 quad_perm:[2,3,0,1] row_mask:0xf bank_mask:0xf bound_ctrl:1
	s_nop 1
	v_mov_b32_dpp v39, v38 row_ror:8 row_mask:0xf bank_mask:0xf bound_ctrl:1
	v_pk_mul_f32 v[38:39], v[38:39], v[40:41] op_sel:[0,1] op_sel_hi:[1,1]
	v_cvt_pk_bf16_f32 v47, v38, v39
	s_mov_b64 exec, s[2:3]
	global_store_dword v46, v47, s[14:15] offset:-4096
	s_mov_b64 exec, -1
	s_waitcnt lgkmcnt(4)
	v_pk_mul_f32 v[40:41], v[40:41], v[42:43]
	v_pk_mul_f32 v[44:45], v[82:83], v[40:41] op_sel_hi:[1,0]
	s_waitcnt lgkmcnt(3)
	v_pk_fma_f32 v[6:7], v[44:45], v[66:67], v[6:7] op_sel_hi:[1,0,1]
	v_pk_mul_f32 v[38:39], v[6:7], v[66:67] op_sel:[0,1] op_sel_hi:[1,1]
	v_pk_fma_f32 v[8:9], v[44:45], v[68:69], v[8:9] op_sel_hi:[1,0,1]
	v_pk_fma_f32 v[38:39], v[8:9], v[68:69], v[38:39] op_sel:[0,1,0] op_sel_hi:[1,1,1]
	s_waitcnt lgkmcnt(2)
	v_pk_fma_f32 v[10:11], v[44:45], v[70:71], v[10:11] op_sel_hi:[1,0,1]
	v_pk_fma_f32 v[38:39], v[10:11], v[70:71], v[38:39] op_sel:[0,1,0] op_sel_hi:[1,1,1]
	v_pk_fma_f32 v[12:13], v[44:45], v[72:73], v[12:13] op_sel_hi:[1,0,1]
	v_pk_fma_f32 v[38:39], v[12:13], v[72:73], v[38:39] op_sel:[0,1,0] op_sel_hi:[1,1,1]
	s_waitcnt lgkmcnt(1)
	v_pk_fma_f32 v[14:15], v[44:45], v[74:75], v[14:15] op_sel_hi:[1,0,1]
	v_pk_fma_f32 v[38:39], v[14:15], v[74:75], v[38:39] op_sel:[0,1,0] op_sel_hi:[1,1,1]
	v_pk_fma_f32 v[16:17], v[44:45], v[76:77], v[16:17] op_sel_hi:[1,0,1]
	v_pk_fma_f32 v[38:39], v[16:17], v[76:77], v[38:39] op_sel:[0,1,0] op_sel_hi:[1,1,1]
	s_waitcnt lgkmcnt(0)
	v_pk_fma_f32 v[18:19], v[44:45], v[78:79], v[18:19] op_sel_hi:[1,0,1]
	v_pk_fma_f32 v[38:39], v[18:19], v[78:79], v[38:39] op_sel:[0,1,0] op_sel_hi:[1,1,1]
	v_pk_fma_f32 v[20:21], v[44:45], v[80:81], v[20:21] op_sel_hi:[1,0,1]
	v_pk_fma_f32 v[38:39], v[20:21], v[80:81], v[38:39] op_sel:[0,1,0] op_sel_hi:[1,1,1]
	s_add_u32 s14, s14, 0x1000
	s_addc_u32 s15, s15, 0
	v_add_f32_dpp v38, v38, v38 row_ror:8 row_mask:0xf bank_mask:0x3 bound_ctrl:1
	v_add_f32_dpp v38, v39, v39 row_ror:8 row_mask:0xf bank_mask:0xc bound_ctrl:1
	ds_read_b64 v[64:65], v3 offset:45312
	ds_read_b128 v[48:51], v2 offset:33024
	v_add_f32_dpp v38, v38, v38 row_half_mirror row_mask:0xf bank_mask:0xf bound_ctrl:1
	ds_read_b128 v[52:55], v2 offset:33280
	ds_read_b128 v[56:59], v2 offset:33536
	v_add_f32_dpp v38, v38, v38 quad_perm:[1,0,3,2] row_mask:0xf bank_mask:0xf bound_ctrl:1
	ds_read_b128 v[60:63], v2 offset:33792
	s_nop 0
	v_add_f32_dpp v38, v38, v38 quad_perm:[2,3,0,1] row_mask:0xf bank_mask:0xf bound_ctrl:1
	s_nop 1
	v_mov_b32_dpp v39, v38 row_ror:8 row_mask:0xf bank_mask:0xf bound_ctrl:1
	v_pk_mul_f32 v[38:39], v[38:39], v[40:41] op_sel:[0,1] op_sel_hi:[1,1]
	v_cvt_pk_bf16_f32 v47, v38, v39
	s_mov_b64 exec, s[2:3]
	global_store_dword v46, v47, s[14:15] offset:-4096
	s_mov_b64 exec, -1
	s_waitcnt vmcnt(8)
	v_lshlrev_b32_e32 v108, 16, v84
	v_lshlrev_b32_e32 v109, 16, v85
	v_and_b32_e32 v110, s17, v84
	v_and_b32_e32 v111, s17, v85
	v_lshlrev_b32_e32 v112, 16, v86
	v_lshlrev_b32_e32 v113, 16, v87
	v_and_b32_e32 v114, s17, v86
	v_and_b32_e32 v115, s17, v87
	v_lshlrev_b32_e32 v116, 16, v88
	v_and_b32_e32 v117, s17, v88
	ds_write_b128 v29, v[108:111] offset:49408
	ds_write_b128 v29, v[112:115] offset:57600
	ds_write_b64 v30, v[90:91] offset:49408
	ds_write_b64 v31, v[116:117] offset:49408
	s_add_i32 s16, s16, 8
	s_waitcnt lgkmcnt(0)
	s_barrier
	s_cmpk_lt_u32 s16, 0x800
	s_cbranch_scc0 .Lret2_done
	global_load_dword v84, v32, s[10:11]
	global_load_dword v85, v32, s[10:11] offset:-1024
	global_load_dword v86, v33, s[10:11]
	global_load_dword v87, v33, s[10:11] offset:-1024
	global_load_dword v88, v34, s[10:11]
	global_load_dword v90, v35, s[12:13]
	global_load_dword v91, v35, s[12:13] offset:4
	s_add_u32 s10, s10, 0x18000
	s_addc_u32 s11, s11, 0
	s_add_u32 s12, s12, 0x4000
	s_addc_u32 s13, s13, 0
	s_waitcnt lgkmcnt(4)
	v_pk_mul_f32 v[40:41], v[40:41], v[42:43]
	v_rcp_f32_e32 v40, v41
	s_nop 0
	v_pk_mul_f32 v[44:45], v[64:65], v[40:41] op_sel_hi:[1,0]
	s_waitcnt lgkmcnt(3)
	v_pk_fma_f32 v[6:7], v[44:45], v[48:49], v[6:7] op_sel_hi:[1,0,1]
	v_pk_mul_f32 v[38:39], v[6:7], v[48:49] op_sel:[0,1] op_sel_hi:[1,1]
	v_pk_fma_f32 v[8:9], v[44:45], v[50:51], v[8:9] op_sel_hi:[1,0,1]
	v_pk_fma_f32 v[38:39], v[8:9], v[50:51], v[38:39] op_sel:[0,1,0] op_sel_hi:[1,1,1]
	s_waitcnt lgkmcnt(2)
	v_pk_fma_f32 v[10:11], v[44:45], v[52:53], v[10:11] op_sel_hi:[1,0,1]
	v_pk_fma_f32 v[38:39], v[10:11], v[52:53], v[38:39] op_sel:[0,1,0] op_sel_hi:[1,1,1]
	v_pk_fma_f32 v[12:13], v[44:45], v[54:55], v[12:13] op_sel_hi:[1,0,1]
	v_pk_fma_f32 v[38:39], v[12:13], v[54:55], v[38:39] op_sel:[0,1,0] op_sel_hi:[1,1,1]
	s_waitcnt lgkmcnt(1)
	v_pk_fma_f32 v[14:15], v[44:45], v[56:57], v[14:15] op_sel_hi:[1,0,1]
	v_pk_fma_f32 v[38:39], v[14:15], v[56:57], v[38:39] op_sel:[0,1,0] op_sel_hi:[1,1,1]
	v_pk_fma_f32 v[16:17], v[44:45], v[58:59], v[16:17] op_sel_hi:[1,0,1]
	v_pk_fma_f32 v[38:39], v[16:17], v[58:59], v[38:39] op_sel:[0,1,0] op_sel_hi:[1,1,1]
	s_waitcnt lgkmcnt(0)
	v_pk_fma_f32 v[18:19], v[44:45], v[60:61], v[18:19] op_sel_hi:[1,0,1]
	v_pk_fma_f32 v[38:39], v[18:19], v[60:61], v[38:39] op_sel:[0,1,0] op_sel_hi:[1,1,1]
	v_pk_fma_f32 v[20:21], v[44:45], v[62:63], v[20:21] op_sel_hi:[1,0,1]
	v_pk_fma_f32 v[38:39], v[20:21], v[62:63], v[38:39] op_sel:[0,1,0] op_sel_hi:[1,1,1]
	s_add_u32 s14, s14, 0x1000
	s_addc_u32 s15, s15, 0
	v_add_f32_dpp v38, v38, v38 row_ror:8 row_mask:0xf bank_mask:0x3 bound_ctrl:1
	v_add_f32_dpp v38, v39, v39 row_ror:8 row_mask:0xf bank_mask:0xc bound_ctrl:1
	ds_read_b64 v[82:83], v3 offset:45568
	ds_read_b128 v[66:69], v2 offset:34048
	v_add_f32_dpp v38, v38, v38 row_half_mirror row_mask:0xf bank_mask:0xf bound_ctrl:1
	ds_read_b128 v[70:73], v2 offset:34304
	ds_read_b128 v[74:77], v2 offset:34560
	v_add_f32_dpp v38, v38, v38 quad_perm:[1,0,3,2] row_mask:0xf bank_mask:0xf bound_ctrl:1
	ds_read_b128 v[78:81], v2 offset:34816
	s_nop 0
	v_add_f32_dpp v38, v38, v38 quad_perm:[2,3,0,1] row_mask:0xf bank_mask:0xf bound_ctrl:1
	s_nop 1
	v_mov_b32_dpp v39, v38 row_ror:8 row_mask:0xf bank_mask:0xf bound_ctrl:1
	v_pk_mul_f32 v[38:39], v[38:39], v[40:41] op_sel:[0,1] op_sel_hi:[1,1]
	v_cvt_pk_bf16_f32 v47, v38, v39
	s_mov_b64 exec, s[2:3]
	global_store_dword v46, v47, s[14:15] offset:-4096
	s_mov_b64 exec, -1
	s_waitcnt lgkmcnt(4)
	v_pk_mul_f32 v[40:41], v[40:41], v[42:43]
	v_pk_mul_f32 v[44:45], v[82:83], v[40:41] op_sel_hi:[1,0]
	s_waitcnt lgkmcnt(3)
	v_pk_fma_f32 v[6:7], v[44:45], v[66:67], v[6:7] op_sel_hi:[1,0,1]
	v_pk_mul_f32 v[38:39], v[6:7], v[66:67] op_sel:[0,1] op_sel_hi:[1,1]
	v_pk_fma_f32 v[8:9], v[44:45], v[68:69], v[8:9] op_sel_hi:[1,0,1]
	v_pk_fma_f32 v[38:39], v[8:9], v[68:69], v[38:39] op_sel:[0,1,0] op_sel_hi:[1,1,1]
	s_waitcnt lgkmcnt(2)
	v_pk_fma_f32 v[10:11], v[44:45], v[70:71], v[10:11] op_sel_hi:[1,0,1]
	v_pk_fma_f32 v[38:39], v[10:11], v[70:71], v[38:39] op_sel:[0,1,0] op_sel_hi:[1,1,1]
	v_pk_fma_f32 v[12:13], v[44:45], v[72:73], v[12:13] op_sel_hi:[1,0,1]
	v_pk_fma_f32 v[38:39], v[12:13], v[72:73], v[38:39] op_sel:[0,1,0] op_sel_hi:[1,1,1]
	s_waitcnt lgkmcnt(1)
	v_pk_fma_f32 v[14:15], v[44:45], v[74:75], v[14:15] op_sel_hi:[1,0,1]
	v_pk_fma_f32 v[38:39], v[14:15], v[74:75], v[38:39] op_sel:[0,1,0] op_sel_hi:[1,1,1]
	v_pk_fma_f32 v[16:17], v[44:45], v[76:77], v[16:17] op_sel_hi:[1,0,1]
	v_pk_fma_f32 v[38:39], v[16:17], v[76:77], v[38:39] op_sel:[0,1,0] op_sel_hi:[1,1,1]
	s_waitcnt lgkmcnt(0)
	v_pk_fma_f32 v[18:19], v[44:45], v[78:79], v[18:19] op_sel_hi:[1,0,1]
	v_pk_fma_f32 v[38:39], v[18:19], v[78:79], v[38:39] op_sel:[0,1,0] op_sel_hi:[1,1,1]
	v_pk_fma_f32 v[20:21], v[44:45], v[80:81], v[20:21] op_sel_hi:[1,0,1]
	v_pk_fma_f32 v[38:39], v[20:21], v[80:81], v[38:39] op_sel:[0,1,0] op_sel_hi:[1,1,1]
	s_add_u32 s14, s14, 0x1000
	s_addc_u32 s15, s15, 0
	v_add_f32_dpp v38, v38, v38 row_ror:8 row_mask:0xf bank_mask:0x3 bound_ctrl:1
	v_add_f32_dpp v38, v39, v39 row_ror:8 row_mask:0xf bank_mask:0xc bound_ctrl:1
	ds_read_b64 v[64:65], v3 offset:45824
	ds_read_b128 v[48:51], v2 offset:35072
	v_add_f32_dpp v38, v38, v38 row_half_mirror row_mask:0xf bank_mask:0xf bound_ctrl:1
	ds_read_b128 v[52:55], v2 offset:35328
	ds_read_b128 v[56:59], v2 offset:35584
	v_add_f32_dpp v38, v38, v38 quad_perm:[1,0,3,2] row_mask:0xf bank_mask:0xf bound_ctrl:1
	ds_read_b128 v[60:63], v2 offset:35840
	s_nop 0
	v_add_f32_dpp v38, v38, v38 quad_perm:[2,3,0,1] row_mask:0xf bank_mask:0xf bound_ctrl:1
	s_nop 1
	v_mov_b32_dpp v39, v38 row_ror:8 row_mask:0xf bank_mask:0xf bound_ctrl:1
	v_pk_mul_f32 v[38:39], v[38:39], v[40:41] op_sel:[0,1] op_sel_hi:[1,1]
	v_cvt_pk_bf16_f32 v47, v38, v39
	s_mov_b64 exec, s[2:3]
	global_store_dword v46, v47, s[14:15] offset:-4096
	s_mov_b64 exec, -1
	s_waitcnt lgkmcnt(4)
	v_pk_mul_f32 v[40:41], v[40:41], v[42:43]
	v_pk_mul_f32 v[44:45], v[64:65], v[40:41] op_sel_hi:[1,0]
	s_waitcnt lgkmcnt(3)
	v_pk_fma_f32 v[6:7], v[44:45], v[48:49], v[6:7] op_sel_hi:[1,0,1]
	v_pk_mul_f32 v[38:39], v[6:7], v[48:49] op_sel:[0,1] op_sel_hi:[1,1]
	v_pk_fma_f32 v[8:9], v[44:45], v[50:51], v[8:9] op_sel_hi:[1,0,1]
	v_pk_fma_f32 v[38:39], v[8:9], v[50:51], v[38:39] op_sel:[0,1,0] op_sel_hi:[1,1,1]
	s_waitcnt lgkmcnt(2)
	v_pk_fma_f32 v[10:11], v[44:45], v[52:53], v[10:11] op_sel_hi:[1,0,1]
	v_pk_fma_f32 v[38:39], v[10:11], v[52:53], v[38:39] op_sel:[0,1,0] op_sel_hi:[1,1,1]
	v_pk_fma_f32 v[12:13], v[44:45], v[54:55], v[12:13] op_sel_hi:[1,0,1]
	v_pk_fma_f32 v[38:39], v[12:13], v[54:55], v[38:39] op_sel:[0,1,0] op_sel_hi:[1,1,1]
	s_waitcnt lgkmcnt(1)
	v_pk_fma_f32 v[14:15], v[44:45], v[56:57], v[14:15] op_sel_hi:[1,0,1]
	v_pk_fma_f32 v[38:39], v[14:15], v[56:57], v[38:39] op_sel:[0,1,0] op_sel_hi:[1,1,1]
	v_pk_fma_f32 v[16:17], v[44:45], v[58:59], v[16:17] op_sel_hi:[1,0,1]
	v_pk_fma_f32 v[38:39], v[16:17], v[58:59], v[38:39] op_sel:[0,1,0] op_sel_hi:[1,1,1]
	s_waitcnt lgkmcnt(0)
	v_pk_fma_f32 v[18:19], v[44:45], v[60:61], v[18:19] op_sel_hi:[1,0,1]
	v_pk_fma_f32 v[38:39], v[18:19], v[60:61], v[38:39] op_sel:[0,1,0] op_sel_hi:[1,1,1]
	v_pk_fma_f32 v[20:21], v[44:45], v[62:63], v[20:21] op_sel_hi:[1,0,1]
	v_pk_fma_f32 v[38:39], v[20:21], v[62:63], v[38:39] op_sel:[0,1,0] op_sel_hi:[1,1,1]
	s_add_u32 s14, s14, 0x1000
	s_addc_u32 s15, s15, 0
	v_add_f32_dpp v38, v38, v38 row_ror:8 row_mask:0xf bank_mask:0x3 bound_ctrl:1
	v_add_f32_dpp v38, v39, v39 row_ror:8 row_mask:0xf bank_mask:0xc bound_ctrl:1
	ds_read_b64 v[82:83], v3 offset:46080
	ds_read_b128 v[66:69], v2 offset:36096
	v_add_f32_dpp v38, v38, v38 row_half_mirror row_mask:0xf bank_mask:0xf bound_ctrl:1
	ds_read_b128 v[70:73], v2 offset:36352
	ds_read_b128 v[74:77], v2 offset:36608
	v_add_f32_dpp v38, v38, v38 quad_perm:[1,0,3,2] row_mask:0xf bank_mask:0xf bound_ctrl:1
	ds_read_b128 v[78:81], v2 offset:36864
	s_nop 0
	v_add_f32_dpp v38, v38, v38 quad_perm:[2,3,0,1] row_mask:0xf bank_mask:0xf bound_ctrl:1
	s_nop 1
	v_mov_b32_dpp v39, v38 row_ror:8 row_mask:0xf bank_mask:0xf bound_ctrl:1
	v_pk_mul_f32 v[38:39], v[38:39], v[40:41] op_sel:[0,1] op_sel_hi:[1,1]
	v_cvt_pk_bf16_f32 v47, v38, v39
	s_mov_b64 exec, s[2:3]
	global_store_dword v46, v47, s[14:15] offset:-4096
	s_mov_b64 exec, -1
	s_waitcnt lgkmcnt(4)
	v_pk_mul_f32 v[40:41], v[40:41], v[42:43]
	v_pk_mul_f32 v[44:45], v[82:83], v[40:41] op_sel_hi:[1,0]
	s_waitcnt lgkmcnt(3)
	v_pk_fma_f32 v[6:7], v[44:45], v[66:67], v[6:7] op_sel_hi:[1,0,1]
	v_pk_mul_f32 v[38:39], v[6:7], v[66:67] op_sel:[0,1] op_sel_hi:[1,1]
	v_pk_fma_f32 v[8:9], v[44:45], v[68:69], v[8:9] op_sel_hi:[1,0,1]
	v_pk_fma_f32 v[38:39], v[8:9], v[68:69], v[38:39] op_sel:[0,1,0] op_sel_hi:[1,1,1]
	s_waitcnt lgkmcnt(2)
	v_pk_fma_f32 v[10:11], v[44:45], v[70:71], v[10:11] op_sel_hi:[1,0,1]
	v_pk_fma_f32 v[38:39], v[10:11], v[70:71], v[38:39] op_sel:[0,1,0] op_sel_hi:[1,1,1]
	v_pk_fma_f32 v[12:13], v[44:45], v[72:73], v[12:13] op_sel_hi:[1,0,1]
	v_pk_fma_f32 v[38:39], v[12:13], v[72:73], v[38:39] op_sel:[0,1,0] op_sel_hi:[1,1,1]
	s_waitcnt lgkmcnt(1)
	v_pk_fma_f32 v[14:15], v[44:45], v[74:75], v[14:15] op_sel_hi:[1,0,1]
	v_pk_fma_f32 v[38:39], v[14:15], v[74:75], v[38:39] op_sel:[0,1,0] op_sel_hi:[1,1,1]
	v_pk_fma_f32 v[16:17], v[44:45], v[76:77], v[16:17] op_sel_hi:[1,0,1]
	v_pk_fma_f32 v[38:39], v[16:17], v[76:77], v[38:39] op_sel:[0,1,0] op_sel_hi:[1,1,1]
	s_waitcnt lgkmcnt(0)
	v_pk_fma_f32 v[18:19], v[44:45], v[78:79], v[18:19] op_sel_hi:[1,0,1]
	v_pk_fma_f32 v[38:39], v[18:19], v[78:79], v[38:39] op_sel:[0,1,0] op_sel_hi:[1,1,1]
	v_pk_fma_f32 v[20:21], v[44:45], v[80:81], v[20:21] op_sel_hi:[1,0,1]
	v_pk_fma_f32 v[38:39], v[20:21], v[80:81], v[38:39] op_sel:[0,1,0] op_sel_hi:[1,1,1]
	s_add_u32 s14, s14, 0x1000
	s_addc_u32 s15, s15, 0
	v_add_f32_dpp v38, v38, v38 row_ror:8 row_mask:0xf bank_mask:0x3 bound_ctrl:1
	v_add_f32_dpp v38, v39, v39 row_ror:8 row_mask:0xf bank_mask:0xc bound_ctrl:1
	ds_read_b64 v[64:65], v3 offset:46336
	ds_read_b128 v[48:51], v2 offset:37120
	v_add_f32_dpp v38, v38, v38 row_half_mirror row_mask:0xf bank_mask:0xf bound_ctrl:1
	ds_read_b128 v[52:55], v2 offset:37376
	ds_read_b128 v[56:59], v2 offset:37632
	v_add_f32_dpp v38, v38, v38 quad_perm:[1,0,3,2] row_mask:0xf bank_mask:0xf bound_ctrl:1
	ds_read_b128 v[60:63], v2 offset:37888
	s_nop 0
	v_add_f32_dpp v38, v38, v38 quad_perm:[2,3,0,1] row_mask:0xf bank_mask:0xf bound_ctrl:1
	s_nop 1
	v_mov_b32_dpp v39, v38 row_ror:8 row_mask:0xf bank_mask:0xf bound_ctrl:1
	v_pk_mul_f32 v[38:39], v[38:39], v[40:41] op_sel:[0,1] op_sel_hi:[1,1]
	v_cvt_pk_bf16_f32 v47, v38, v39
	s_mov_b64 exec, s[2:3]
	global_store_dword v46, v47, s[14:15] offset:-4096
	s_mov_b64 exec, -1
	s_waitcnt lgkmcnt(4)
	v_pk_mul_f32 v[40:41], v[40:41], v[42:43]
	v_pk_mul_f32 v[44:45], v[64:65], v[40:41] op_sel_hi:[1,0]
	s_waitcnt lgkmcnt(3)
	v_pk_fma_f32 v[6:7], v[44:45], v[48:49], v[6:7] op_sel_hi:[1,0,1]
	v_pk_mul_f32 v[38:39], v[6:7], v[48:49] op_sel:[0,1] op_sel_hi:[1,1]
	v_pk_fma_f32 v[8:9], v[44:45], v[50:51], v[8:9] op_sel_hi:[1,0,1]
	v_pk_fma_f32 v[38:39], v[8:9], v[50:51], v[38:39] op_sel:[0,1,0] op_sel_hi:[1,1,1]
	s_waitcnt lgkmcnt(2)
	v_pk_fma_f32 v[10:11], v[44:45], v[52:53], v[10:11] op_sel_hi:[1,0,1]
	v_pk_fma_f32 v[38:39], v[10:11], v[52:53], v[38:39] op_sel:[0,1,0] op_sel_hi:[1,1,1]
	v_pk_fma_f32 v[12:13], v[44:45], v[54:55], v[12:13] op_sel_hi:[1,0,1]
	v_pk_fma_f32 v[38:39], v[12:13], v[54:55], v[38:39] op_sel:[0,1,0] op_sel_hi:[1,1,1]
	s_waitcnt lgkmcnt(1)
	v_pk_fma_f32 v[14:15], v[44:45], v[56:57], v[14:15] op_sel_hi:[1,0,1]
	v_pk_fma_f32 v[38:39], v[14:15], v[56:57], v[38:39] op_sel:[0,1,0] op_sel_hi:[1,1,1]
	v_pk_fma_f32 v[16:17], v[44:45], v[58:59], v[16:17] op_sel_hi:[1,0,1]
	v_pk_fma_f32 v[38:39], v[16:17], v[58:59], v[38:39] op_sel:[0,1,0] op_sel_hi:[1,1,1]
	s_waitcnt lgkmcnt(0)
	v_pk_fma_f32 v[18:19], v[44:45], v[60:61], v[18:19] op_sel_hi:[1,0,1]
	v_pk_fma_f32 v[38:39], v[18:19], v[60:61], v[38:39] op_sel:[0,1,0] op_sel_hi:[1,1,1]
	v_pk_fma_f32 v[20:21], v[44:45], v[62:63], v[20:21] op_sel_hi:[1,0,1]
	v_pk_fma_f32 v[38:39], v[20:21], v[62:63], v[38:39] op_sel:[0,1,0] op_sel_hi:[1,1,1]
	s_add_u32 s14, s14, 0x1000
	s_addc_u32 s15, s15, 0
	v_add_f32_dpp v38, v38, v38 row_ror:8 row_mask:0xf bank_mask:0x3 bound_ctrl:1
	v_add_f32_dpp v38, v39, v39 row_ror:8 row_mask:0xf bank_mask:0xc bound_ctrl:1
	ds_read_b64 v[82:83], v3 offset:46592
	ds_read_b128 v[66:69], v2 offset:38144
	v_add_f32_dpp v38, v38, v38 row_half_mirror row_mask:0xf bank_mask:0xf bound_ctrl:1
	ds_read_b128 v[70:73], v2 offset:38400
	ds_read_b128 v[74:77], v2 offset:38656
	v_add_f32_dpp v38, v38, v38 quad_perm:[1,0,3,2] row_mask:0xf bank_mask:0xf bound_ctrl:1
	ds_read_b128 v[78:81], v2 offset:38912
	s_nop 0
	v_add_f32_dpp v38, v38, v38 quad_perm:[2,3,0,1] row_mask:0xf bank_mask:0xf bound_ctrl:1
	s_nop 1
	v_mov_b32_dpp v39, v38 row_ror:8 row_mask:0xf bank_mask:0xf bound_ctrl:1
	v_pk_mul_f32 v[38:39], v[38:39], v[40:41] op_sel:[0,1] op_sel_hi:[1,1]
	v_cvt_pk_bf16_f32 v47, v38, v39
	s_mov_b64 exec, s[2:3]
	global_store_dword v46, v47, s[14:15] offset:-4096
	s_mov_b64 exec, -1
	s_waitcnt lgkmcnt(4)
	v_pk_mul_f32 v[40:41], v[40:41], v[42:43]
	v_pk_mul_f32 v[44:45], v[82:83], v[40:41] op_sel_hi:[1,0]
	s_waitcnt lgkmcnt(3)
	v_pk_fma_f32 v[6:7], v[44:45], v[66:67], v[6:7] op_sel_hi:[1,0,1]
	v_pk_mul_f32 v[38:39], v[6:7], v[66:67] op_sel:[0,1] op_sel_hi:[1,1]
	v_pk_fma_f32 v[8:9], v[44:45], v[68:69], v[8:9] op_sel_hi:[1,0,1]
	v_pk_fma_f32 v[38:39], v[8:9], v[68:69], v[38:39] op_sel:[0,1,0] op_sel_hi:[1,1,1]
	s_waitcnt lgkmcnt(2)
	v_pk_fma_f32 v[10:11], v[44:45], v[70:71], v[10:11] op_sel_hi:[1,0,1]
	v_pk_fma_f32 v[38:39], v[10:11], v[70:71], v[38:39] op_sel:[0,1,0] op_sel_hi:[1,1,1]
	v_pk_fma_f32 v[12:13], v[44:45], v[72:73], v[12:13] op_sel_hi:[1,0,1]
	v_pk_fma_f32 v[38:39], v[12:13], v[72:73], v[38:39] op_sel:[0,1,0] op_sel_hi:[1,1,1]
	s_waitcnt lgkmcnt(1)
	v_pk_fma_f32 v[14:15], v[44:45], v[74:75], v[14:15] op_sel_hi:[1,0,1]
	v_pk_fma_f32 v[38:39], v[14:15], v[74:75], v[38:39] op_sel:[0,1,0] op_sel_hi:[1,1,1]
	v_pk_fma_f32 v[16:17], v[44:45], v[76:77], v[16:17] op_sel_hi:[1,0,1]
	v_pk_fma_f32 v[38:39], v[16:17], v[76:77], v[38:39] op_sel:[0,1,0] op_sel_hi:[1,1,1]
	s_waitcnt lgkmcnt(0)
	v_pk_fma_f32 v[18:19], v[44:45], v[78:79], v[18:19] op_sel_hi:[1,0,1]
	v_pk_fma_f32 v[38:39], v[18:19], v[78:79], v[38:39] op_sel:[0,1,0] op_sel_hi:[1,1,1]
	v_pk_fma_f32 v[20:21], v[44:45], v[80:81], v[20:21] op_sel_hi:[1,0,1]
	v_pk_fma_f32 v[38:39], v[20:21], v[80:81], v[38:39] op_sel:[0,1,0] op_sel_hi:[1,1,1]
	s_add_u32 s14, s14, 0x1000
	s_addc_u32 s15, s15, 0
	v_add_f32_dpp v38, v38, v38 row_ror:8 row_mask:0xf bank_mask:0x3 bound_ctrl:1
	v_add_f32_dpp v38, v39, v39 row_ror:8 row_mask:0xf bank_mask:0xc bound_ctrl:1
	ds_read_b64 v[64:65], v3 offset:46848
	ds_read_b128 v[48:51], v2 offset:39168
	v_add_f32_dpp v38, v38, v38 row_half_mirror row_mask:0xf bank_mask:0xf bound_ctrl:1
	ds_read_b128 v[52:55], v2 offset:39424
	ds_read_b128 v[56:59], v2 offset:39680
	v_add_f32_dpp v38, v38, v38 quad_perm:[1,0,3,2] row_mask:0xf bank_mask:0xf bound_ctrl:1
	ds_read_b128 v[60:63], v2 offset:39936
	s_nop 0
	v_add_f32_dpp v38, v38, v38 quad_perm:[2,3,0,1] row_mask:0xf bank_mask:0xf bound_ctrl:1
	s_nop 1
	v_mov_b32_dpp v39, v38 row_ror:8 row_mask:0xf bank_mask:0xf bound_ctrl:1
	v_pk_mul_f32 v[38:39], v[38:39], v[40:41] op_sel:[0,1] op_sel_hi:[1,1]
	v_cvt_pk_bf16_f32 v47, v38, v39
	s_mov_b64 exec, s[2:3]
	global_store_dword v46, v47, s[14:15] offset:-4096
	s_mov_b64 exec, -1
	s_waitcnt lgkmcnt(4)
	v_pk_mul_f32 v[40:41], v[40:41], v[42:43]
	v_pk_mul_f32 v[44:45], v[64:65], v[40:41] op_sel_hi:[1,0]
	s_waitcnt lgkmcnt(3)
	v_pk_fma_f32 v[6:7], v[44:45], v[48:49], v[6:7] op_sel_hi:[1,0,1]
	v_pk_mul_f32 v[38:39], v[6:7], v[48:49] op_sel:[0,1] op_sel_hi:[1,1]
	v_pk_fma_f32 v[8:9], v[44:45], v[50:51], v[8:9] op_sel_hi:[1,0,1]
	v_pk_fma_f32 v[38:39], v[8:9], v[50:51], v[38:39] op_sel:[0,1,0] op_sel_hi:[1,1,1]
	s_waitcnt lgkmcnt(2)
	v_pk_fma_f32 v[10:11], v[44:45], v[52:53], v[10:11] op_sel_hi:[1,0,1]
	v_pk_fma_f32 v[38:39], v[10:11], v[52:53], v[38:39] op_sel:[0,1,0] op_sel_hi:[1,1,1]
	v_pk_fma_f32 v[12:13], v[44:45], v[54:55], v[12:13] op_sel_hi:[1,0,1]
	v_pk_fma_f32 v[38:39], v[12:13], v[54:55], v[38:39] op_sel:[0,1,0] op_sel_hi:[1,1,1]
	s_waitcnt lgkmcnt(1)
	v_pk_fma_f32 v[14:15], v[44:45], v[56:57], v[14:15] op_sel_hi:[1,0,1]
	v_pk_fma_f32 v[38:39], v[14:15], v[56:57], v[38:39] op_sel:[0,1,0] op_sel_hi:[1,1,1]
	v_pk_fma_f32 v[16:17], v[44:45], v[58:59], v[16:17] op_sel_hi:[1,0,1]
	v_pk_fma_f32 v[38:39], v[16:17], v[58:59], v[38:39] op_sel:[0,1,0] op_sel_hi:[1,1,1]
	s_waitcnt lgkmcnt(0)
	v_pk_fma_f32 v[18:19], v[44:45], v[60:61], v[18:19] op_sel_hi:[1,0,1]
	v_pk_fma_f32 v[38:39], v[18:19], v[60:61], v[38:39] op_sel:[0,1,0] op_sel_hi:[1,1,1]
	v_pk_fma_f32 v[20:21], v[44:45], v[62:63], v[20:21] op_sel_hi:[1,0,1]
	v_pk_fma_f32 v[38:39], v[20:21], v[62:63], v[38:39] op_sel:[0,1,0] op_sel_hi:[1,1,1]
	s_add_u32 s14, s14, 0x1000
	s_addc_u32 s15, s15, 0
	v_add_f32_dpp v38, v38, v38 row_ror:8 row_mask:0xf bank_mask:0x3 bound_ctrl:1
	v_add_f32_dpp v38, v39, v39 row_ror:8 row_mask:0xf bank_mask:0xc bound_ctrl:1
	ds_read_b64 v[82:83], v3 offset:47104
	ds_read_b128 v[66:69], v2 offset:40192
	v_add_f32_dpp v38, v38, v38 row_half_mirror row_mask:0xf bank_mask:0xf bound_ctrl:1
	ds_read_b128 v[70:73], v2 offset:40448
	ds_read_b128 v[74:77], v2 offset:40704
	v_add_f32_dpp v38, v38, v38 quad_perm:[1,0,3,2] row_mask:0xf bank_mask:0xf bound_ctrl:1
	ds_read_b128 v[78:81], v2 offset:40960
	s_nop 0
	v_add_f32_dpp v38, v38, v38 quad_perm:[2,3,0,1] row_mask:0xf bank_mask:0xf bound_ctrl:1
	s_nop 1
	v_mov_b32_dpp v39, v38 row_ror:8 row_mask:0xf bank_mask:0xf bound_ctrl:1
	v_pk_mul_f32 v[38:39], v[38:39], v[40:41] op_sel:[0,1] op_sel_hi:[1,1]
	v_cvt_pk_bf16_f32 v47, v38, v39
	s_mov_b64 exec, s[2:3]
	global_store_dword v46, v47, s[14:15] offset:-4096
	s_mov_b64 exec, -1
	s_waitcnt lgkmcnt(4)
	v_pk_mul_f32 v[40:41], v[40:41], v[42:43]
	v_pk_mul_f32 v[44:45], v[82:83], v[40:41] op_sel_hi:[1,0]
	s_waitcnt lgkmcnt(3)
	v_pk_fma_f32 v[6:7], v[44:45], v[66:67], v[6:7] op_sel_hi:[1,0,1]
	v_pk_mul_f32 v[38:39], v[6:7], v[66:67] op_sel:[0,1] op_sel_hi:[1,1]
	v_pk_fma_f32 v[8:9], v[44:45], v[68:69], v[8:9] op_sel_hi:[1,0,1]
	v_pk_fma_f32 v[38:39], v[8:9], v[68:69], v[38:39] op_sel:[0,1,0] op_sel_hi:[1,1,1]
	s_waitcnt lgkmcnt(2)
	v_pk_fma_f32 v[10:11], v[44:45], v[70:71], v[10:11] op_sel_hi:[1,0,1]
	v_pk_fma_f32 v[38:39], v[10:11], v[70:71], v[38:39] op_sel:[0,1,0] op_sel_hi:[1,1,1]
	v_pk_fma_f32 v[12:13], v[44:45], v[72:73], v[12:13] op_sel_hi:[1,0,1]
	v_pk_fma_f32 v[38:39], v[12:13], v[72:73], v[38:39] op_sel:[0,1,0] op_sel_hi:[1,1,1]
	s_waitcnt lgkmcnt(1)
	v_pk_fma_f32 v[14:15], v[44:45], v[74:75], v[14:15] op_sel_hi:[1,0,1]
	v_pk_fma_f32 v[38:39], v[14:15], v[74:75], v[38:39] op_sel:[0,1,0] op_sel_hi:[1,1,1]
	v_pk_fma_f32 v[16:17], v[44:45], v[76:77], v[16:17] op_sel_hi:[1,0,1]
	v_pk_fma_f32 v[38:39], v[16:17], v[76:77], v[38:39] op_sel:[0,1,0] op_sel_hi:[1,1,1]
	s_waitcnt lgkmcnt(0)
	v_pk_fma_f32 v[18:19], v[44:45], v[78:79], v[18:19] op_sel_hi:[1,0,1]
	v_pk_fma_f32 v[38:39], v[18:19], v[78:79], v[38:39] op_sel:[0,1,0] op_sel_hi:[1,1,1]
	v_pk_fma_f32 v[20:21], v[44:45], v[80:81], v[20:21] op_sel_hi:[1,0,1]
	v_pk_fma_f32 v[38:39], v[20:21], v[80:81], v[38:39] op_sel:[0,1,0] op_sel_hi:[1,1,1]
	s_add_u32 s14, s14, 0x1000
	s_addc_u32 s15, s15, 0
	v_add_f32_dpp v38, v38, v38 row_ror:8 row_mask:0xf bank_mask:0x3 bound_ctrl:1
	v_add_f32_dpp v38, v39, v39 row_ror:8 row_mask:0xf bank_mask:0xc bound_ctrl:1
	ds_read_b64 v[64:65], v23 offset:37120
	ds_read_b128 v[48:51], v2 offset:57600
	v_add_f32_dpp v38, v38, v38 row_half_mirror row_mask:0xf bank_mask:0xf bound_ctrl:1
	ds_read_b128 v[52:55], v2 offset:57856
	ds_read_b128 v[56:59], v2 offset:58112
	v_add_f32_dpp v38, v38, v38 quad_perm:[1,0,3,2] row_mask:0xf bank_mask:0xf bound_ctrl:1
	ds_read_b128 v[60:63], v2 offset:58368
	s_nop 0
	v_add_f32_dpp v38, v38, v38 quad_perm:[2,3,0,1] row_mask:0xf bank_mask:0xf bound_ctrl:1
	s_nop 1
	v_mov_b32_dpp v39, v38 row_ror:8 row_mask:0xf bank_mask:0xf bound_ctrl:1
	v_pk_mul_f32 v[38:39], v[38:39], v[40:41] op_sel:[0,1] op_sel_hi:[1,1]
	v_cvt_pk_bf16_f32 v47, v38, v39
	s_mov_b64 exec, s[2:3]
	global_store_dword v46, v47, s[14:15] offset:-4096
	s_mov_b64 exec, -1
	s_waitcnt vmcnt(8)
	v_lshlrev_b32_e32 v108, 16, v84
	v_lshlrev_b32_e32 v109, 16, v85
	v_and_b32_e32 v110, s17, v84
	v_and_b32_e32 v111, s17, v85
	v_lshlrev_b32_e32 v112, 16, v86
	v_lshlrev_b32_e32 v113, 16, v87
	v_and_b32_e32 v114, s17, v86
	v_and_b32_e32 v115, s17, v87
	v_lshlrev_b32_e32 v116, 16, v88
	v_and_b32_e32 v117, s17, v88
	ds_write_b128 v29, v[108:111] offset:256
	ds_write_b128 v29, v[112:115] offset:8448
	ds_write_b64 v30, v[90:91] offset:256
	ds_write_b64 v31, v[116:117] offset:256
	s_add_i32 s16, s16, 8
	s_waitcnt lgkmcnt(0)
	s_barrier
	s_cmpk_lt_u32 s16, 0x800
	s_cbranch_scc0 .Lret2_done
	global_load_dword v84, v32, s[10:11]
	global_load_dword v85, v32, s[10:11] offset:-1024
	global_load_dword v86, v33, s[10:11]
	global_load_dword v87, v33, s[10:11] offset:-1024
	global_load_dword v88, v34, s[10:11]
	global_load_dword v90, v35, s[12:13]
	global_load_dword v91, v35, s[12:13] offset:4
	s_add_u32 s10, s10, 0x18000
	s_addc_u32 s11, s11, 0
	s_add_u32 s12, s12, 0x4000
	s_addc_u32 s13, s13, 0
	s_waitcnt lgkmcnt(4)
	v_pk_mul_f32 v[40:41], v[40:41], v[42:43]
	v_rcp_f32_e32 v40, v41
	s_nop 0
	v_pk_mul_f32 v[44:45], v[64:65], v[40:41] op_sel_hi:[1,0]
	s_waitcnt lgkmcnt(3)
	v_pk_fma_f32 v[6:7], v[44:45], v[48:49], v[6:7] op_sel_hi:[1,0,1]
	v_pk_mul_f32 v[38:39], v[6:7], v[48:49] op_sel:[0,1] op_sel_hi:[1,1]
	v_pk_fma_f32 v[8:9], v[44:45], v[50:51], v[8:9] op_sel_hi:[1,0,1]
	v_pk_fma_f32 v[38:39], v[8:9], v[50:51], v[38:39] op_sel:[0,1,0] op_sel_hi:[1,1,1]
	s_waitcnt lgkmcnt(2)
	v_pk_fma_f32 v[10:11], v[44:45], v[52:53], v[10:11] op_sel_hi:[1,0,1]
	v_pk_fma_f32 v[38:39], v[10:11], v[52:53], v[38:39] op_sel:[0,1,0] op_sel_hi:[1,1,1]
	v_pk_fma_f32 v[12:13], v[44:45], v[54:55], v[12:13] op_sel_hi:[1,0,1]
	v_pk_fma_f32 v[38:39], v[12:13], v[54:55], v[38:39] op_sel:[0,1,0] op_sel_hi:[1,1,1]
	s_waitcnt lgkmcnt(1)
	v_pk_fma_f32 v[14:15], v[44:45], v[56:57], v[14:15] op_sel_hi:[1,0,1]
	v_pk_fma_f32 v[38:39], v[14:15], v[56:57], v[38:39] op_sel:[0,1,0] op_sel_hi:[1,1,1]
	v_pk_fma_f32 v[16:17], v[44:45], v[58:59], v[16:17] op_sel_hi:[1,0,1]
	v_pk_fma_f32 v[38:39], v[16:17], v[58:59], v[38:39] op_sel:[0,1,0] op_sel_hi:[1,1,1]
	s_waitcnt lgkmcnt(0)
	v_pk_fma_f32 v[18:19], v[44:45], v[60:61], v[18:19] op_sel_hi:[1,0,1]
	v_pk_fma_f32 v[38:39], v[18:19], v[60:61], v[38:39] op_sel:[0,1,0] op_sel_hi:[1,1,1]
	v_pk_fma_f32 v[20:21], v[44:45], v[62:63], v[20:21] op_sel_hi:[1,0,1]
	v_pk_fma_f32 v[38:39], v[20:21], v[62:63], v[38:39] op_sel:[0,1,0] op_sel_hi:[1,1,1]
	s_add_u32 s14, s14, 0x1000
	s_addc_u32 s15, s15, 0
	v_add_f32_dpp v38, v38, v38 row_ror:8 row_mask:0xf bank_mask:0x3 bound_ctrl:1
	v_add_f32_dpp v38, v39, v39 row_ror:8 row_mask:0xf bank_mask:0xc bound_ctrl:1
	ds_read_b64 v[82:83], v23 offset:37376
	ds_read_b128 v[66:69], v2 offset:58624
	v_add_f32_dpp v38, v38, v38 row_half_mirror row_mask:0xf bank_mask:0xf bound_ctrl:1
	ds_read_b128 v[70:73], v2 offset:58880
	ds_read_b128 v[74:77], v2 offset:59136
	v_add_f32_dpp v38, v38, v38 quad_perm:[1,0,3,2] row_mask:0xf bank_mask:0xf bound_ctrl:1
	ds_read_b128 v[78:81], v2 offset:59392
	s_nop 0
	v_add_f32_dpp v38, v38, v38 quad_perm:[2,3,0,1] row_mask:0xf bank_mask:0xf bound_ctrl:1
	s_nop 1
	v_mov_b32_dpp v39, v38 row_ror:8 row_mask:0xf bank_mask:0xf bound_ctrl:1
	v_pk_mul_f32 v[38:39], v[38:39], v[40:41] op_sel:[0,1] op_sel_hi:[1,1]
	v_cvt_pk_bf16_f32 v47, v38, v39
	s_mov_b64 exec, s[2:3]
	global_store_dword v46, v47, s[14:15] offset:-4096
	s_mov_b64 exec, -1
	s_waitcnt lgkmcnt(4)
	v_pk_mul_f32 v[40:41], v[40:41], v[42:43]
	v_pk_mul_f32 v[44:45], v[82:83], v[40:41] op_sel_hi:[1,0]
	s_waitcnt lgkmcnt(3)
	v_pk_fma_f32 v[6:7], v[44:45], v[66:67], v[6:7] op_sel_hi:[1,0,1]
	v_pk_mul_f32 v[38:39], v[6:7], v[66:67] op_sel:[0,1] op_sel_hi:[1,1]
	v_pk_fma_f32 v[8:9], v[44:45], v[68:69], v[8:9] op_sel_hi:[1,0,1]
	v_pk_fma_f32 v[38:39], v[8:9], v[68:69], v[38:39] op_sel:[0,1,0] op_sel_hi:[1,1,1]
	s_waitcnt lgkmcnt(2)
	v_pk_fma_f32 v[10:11], v[44:45], v[70:71], v[10:11] op_sel_hi:[1,0,1]
	v_pk_fma_f32 v[38:39], v[10:11], v[70:71], v[38:39] op_sel:[0,1,0] op_sel_hi:[1,1,1]
	v_pk_fma_f32 v[12:13], v[44:45], v[72:73], v[12:13] op_sel_hi:[1,0,1]
	v_pk_fma_f32 v[38:39], v[12:13], v[72:73], v[38:39] op_sel:[0,1,0] op_sel_hi:[1,1,1]
	s_waitcnt lgkmcnt(1)
	v_pk_fma_f32 v[14:15], v[44:45], v[74:75], v[14:15] op_sel_hi:[1,0,1]
	v_pk_fma_f32 v[38:39], v[14:15], v[74:75], v[38:39] op_sel:[0,1,0] op_sel_hi:[1,1,1]
	v_pk_fma_f32 v[16:17], v[44:45], v[76:77], v[16:17] op_sel_hi:[1,0,1]
	v_pk_fma_f32 v[38:39], v[16:17], v[76:77], v[38:39] op_sel:[0,1,0] op_sel_hi:[1,1,1]
	s_waitcnt lgkmcnt(0)
	v_pk_fma_f32 v[18:19], v[44:45], v[78:79], v[18:19] op_sel_hi:[1,0,1]
	v_pk_fma_f32 v[38:39], v[18:19], v[78:79], v[38:39] op_sel:[0,1,0] op_sel_hi:[1,1,1]
	v_pk_fma_f32 v[20:21], v[44:45], v[80:81], v[20:21] op_sel_hi:[1,0,1]
	v_pk_fma_f32 v[38:39], v[20:21], v[80:81], v[38:39] op_sel:[0,1,0] op_sel_hi:[1,1,1]
	s_add_u32 s14, s14, 0x1000
	s_addc_u32 s15, s15, 0
	v_add_f32_dpp v38, v38, v38 row_ror:8 row_mask:0xf bank_mask:0x3 bound_ctrl:1
	v_add_f32_dpp v38, v39, v39 row_ror:8 row_mask:0xf bank_mask:0xc bound_ctrl:1
	ds_read_b64 v[64:65], v23 offset:37632
	ds_read_b128 v[48:51], v2 offset:59648
	v_add_f32_dpp v38, v38, v38 row_half_mirror row_mask:0xf bank_mask:0xf bound_ctrl:1
	ds_read_b128 v[52:55], v2 offset:59904
	ds_read_b128 v[56:59], v2 offset:60160
	v_add_f32_dpp v38, v38, v38 quad_perm:[1,0,3,2] row_mask:0xf bank_mask:0xf bound_ctrl:1
	ds_read_b128 v[60:63], v2 offset:60416
	s_nop 0
	v_add_f32_dpp v38, v38, v38 quad_perm:[2,3,0,1] row_mask:0xf bank_mask:0xf bound_ctrl:1
	s_nop 1
	v_mov_b32_dpp v39, v38 row_ror:8 row_mask:0xf bank_mask:0xf bound_ctrl:1
	v_pk_mul_f32 v[38:39], v[38:39], v[40:41] op_sel:[0,1] op_sel_hi:[1,1]
	v_cvt_pk_bf16_f32 v47, v38, v39
	s_mov_b64 exec, s[2:3]
	global_store_dword v46, v47, s[14:15] offset:-4096
	s_mov_b64 exec, -1
	s_waitcnt lgkmcnt(4)
	v_pk_mul_f32 v[40:41], v[40:41], v[42:43]
	v_pk_mul_f32 v[44:45], v[64:65], v[40:41] op_sel_hi:[1,0]
	s_waitcnt lgkmcnt(3)
	v_pk_fma_f32 v[6:7], v[44:45], v[48:49], v[6:7] op_sel_hi:[1,0,1]
	v_pk_mul_f32 v[38:39], v[6:7], v[48:49] op_sel:[0,1] op_sel_hi:[1,1]
	v_pk_fma_f32 v[8:9], v[44:45], v[50:51], v[8:9] op_sel_hi:[1,0,1]
	v_pk_fma_f32 v[38:39], v[8:9], v[50:51], v[38:39] op_sel:[0,1,0] op_sel_hi:[1,1,1]
	s_waitcnt lgkmcnt(2)
	v_pk_fma_f32 v[10:11], v[44:45], v[52:53], v[10:11] op_sel_hi:[1,0,1]
	v_pk_fma_f32 v[38:39], v[10:11], v[52:53], v[38:39] op_sel:[0,1,0] op_sel_hi:[1,1,1]
	v_pk_fma_f32 v[12:13], v[44:45], v[54:55], v[12:13] op_sel_hi:[1,0,1]
	v_pk_fma_f32 v[38:39], v[12:13], v[54:55], v[38:39] op_sel:[0,1,0] op_sel_hi:[1,1,1]
	s_waitcnt lgkmcnt(1)
	v_pk_fma_f32 v[14:15], v[44:45], v[56:57], v[14:15] op_sel_hi:[1,0,1]
	v_pk_fma_f32 v[38:39], v[14:15], v[56:57], v[38:39] op_sel:[0,1,0] op_sel_hi:[1,1,1]
	v_pk_fma_f32 v[16:17], v[44:45], v[58:59], v[16:17] op_sel_hi:[1,0,1]
	v_pk_fma_f32 v[38:39], v[16:17], v[58:59], v[38:39] op_sel:[0,1,0] op_sel_hi:[1,1,1]
	s_waitcnt lgkmcnt(0)
	v_pk_fma_f32 v[18:19], v[44:45], v[60:61], v[18:19] op_sel_hi:[1,0,1]
	v_pk_fma_f32 v[38:39], v[18:19], v[60:61], v[38:39] op_sel:[0,1,0] op_sel_hi:[1,1,1]
	v_pk_fma_f32 v[20:21], v[44:45], v[62:63], v[20:21] op_sel_hi:[1,0,1]
	v_pk_fma_f32 v[38:39], v[20:21], v[62:63], v[38:39] op_sel:[0,1,0] op_sel_hi:[1,1,1]
	s_add_u32 s14, s14, 0x1000
	s_addc_u32 s15, s15, 0
	v_add_f32_dpp v38, v38, v38 row_ror:8 row_mask:0xf bank_mask:0x3 bound_ctrl:1
	v_add_f32_dpp v38, v39, v39 row_ror:8 row_mask:0xf bank_mask:0xc bound_ctrl:1
	ds_read_b64 v[82:83], v23 offset:37888
	ds_read_b128 v[66:69], v2 offset:60672
	v_add_f32_dpp v38, v38, v38 row_half_mirror row_mask:0xf bank_mask:0xf bound_ctrl:1
	ds_read_b128 v[70:73], v2 offset:60928
	ds_read_b128 v[74:77], v2 offset:61184
	v_add_f32_dpp v38, v38, v38 quad_perm:[1,0,3,2] row_mask:0xf bank_mask:0xf bound_ctrl:1
	ds_read_b128 v[78:81], v2 offset:61440
	s_nop 0
	v_add_f32_dpp v38, v38, v38 quad_perm:[2,3,0,1] row_mask:0xf bank_mask:0xf bound_ctrl:1
	s_nop 1
	v_mov_b32_dpp v39, v38 row_ror:8 row_mask:0xf bank_mask:0xf bound_ctrl:1
	v_pk_mul_f32 v[38:39], v[38:39], v[40:41] op_sel:[0,1] op_sel_hi:[1,1]
	v_cvt_pk_bf16_f32 v47, v38, v39
	s_mov_b64 exec, s[2:3]
	global_store_dword v46, v47, s[14:15] offset:-4096
	s_mov_b64 exec, -1
	s_waitcnt lgkmcnt(4)
	v_pk_mul_f32 v[40:41], v[40:41], v[42:43]
	v_pk_mul_f32 v[44:45], v[82:83], v[40:41] op_sel_hi:[1,0]
	s_waitcnt lgkmcnt(3)
	v_pk_fma_f32 v[6:7], v[44:45], v[66:67], v[6:7] op_sel_hi:[1,0,1]
	v_pk_mul_f32 v[38:39], v[6:7], v[66:67] op_sel:[0,1] op_sel_hi:[1,1]
	v_pk_fma_f32 v[8:9], v[44:45], v[68:69], v[8:9] op_sel_hi:[1,0,1]
	v_pk_fma_f32 v[38:39], v[8:9], v[68:69], v[38:39] op_sel:[0,1,0] op_sel_hi:[1,1,1]
	s_waitcnt lgkmcnt(2)
	v_pk_fma_f32 v[10:11], v[44:45], v[70:71], v[10:11] op_sel_hi:[1,0,1]
	v_pk_fma_f32 v[38:39], v[10:11], v[70:71], v[38:39] op_sel:[0,1,0] op_sel_hi:[1,1,1]
	v_pk_fma_f32 v[12:13], v[44:45], v[72:73], v[12:13] op_sel_hi:[1,0,1]
	v_pk_fma_f32 v[38:39], v[12:13], v[72:73], v[38:39] op_sel:[0,1,0] op_sel_hi:[1,1,1]
	s_waitcnt lgkmcnt(1)
	v_pk_fma_f32 v[14:15], v[44:45], v[74:75], v[14:15] op_sel_hi:[1,0,1]
	v_pk_fma_f32 v[38:39], v[14:15], v[74:75], v[38:39] op_sel:[0,1,0] op_sel_hi:[1,1,1]
	v_pk_fma_f32 v[16:17], v[44:45], v[76:77], v[16:17] op_sel_hi:[1,0,1]
	v_pk_fma_f32 v[38:39], v[16:17], v[76:77], v[38:39] op_sel:[0,1,0] op_sel_hi:[1,1,1]
	s_waitcnt lgkmcnt(0)
	v_pk_fma_f32 v[18:19], v[44:45], v[78:79], v[18:19] op_sel_hi:[1,0,1]
	v_pk_fma_f32 v[38:39], v[18:19], v[78:79], v[38:39] op_sel:[0,1,0] op_sel_hi:[1,1,1]
	v_pk_fma_f32 v[20:21], v[44:45], v[80:81], v[20:21] op_sel_hi:[1,0,1]
	v_pk_fma_f32 v[38:39], v[20:21], v[80:81], v[38:39] op_sel:[0,1,0] op_sel_hi:[1,1,1]
	s_add_u32 s14, s14, 0x1000
	s_addc_u32 s15, s15, 0
	v_add_f32_dpp v38, v38, v38 row_ror:8 row_mask:0xf bank_mask:0x3 bound_ctrl:1
	v_add_f32_dpp v38, v39, v39 row_ror:8 row_mask:0xf bank_mask:0xc bound_ctrl:1
	ds_read_b64 v[64:65], v23 offset:38144
	ds_read_b128 v[48:51], v2 offset:61696
	v_add_f32_dpp v38, v38, v38 row_half_mirror row_mask:0xf bank_mask:0xf bound_ctrl:1
	ds_read_b128 v[52:55], v2 offset:61952
	ds_read_b128 v[56:59], v2 offset:62208
	v_add_f32_dpp v38, v38, v38 quad_perm:[1,0,3,2] row_mask:0xf bank_mask:0xf bound_ctrl:1
	ds_read_b128 v[60:63], v2 offset:62464
	s_nop 0
	v_add_f32_dpp v38, v38, v38 quad_perm:[2,3,0,1] row_mask:0xf bank_mask:0xf bound_ctrl:1
	s_nop 1
	v_mov_b32_dpp v39, v38 row_ror:8 row_mask:0xf bank_mask:0xf bound_ctrl:1
	v_pk_mul_f32 v[38:39], v[38:39], v[40:41] op_sel:[0,1] op_sel_hi:[1,1]
	v_cvt_pk_bf16_f32 v47, v38, v39
	s_mov_b64 exec, s[2:3]
	global_store_dword v46, v47, s[14:15] offset:-4096
	s_mov_b64 exec, -1
	s_waitcnt lgkmcnt(4)
	v_pk_mul_f32 v[40:41], v[40:41], v[42:43]
	v_pk_mul_f32 v[44:45], v[64:65], v[40:41] op_sel_hi:[1,0]
	s_waitcnt lgkmcnt(3)
	v_pk_fma_f32 v[6:7], v[44:45], v[48:49], v[6:7] op_sel_hi:[1,0,1]
	v_pk_mul_f32 v[38:39], v[6:7], v[48:49] op_sel:[0,1] op_sel_hi:[1,1]
	v_pk_fma_f32 v[8:9], v[44:45], v[50:51], v[8:9] op_sel_hi:[1,0,1]
	v_pk_fma_f32 v[38:39], v[8:9], v[50:51], v[38:39] op_sel:[0,1,0] op_sel_hi:[1,1,1]
	s_waitcnt lgkmcnt(2)
	v_pk_fma_f32 v[10:11], v[44:45], v[52:53], v[10:11] op_sel_hi:[1,0,1]
	v_pk_fma_f32 v[38:39], v[10:11], v[52:53], v[38:39] op_sel:[0,1,0] op_sel_hi:[1,1,1]
	v_pk_fma_f32 v[12:13], v[44:45], v[54:55], v[12:13] op_sel_hi:[1,0,1]
	v_pk_fma_f32 v[38:39], v[12:13], v[54:55], v[38:39] op_sel:[0,1,0] op_sel_hi:[1,1,1]
	s_waitcnt lgkmcnt(1)
	v_pk_fma_f32 v[14:15], v[44:45], v[56:57], v[14:15] op_sel_hi:[1,0,1]
	v_pk_fma_f32 v[38:39], v[14:15], v[56:57], v[38:39] op_sel:[0,1,0] op_sel_hi:[1,1,1]
	v_pk_fma_f32 v[16:17], v[44:45], v[58:59], v[16:17] op_sel_hi:[1,0,1]
	v_pk_fma_f32 v[38:39], v[16:17], v[58:59], v[38:39] op_sel:[0,1,0] op_sel_hi:[1,1,1]
	s_waitcnt lgkmcnt(0)
	v_pk_fma_f32 v[18:19], v[44:45], v[60:61], v[18:19] op_sel_hi:[1,0,1]
	v_pk_fma_f32 v[38:39], v[18:19], v[60:61], v[38:39] op_sel:[0,1,0] op_sel_hi:[1,1,1]
	v_pk_fma_f32 v[20:21], v[44:45], v[62:63], v[20:21] op_sel_hi:[1,0,1]
	v_pk_fma_f32 v[38:39], v[20:21], v[62:63], v[38:39] op_sel:[0,1,0] op_sel_hi:[1,1,1]
	s_add_u32 s14, s14, 0x1000
	s_addc_u32 s15, s15, 0
	v_add_f32_dpp v38, v38, v38 row_ror:8 row_mask:0xf bank_mask:0x3 bound_ctrl:1
	v_add_f32_dpp v38, v39, v39 row_ror:8 row_mask:0xf bank_mask:0xc bound_ctrl:1
	ds_read_b64 v[82:83], v23 offset:38400
	ds_read_b128 v[66:69], v2 offset:62720
	v_add_f32_dpp v38, v38, v38 row_half_mirror row_mask:0xf bank_mask:0xf bound_ctrl:1
	ds_read_b128 v[70:73], v2 offset:62976
	ds_read_b128 v[74:77], v2 offset:63232
	v_add_f32_dpp v38, v38, v38 quad_perm:[1,0,3,2] row_mask:0xf bank_mask:0xf bound_ctrl:1
	ds_read_b128 v[78:81], v2 offset:63488
	s_nop 0
	v_add_f32_dpp v38, v38, v38 quad_perm:[2,3,0,1] row_mask:0xf bank_mask:0xf bound_ctrl:1
	s_nop 1
	v_mov_b32_dpp v39, v38 row_ror:8 row_mask:0xf bank_mask:0xf bound_ctrl:1
	v_pk_mul_f32 v[38:39], v[38:39], v[40:41] op_sel:[0,1] op_sel_hi:[1,1]
	v_cvt_pk_bf16_f32 v47, v38, v39
	s_mov_b64 exec, s[2:3]
	global_store_dword v46, v47, s[14:15] offset:-4096
	s_mov_b64 exec, -1
	s_waitcnt lgkmcnt(4)
	v_pk_mul_f32 v[40:41], v[40:41], v[42:43]
	v_pk_mul_f32 v[44:45], v[82:83], v[40:41] op_sel_hi:[1,0]
	s_waitcnt lgkmcnt(3)
	v_pk_fma_f32 v[6:7], v[44:45], v[66:67], v[6:7] op_sel_hi:[1,0,1]
	v_pk_mul_f32 v[38:39], v[6:7], v[66:67] op_sel:[0,1] op_sel_hi:[1,1]
	v_pk_fma_f32 v[8:9], v[44:45], v[68:69], v[8:9] op_sel_hi:[1,0,1]
	v_pk_fma_f32 v[38:39], v[8:9], v[68:69], v[38:39] op_sel:[0,1,0] op_sel_hi:[1,1,1]
	s_waitcnt lgkmcnt(2)
	v_pk_fma_f32 v[10:11], v[44:45], v[70:71], v[10:11] op_sel_hi:[1,0,1]
	v_pk_fma_f32 v[38:39], v[10:11], v[70:71], v[38:39] op_sel:[0,1,0] op_sel_hi:[1,1,1]
	v_pk_fma_f32 v[12:13], v[44:45], v[72:73], v[12:13] op_sel_hi:[1,0,1]
	v_pk_fma_f32 v[38:39], v[12:13], v[72:73], v[38:39] op_sel:[0,1,0] op_sel_hi:[1,1,1]
	s_waitcnt lgkmcnt(1)
	v_pk_fma_f32 v[14:15], v[44:45], v[74:75], v[14:15] op_sel_hi:[1,0,1]
	v_pk_fma_f32 v[38:39], v[14:15], v[74:75], v[38:39] op_sel:[0,1,0] op_sel_hi:[1,1,1]
	v_pk_fma_f32 v[16:17], v[44:45], v[76:77], v[16:17] op_sel_hi:[1,0,1]
	v_pk_fma_f32 v[38:39], v[16:17], v[76:77], v[38:39] op_sel:[0,1,0] op_sel_hi:[1,1,1]
	s_waitcnt lgkmcnt(0)
	v_pk_fma_f32 v[18:19], v[44:45], v[78:79], v[18:19] op_sel_hi:[1,0,1]
	v_pk_fma_f32 v[38:39], v[18:19], v[78:79], v[38:39] op_sel:[0,1,0] op_sel_hi:[1,1,1]
	v_pk_fma_f32 v[20:21], v[44:45], v[80:81], v[20:21] op_sel_hi:[1,0,1]
	v_pk_fma_f32 v[38:39], v[20:21], v[80:81], v[38:39] op_sel:[0,1,0] op_sel_hi:[1,1,1]
	s_add_u32 s14, s14, 0x1000
	s_addc_u32 s15, s15, 0
	v_add_f32_dpp v38, v38, v38 row_ror:8 row_mask:0xf bank_mask:0x3 bound_ctrl:1
	v_add_f32_dpp v38, v39, v39 row_ror:8 row_mask:0xf bank_mask:0xc bound_ctrl:1
	ds_read_b64 v[64:65], v23 offset:38656
	ds_read_b128 v[48:51], v2 offset:63744
	v_add_f32_dpp v38, v38, v38 row_half_mirror row_mask:0xf bank_mask:0xf bound_ctrl:1
	ds_read_b128 v[52:55], v2 offset:64000
	ds_read_b128 v[56:59], v2 offset:64256
	v_add_f32_dpp v38, v38, v38 quad_perm:[1,0,3,2] row_mask:0xf bank_mask:0xf bound_ctrl:1
	ds_read_b128 v[60:63], v2 offset:64512
	s_nop 0
	v_add_f32_dpp v38, v38, v38 quad_perm:[2,3,0,1] row_mask:0xf bank_mask:0xf bound_ctrl:1
	s_nop 1
	v_mov_b32_dpp v39, v38 row_ror:8 row_mask:0xf bank_mask:0xf bound_ctrl:1
	v_pk_mul_f32 v[38:39], v[38:39], v[40:41] op_sel:[0,1] op_sel_hi:[1,1]
	v_cvt_pk_bf16_f32 v47, v38, v39
	s_mov_b64 exec, s[2:3]
	global_store_dword v46, v47, s[14:15] offset:-4096
	s_mov_b64 exec, -1
	s_waitcnt lgkmcnt(4)
	v_pk_mul_f32 v[40:41], v[40:41], v[42:43]
	v_pk_mul_f32 v[44:45], v[64:65], v[40:41] op_sel_hi:[1,0]
	s_waitcnt lgkmcnt(3)
	v_pk_fma_f32 v[6:7], v[44:45], v[48:49], v[6:7] op_sel_hi:[1,0,1]
	v_pk_mul_f32 v[38:39], v[6:7], v[48:49] op_sel:[0,1] op_sel_hi:[1,1]
	v_pk_fma_f32 v[8:9], v[44:45], v[50:51], v[8:9] op_sel_hi:[1,0,1]
	v_pk_fma_f32 v[38:39], v[8:9], v[50:51], v[38:39] op_sel:[0,1,0] op_sel_hi:[1,1,1]
	s_waitcnt lgkmcnt(2)
	v_pk_fma_f32 v[10:11], v[44:45], v[52:53], v[10:11] op_sel_hi:[1,0,1]
	v_pk_fma_f32 v[38:39], v[10:11], v[52:53], v[38:39] op_sel:[0,1,0] op_sel_hi:[1,1,1]
	v_pk_fma_f32 v[12:13], v[44:45], v[54:55], v[12:13] op_sel_hi:[1,0,1]
	v_pk_fma_f32 v[38:39], v[12:13], v[54:55], v[38:39] op_sel:[0,1,0] op_sel_hi:[1,1,1]
	s_waitcnt lgkmcnt(1)
	v_pk_fma_f32 v[14:15], v[44:45], v[56:57], v[14:15] op_sel_hi:[1,0,1]
	v_pk_fma_f32 v[38:39], v[14:15], v[56:57], v[38:39] op_sel:[0,1,0] op_sel_hi:[1,1,1]
	v_pk_fma_f32 v[16:17], v[44:45], v[58:59], v[16:17] op_sel_hi:[1,0,1]
	v_pk_fma_f32 v[38:39], v[16:17], v[58:59], v[38:39] op_sel:[0,1,0] op_sel_hi:[1,1,1]
	s_waitcnt lgkmcnt(0)
	v_pk_fma_f32 v[18:19], v[44:45], v[60:61], v[18:19] op_sel_hi:[1,0,1]
	v_pk_fma_f32 v[38:39], v[18:19], v[60:61], v[38:39] op_sel:[0,1,0] op_sel_hi:[1,1,1]
	v_pk_fma_f32 v[20:21], v[44:45], v[62:63], v[20:21] op_sel_hi:[1,0,1]
	v_pk_fma_f32 v[38:39], v[20:21], v[62:63], v[38:39] op_sel:[0,1,0] op_sel_hi:[1,1,1]
	s_add_u32 s14, s14, 0x1000
	s_addc_u32 s15, s15, 0
	v_add_f32_dpp v38, v38, v38 row_ror:8 row_mask:0xf bank_mask:0x3 bound_ctrl:1
	v_add_f32_dpp v38, v39, v39 row_ror:8 row_mask:0xf bank_mask:0xc bound_ctrl:1
	ds_read_b64 v[82:83], v23 offset:38912
	ds_read_b128 v[66:69], v2 offset:64768
	v_add_f32_dpp v38, v38, v38 row_half_mirror row_mask:0xf bank_mask:0xf bound_ctrl:1
	ds_read_b128 v[70:73], v2 offset:65024
	ds_read_b128 v[74:77], v2 offset:65280
	v_add_f32_dpp v38, v38, v38 quad_perm:[1,0,3,2] row_mask:0xf bank_mask:0xf bound_ctrl:1
	ds_read_b128 v[78:81], v22 offset:32768
	s_nop 0
	v_add_f32_dpp v38, v38, v38 quad_perm:[2,3,0,1] row_mask:0xf bank_mask:0xf bound_ctrl:1
	s_nop 1
	v_mov_b32_dpp v39, v38 row_ror:8 row_mask:0xf bank_mask:0xf bound_ctrl:1
	v_pk_mul_f32 v[38:39], v[38:39], v[40:41] op_sel:[0,1] op_sel_hi:[1,1]
	v_cvt_pk_bf16_f32 v47, v38, v39
	s_mov_b64 exec, s[2:3]
	global_store_dword v46, v47, s[14:15] offset:-4096
	s_mov_b64 exec, -1
	s_waitcnt lgkmcnt(4)
	v_pk_mul_f32 v[40:41], v[40:41], v[42:43]
	v_pk_mul_f32 v[44:45], v[82:83], v[40:41] op_sel_hi:[1,0]
	s_waitcnt lgkmcnt(3)
	v_pk_fma_f32 v[6:7], v[44:45], v[66:67], v[6:7] op_sel_hi:[1,0,1]
	v_pk_mul_f32 v[38:39], v[6:7], v[66:67] op_sel:[0,1] op_sel_hi:[1,1]
	v_pk_fma_f32 v[8:9], v[44:45], v[68:69], v[8:9] op_sel_hi:[1,0,1]
	v_pk_fma_f32 v[38:39], v[8:9], v[68:69], v[38:39] op_sel:[0,1,0] op_sel_hi:[1,1,1]
	s_waitcnt lgkmcnt(2)
	v_pk_fma_f32 v[10:11], v[44:45], v[70:71], v[10:11] op_sel_hi:[1,0,1]
	v_pk_fma_f32 v[38:39], v[10:11], v[70:71], v[38:39] op_sel:[0,1,0] op_sel_hi:[1,1,1]
	v_pk_fma_f32 v[12:13], v[44:45], v[72:73], v[12:13] op_sel_hi:[1,0,1]
	v_pk_fma_f32 v[38:39], v[12:13], v[72:73], v[38:39] op_sel:[0,1,0] op_sel_hi:[1,1,1]
	s_waitcnt lgkmcnt(1)
	v_pk_fma_f32 v[14:15], v[44:45], v[74:75], v[14:15] op_sel_hi:[1,0,1]
	v_pk_fma_f32 v[38:39], v[14:15], v[74:75], v[38:39] op_sel:[0,1,0] op_sel_hi:[1,1,1]
	v_pk_fma_f32 v[16:17], v[44:45], v[76:77], v[16:17] op_sel_hi:[1,0,1]
	v_pk_fma_f32 v[38:39], v[16:17], v[76:77], v[38:39] op_sel:[0,1,0] op_sel_hi:[1,1,1]
	s_waitcnt lgkmcnt(0)
	v_pk_fma_f32 v[18:19], v[44:45], v[78:79], v[18:19] op_sel_hi:[1,0,1]
	v_pk_fma_f32 v[38:39], v[18:19], v[78:79], v[38:39] op_sel:[0,1,0] op_sel_hi:[1,1,1]
	v_pk_fma_f32 v[20:21], v[44:45], v[80:81], v[20:21] op_sel_hi:[1,0,1]
	v_pk_fma_f32 v[38:39], v[20:21], v[80:81], v[38:39] op_sel:[0,1,0] op_sel_hi:[1,1,1]
	s_add_u32 s14, s14, 0x1000
	s_addc_u32 s15, s15, 0
	v_add_f32_dpp v38, v38, v38 row_ror:8 row_mask:0xf bank_mask:0x3 bound_ctrl:1
	v_add_f32_dpp v38, v39, v39 row_ror:8 row_mask:0xf bank_mask:0xc bound_ctrl:1
	ds_read_b64 v[64:65], v3 offset:20736
	ds_read_b128 v[48:51], v2 offset:8448
	v_add_f32_dpp v38, v38, v38 row_half_mirror row_mask:0xf bank_mask:0xf bound_ctrl:1
	ds_read_b128 v[52:55], v2 offset:8704
	ds_read_b128 v[56:59], v2 offset:8960
	v_add_f32_dpp v38, v38, v38 quad_perm:[1,0,3,2] row_mask:0xf bank_mask:0xf bound_ctrl:1
	ds_read_b128 v[60:63], v2 offset:9216
	s_nop 0
	v_add_f32_dpp v38, v38, v38 quad_perm:[2,3,0,1] row_mask:0xf bank_mask:0xf bound_ctrl:1
	s_nop 1
	v_mov_b32_dpp v39, v38 row_ror:8 row_mask:0xf bank_mask:0xf bound_ctrl:1
	v_pk_mul_f32 v[38:39], v[38:39], v[40:41] op_sel:[0,1] op_sel_hi:[1,1]
	v_cvt_pk_bf16_f32 v47, v38, v39
	s_mov_b64 exec, s[2:3]
	global_store_dword v46, v47, s[14:15] offset:-4096
	s_mov_b64 exec, -1
	s_waitcnt vmcnt(8)
	v_lshlrev_b32_e32 v108, 16, v84
	v_lshlrev_b32_e32 v109, 16, v85
	v_and_b32_e32 v110, s17, v84
	v_and_b32_e32 v111, s17, v85
	v_lshlrev_b32_e32 v112, 16, v86
	v_lshlrev_b32_e32 v113, 16, v87
	v_and_b32_e32 v114, s17, v86
	v_and_b32_e32 v115, s17, v87
	v_lshlrev_b32_e32 v116, 16, v88
	v_and_b32_e32 v117, s17, v88
	ds_write_b128 v29, v[108:111] offset:24832
	ds_write_b128 v29, v[112:115] offset:33024
	ds_write_b64 v30, v[90:91] offset:24832
	ds_write_b64 v31, v[116:117] offset:24832
	s_add_i32 s16, s16, 8
	s_waitcnt lgkmcnt(0)
	s_barrier
	s_cmpk_lt_u32 s16, 0x800
	s_cbranch_scc1 .Lret2_loop

.Lgla2_loop:
	global_load_dword v110, v32, s[10:11]
	global_load_dword v111, v32, s[10:11] offset:-1024
	global_load_dword v112, v33, s[10:11]
	global_load_dword v113, v33, s[10:11] offset:-1024
	global_load_dword v114, v34, s[10:11]
	global_load_dword v116, v35, s[12:13]
	global_load_dword v117, v35, s[12:13] offset:4
	s_add_u32 s10, s10, 0x18000
	s_addc_u32 s11, s11, 0
	s_add_u32 s12, s12, 0x4000
	s_addc_u32 s13, s13, 0
	s_waitcnt lgkmcnt(4)
	v_pk_mul_f32 v[42:43], v[72:73], v[48:49] op_sel_hi:[1,0]
	v_pk_fma_f32 v[6:7], v[6:7], v[64:65], v[42:43] op_sel:[0,0,0] op_sel_hi:[1,0,1]
	v_pk_mul_f32 v[38:39], v[6:7], v[48:49] op_sel:[0,1] op_sel_hi:[1,1]
	v_pk_mul_f32 v[44:45], v[72:73], v[50:51] op_sel_hi:[1,0]
	v_pk_fma_f32 v[8:9], v[8:9], v[64:65], v[44:45] op_sel:[0,1,0] op_sel_hi:[1,1,1]
	v_pk_fma_f32 v[38:39], v[8:9], v[50:51], v[38:39] op_sel:[0,1,0] op_sel_hi:[1,1,1]
	s_waitcnt lgkmcnt(3)
	v_pk_mul_f32 v[42:43], v[72:73], v[52:53] op_sel_hi:[1,0]
	v_pk_fma_f32 v[10:11], v[10:11], v[66:67], v[42:43] op_sel:[0,0,0] op_sel_hi:[1,0,1]
	v_pk_fma_f32 v[38:39], v[10:11], v[52:53], v[38:39] op_sel:[0,1,0] op_sel_hi:[1,1,1]
	v_pk_mul_f32 v[44:45], v[72:73], v[54:55] op_sel_hi:[1,0]
	v_pk_fma_f32 v[12:13], v[12:13], v[66:67], v[44:45] op_sel:[0,1,0] op_sel_hi:[1,1,1]
	v_pk_fma_f32 v[38:39], v[12:13], v[54:55], v[38:39] op_sel:[0,1,0] op_sel_hi:[1,1,1]
	s_waitcnt lgkmcnt(1)
	v_pk_mul_f32 v[42:43], v[72:73], v[56:57] op_sel_hi:[1,0]
	v_pk_fma_f32 v[14:15], v[14:15], v[68:69], v[42:43] op_sel:[0,0,0] op_sel_hi:[1,0,1]
	v_pk_fma_f32 v[38:39], v[14:15], v[56:57], v[38:39] op_sel:[0,1,0] op_sel_hi:[1,1,1]
	v_pk_mul_f32 v[44:45], v[72:73], v[58:59] op_sel_hi:[1,0]
	v_pk_fma_f32 v[16:17], v[16:17], v[68:69], v[44:45] op_sel:[0,1,0] op_sel_hi:[1,1,1]
	v_pk_fma_f32 v[38:39], v[16:17], v[58:59], v[38:39] op_sel:[0,1,0] op_sel_hi:[1,1,1]
	s_waitcnt lgkmcnt(0)
	v_pk_mul_f32 v[42:43], v[72:73], v[60:61] op_sel_hi:[1,0]
	v_pk_fma_f32 v[18:19], v[18:19], v[70:71], v[42:43] op_sel:[0,0,0] op_sel_hi:[1,0,1]
	v_pk_fma_f32 v[38:39], v[18:19], v[60:61], v[38:39] op_sel:[0,1,0] op_sel_hi:[1,1,1]
	v_pk_mul_f32 v[44:45], v[72:73], v[62:63] op_sel_hi:[1,0]
	v_pk_fma_f32 v[20:21], v[20:21], v[70:71], v[44:45] op_sel:[0,1,0] op_sel_hi:[1,1,1]
	v_pk_fma_f32 v[38:39], v[20:21], v[62:63], v[38:39] op_sel:[0,1,0] op_sel_hi:[1,1,1]
	s_add_u32 s14, s14, 0x1000
	s_addc_u32 s15, s15, 0
	v_add_f32_dpp v38, v38, v38 row_ror:8 row_mask:0xf bank_mask:0x3 bound_ctrl:1
	v_add_f32_dpp v38, v39, v39 row_ror:8 row_mask:0xf bank_mask:0xc bound_ctrl:1
	ds_read_b64 v[104:105], v3 offset:20992
	ds_read_b128 v[80:83], v2 offset:1280
	v_add_f32_dpp v38, v38, v38 row_half_mirror row_mask:0xf bank_mask:0xf bound_ctrl:1
	ds_read_b128 v[96:99], v2 offset:17152
	ds_read_b128 v[84:87], v2 offset:1536
	v_add_f32_dpp v38, v38, v38 quad_perm:[1,0,3,2] row_mask:0xf bank_mask:0xf bound_ctrl:1
	ds_read_b128 v[88:91], v2 offset:1792
	ds_read_b128 v[100:103], v2 offset:17408
	v_add_f32_dpp v38, v38, v38 quad_perm:[2,3,0,1] row_mask:0xf bank_mask:0xf bound_ctrl:1
	ds_read_b128 v[92:95], v2 offset:2048
	s_nop 0
	v_mov_b32_dpp v39, v38 row_ror:8 row_mask:0xf bank_mask:0xf bound_ctrl:1
	v_pk_mul_f32 v[38:39], v[38:39], v[40:41] op_sel_hi:[1,0]
	v_cvt_pk_bf16_f32 v47, v38, v39
	s_mov_b64 exec, s[2:3]
	global_store_dword v46, v47, s[14:15] offset:-4096
	s_mov_b64 exec, -1
	s_waitcnt lgkmcnt(4)
	v_pk_mul_f32 v[42:43], v[104:105], v[80:81] op_sel_hi:[1,0]
	v_pk_fma_f32 v[6:7], v[6:7], v[96:97], v[42:43] op_sel:[0,0,0] op_sel_hi:[1,0,1]
	v_pk_mul_f32 v[38:39], v[6:7], v[80:81] op_sel:[0,1] op_sel_hi:[1,1]
	v_pk_mul_f32 v[44:45], v[104:105], v[82:83] op_sel_hi:[1,0]
	v_pk_fma_f32 v[8:9], v[8:9], v[96:97], v[44:45] op_sel:[0,1,0] op_sel_hi:[1,1,1]
	v_pk_fma_f32 v[38:39], v[8:9], v[82:83], v[38:39] op_sel:[0,1,0] op_sel_hi:[1,1,1]
	s_waitcnt lgkmcnt(3)
	v_pk_mul_f32 v[42:43], v[104:105], v[84:85] op_sel_hi:[1,0]
	v_pk_fma_f32 v[10:11], v[10:11], v[98:99], v[42:43] op_sel:[0,0,0] op_sel_hi:[1,0,1]
	v_pk_fma_f32 v[38:39], v[10:11], v[84:85], v[38:39] op_sel:[0,1,0] op_sel_hi:[1,1,1]
	v_pk_mul_f32 v[44:45], v[104:105], v[86:87] op_sel_hi:[1,0]
	v_pk_fma_f32 v[12:13], v[12:13], v[98:99], v[44:45] op_sel:[0,1,0] op_sel_hi:[1,1,1]
	v_pk_fma_f32 v[38:39], v[12:13], v[86:87], v[38:39] op_sel:[0,1,0] op_sel_hi:[1,1,1]
	s_waitcnt lgkmcnt(1)
	v_pk_mul_f32 v[42:43], v[104:105], v[88:89] op_sel_hi:[1,0]
	v_pk_fma_f32 v[14:15], v[14:15], v[100:101], v[42:43] op_sel:[0,0,0] op_sel_hi:[1,0,1]
	v_pk_fma_f32 v[38:39], v[14:15], v[88:89], v[38:39] op_sel:[0,1,0] op_sel_hi:[1,1,1]
	v_pk_mul_f32 v[44:45], v[104:105], v[90:91] op_sel_hi:[1,0]
	v_pk_fma_f32 v[16:17], v[16:17], v[100:101], v[44:45] op_sel:[0,1,0] op_sel_hi:[1,1,1]
	v_pk_fma_f32 v[38:39], v[16:17], v[90:91], v[38:39] op_sel:[0,1,0] op_sel_hi:[1,1,1]
	s_waitcnt lgkmcnt(0)
	v_pk_mul_f32 v[42:43], v[104:105], v[92:93] op_sel_hi:[1,0]
	v_pk_fma_f32 v[18:19], v[18:19], v[102:103], v[42:43] op_sel:[0,0,0] op_sel_hi:[1,0,1]
	v_pk_fma_f32 v[38:39], v[18:19], v[92:93], v[38:39] op_sel:[0,1,0] op_sel_hi:[1,1,1]
	v_pk_mul_f32 v[44:45], v[104:105], v[94:95] op_sel_hi:[1,0]
	v_pk_fma_f32 v[20:21], v[20:21], v[102:103], v[44:45] op_sel:[0,1,0] op_sel_hi:[1,1,1]
	v_pk_fma_f32 v[38:39], v[20:21], v[94:95], v[38:39] op_sel:[0,1,0] op_sel_hi:[1,1,1]
	s_add_u32 s14, s14, 0x1000
	s_addc_u32 s15, s15, 0
	v_add_f32_dpp v38, v38, v38 row_ror:8 row_mask:0xf bank_mask:0x3 bound_ctrl:1
	v_add_f32_dpp v38, v39, v39 row_ror:8 row_mask:0xf bank_mask:0xc bound_ctrl:1
	ds_read_b64 v[72:73], v3 offset:21248
	ds_read_b128 v[48:51], v2 offset:2304
	v_add_f32_dpp v38, v38, v38 row_half_mirror row_mask:0xf bank_mask:0xf bound_ctrl:1
	ds_read_b128 v[64:67], v2 offset:17664
	ds_read_b128 v[52:55], v2 offset:2560
	v_add_f32_dpp v38, v38, v38 quad_perm:[1,0,3,2] row_mask:0xf bank_mask:0xf bound_ctrl:1
	ds_read_b128 v[56:59], v2 offset:2816
	ds_read_b128 v[68:71], v2 offset:17920
	v_add_f32_dpp v38, v38, v38 quad_perm:[2,3,0,1] row_mask:0xf bank_mask:0xf bound_ctrl:1
	ds_read_b128 v[60:63], v2 offset:3072
	s_nop 0
	v_mov_b32_dpp v39, v38 row_ror:8 row_mask:0xf bank_mask:0xf bound_ctrl:1
	v_pk_mul_f32 v[38:39], v[38:39], v[40:41] op_sel_hi:[1,0]
	v_cvt_pk_bf16_f32 v47, v38, v39
	s_mov_b64 exec, s[2:3]
	global_store_dword v46, v47, s[14:15] offset:-4096
	s_mov_b64 exec, -1
	s_waitcnt lgkmcnt(4)
	v_pk_mul_f32 v[42:43], v[72:73], v[48:49] op_sel_hi:[1,0]
	v_pk_fma_f32 v[6:7], v[6:7], v[64:65], v[42:43] op_sel:[0,0,0] op_sel_hi:[1,0,1]
	v_pk_mul_f32 v[38:39], v[6:7], v[48:49] op_sel:[0,1] op_sel_hi:[1,1]
	v_pk_mul_f32 v[44:45], v[72:73], v[50:51] op_sel_hi:[1,0]
	v_pk_fma_f32 v[8:9], v[8:9], v[64:65], v[44:45] op_sel:[0,1,0] op_sel_hi:[1,1,1]
	v_pk_fma_f32 v[38:39], v[8:9], v[50:51], v[38:39] op_sel:[0,1,0] op_sel_hi:[1,1,1]
	s_waitcnt lgkmcnt(3)
	v_pk_mul_f32 v[42:43], v[72:73], v[52:53] op_sel_hi:[1,0]
	v_pk_fma_f32 v[10:11], v[10:11], v[66:67], v[42:43] op_sel:[0,0,0] op_sel_hi:[1,0,1]
	v_pk_fma_f32 v[38:39], v[10:11], v[52:53], v[38:39] op_sel:[0,1,0] op_sel_hi:[1,1,1]
	v_pk_mul_f32 v[44:45], v[72:73], v[54:55] op_sel_hi:[1,0]
	v_pk_fma_f32 v[12:13], v[12:13], v[66:67], v[44:45] op_sel:[0,1,0] op_sel_hi:[1,1,1]
	v_pk_fma_f32 v[38:39], v[12:13], v[54:55], v[38:39] op_sel:[0,1,0] op_sel_hi:[1,1,1]
	s_waitcnt lgkmcnt(1)
	v_pk_mul_f32 v[42:43], v[72:73], v[56:57] op_sel_hi:[1,0]
	v_pk_fma_f32 v[14:15], v[14:15], v[68:69], v[42:43] op_sel:[0,0,0] op_sel_hi:[1,0,1]
	v_pk_fma_f32 v[38:39], v[14:15], v[56:57], v[38:39] op_sel:[0,1,0] op_sel_hi:[1,1,1]
	v_pk_mul_f32 v[44:45], v[72:73], v[58:59] op_sel_hi:[1,0]
	v_pk_fma_f32 v[16:17], v[16:17], v[68:69], v[44:45] op_sel:[0,1,0] op_sel_hi:[1,1,1]
	v_pk_fma_f32 v[38:39], v[16:17], v[58:59], v[38:39] op_sel:[0,1,0] op_sel_hi:[1,1,1]
	s_waitcnt lgkmcnt(0)
	v_pk_mul_f32 v[42:43], v[72:73], v[60:61] op_sel_hi:[1,0]
	v_pk_fma_f32 v[18:19], v[18:19], v[70:71], v[42:43] op_sel:[0,0,0] op_sel_hi:[1,0,1]
	v_pk_fma_f32 v[38:39], v[18:19], v[60:61], v[38:39] op_sel:[0,1,0] op_sel_hi:[1,1,1]
	v_pk_mul_f32 v[44:45], v[72:73], v[62:63] op_sel_hi:[1,0]
	v_pk_fma_f32 v[20:21], v[20:21], v[70:71], v[44:45] op_sel:[0,1,0] op_sel_hi:[1,1,1]
	v_pk_fma_f32 v[38:39], v[20:21], v[62:63], v[38:39] op_sel:[0,1,0] op_sel_hi:[1,1,1]
	s_add_u32 s14, s14, 0x1000
	s_addc_u32 s15, s15, 0
	v_add_f32_dpp v38, v38, v38 row_ror:8 row_mask:0xf bank_mask:0x3 bound_ctrl:1
	v_add_f32_dpp v38, v39, v39 row_ror:8 row_mask:0xf bank_mask:0xc bound_ctrl:1
	ds_read_b64 v[104:105], v3 offset:21504
	ds_read_b128 v[80:83], v2 offset:3328
	v_add_f32_dpp v38, v38, v38 row_half_mirror row_mask:0xf bank_mask:0xf bound_ctrl:1
	ds_read_b128 v[96:99], v2 offset:18176
	ds_read_b128 v[84:87], v2 offset:3584
	v_add_f32_dpp v38, v38, v38 quad_perm:[1,0,3,2] row_mask:0xf bank_mask:0xf bound_ctrl:1
	ds_read_b128 v[88:91], v2 offset:3840
	ds_read_b128 v[100:103], v2 offset:18432
	v_add_f32_dpp v38, v38, v38 quad_perm:[2,3,0,1] row_mask:0xf bank_mask:0xf bound_ctrl:1
	ds_read_b128 v[92:95], v2 offset:4096
	s_nop 0
	v_mov_b32_dpp v39, v38 row_ror:8 row_mask:0xf bank_mask:0xf bound_ctrl:1
	v_pk_mul_f32 v[38:39], v[38:39], v[40:41] op_sel_hi:[1,0]
	v_cvt_pk_bf16_f32 v47, v38, v39
	s_mov_b64 exec, s[2:3]
	global_store_dword v46, v47, s[14:15] offset:-4096
	s_mov_b64 exec, -1
	s_waitcnt lgkmcnt(4)
	v_pk_mul_f32 v[42:43], v[104:105], v[80:81] op_sel_hi:[1,0]
	v_pk_fma_f32 v[6:7], v[6:7], v[96:97], v[42:43] op_sel:[0,0,0] op_sel_hi:[1,0,1]
	v_pk_mul_f32 v[38:39], v[6:7], v[80:81] op_sel:[0,1] op_sel_hi:[1,1]
	v_pk_mul_f32 v[44:45], v[104:105], v[82:83] op_sel_hi:[1,0]
	v_pk_fma_f32 v[8:9], v[8:9], v[96:97], v[44:45] op_sel:[0,1,0] op_sel_hi:[1,1,1]
	v_pk_fma_f32 v[38:39], v[8:9], v[82:83], v[38:39] op_sel:[0,1,0] op_sel_hi:[1,1,1]
	s_waitcnt lgkmcnt(3)
	v_pk_mul_f32 v[42:43], v[104:105], v[84:85] op_sel_hi:[1,0]
	v_pk_fma_f32 v[10:11], v[10:11], v[98:99], v[42:43] op_sel:[0,0,0] op_sel_hi:[1,0,1]
	v_pk_fma_f32 v[38:39], v[10:11], v[84:85], v[38:39] op_sel:[0,1,0] op_sel_hi:[1,1,1]
	v_pk_mul_f32 v[44:45], v[104:105], v[86:87] op_sel_hi:[1,0]
	v_pk_fma_f32 v[12:13], v[12:13], v[98:99], v[44:45] op_sel:[0,1,0] op_sel_hi:[1,1,1]
	v_pk_fma_f32 v[38:39], v[12:13], v[86:87], v[38:39] op_sel:[0,1,0] op_sel_hi:[1,1,1]
	s_waitcnt lgkmcnt(1)
	v_pk_mul_f32 v[42:43], v[104:105], v[88:89] op_sel_hi:[1,0]
	v_pk_fma_f32 v[14:15], v[14:15], v[100:101], v[42:43] op_sel:[0,0,0] op_sel_hi:[1,0,1]
	v_pk_fma_f32 v[38:39], v[14:15], v[88:89], v[38:39] op_sel:[0,1,0] op_sel_hi:[1,1,1]
	v_pk_mul_f32 v[44:45], v[104:105], v[90:91] op_sel_hi:[1,0]
	v_pk_fma_f32 v[16:17], v[16:17], v[100:101], v[44:45] op_sel:[0,1,0] op_sel_hi:[1,1,1]
	v_pk_fma_f32 v[38:39], v[16:17], v[90:91], v[38:39] op_sel:[0,1,0] op_sel_hi:[1,1,1]
	s_waitcnt lgkmcnt(0)
	v_pk_mul_f32 v[42:43], v[104:105], v[92:93] op_sel_hi:[1,0]
	v_pk_fma_f32 v[18:19], v[18:19], v[102:103], v[42:43] op_sel:[0,0,0] op_sel_hi:[1,0,1]
	v_pk_fma_f32 v[38:39], v[18:19], v[92:93], v[38:39] op_sel:[0,1,0] op_sel_hi:[1,1,1]
	v_pk_mul_f32 v[44:45], v[104:105], v[94:95] op_sel_hi:[1,0]
	v_pk_fma_f32 v[20:21], v[20:21], v[102:103], v[44:45] op_sel:[0,1,0] op_sel_hi:[1,1,1]
	v_pk_fma_f32 v[38:39], v[20:21], v[94:95], v[38:39] op_sel:[0,1,0] op_sel_hi:[1,1,1]
	s_add_u32 s14, s14, 0x1000
	s_addc_u32 s15, s15, 0
	v_add_f32_dpp v38, v38, v38 row_ror:8 row_mask:0xf bank_mask:0x3 bound_ctrl:1
	v_add_f32_dpp v38, v39, v39 row_ror:8 row_mask:0xf bank_mask:0xc bound_ctrl:1
	ds_read_b64 v[72:73], v3 offset:21760
	ds_read_b128 v[48:51], v2 offset:4352
	v_add_f32_dpp v38, v38, v38 row_half_mirror row_mask:0xf bank_mask:0xf bound_ctrl:1
	ds_read_b128 v[64:67], v2 offset:18688
	ds_read_b128 v[52:55], v2 offset:4608
	v_add_f32_dpp v38, v38, v38 quad_perm:[1,0,3,2] row_mask:0xf bank_mask:0xf bound_ctrl:1
	ds_read_b128 v[56:59], v2 offset:4864
	ds_read_b128 v[68:71], v2 offset:18944
	v_add_f32_dpp v38, v38, v38 quad_perm:[2,3,0,1] row_mask:0xf bank_mask:0xf bound_ctrl:1
	ds_read_b128 v[60:63], v2 offset:5120
	s_nop 0
	v_mov_b32_dpp v39, v38 row_ror:8 row_mask:0xf bank_mask:0xf bound_ctrl:1
	v_pk_mul_f32 v[38:39], v[38:39], v[40:41] op_sel_hi:[1,0]
	v_cvt_pk_bf16_f32 v47, v38, v39
	s_mov_b64 exec, s[2:3]
	global_store_dword v46, v47, s[14:15] offset:-4096
	s_mov_b64 exec, -1
	s_waitcnt lgkmcnt(4)
	v_pk_mul_f32 v[42:43], v[72:73], v[48:49] op_sel_hi:[1,0]
	v_pk_fma_f32 v[6:7], v[6:7], v[64:65], v[42:43] op_sel:[0,0,0] op_sel_hi:[1,0,1]
	v_pk_mul_f32 v[38:39], v[6:7], v[48:49] op_sel:[0,1] op_sel_hi:[1,1]
	v_pk_mul_f32 v[44:45], v[72:73], v[50:51] op_sel_hi:[1,0]
	v_pk_fma_f32 v[8:9], v[8:9], v[64:65], v[44:45] op_sel:[0,1,0] op_sel_hi:[1,1,1]
	v_pk_fma_f32 v[38:39], v[8:9], v[50:51], v[38:39] op_sel:[0,1,0] op_sel_hi:[1,1,1]
	s_waitcnt lgkmcnt(3)
	v_pk_mul_f32 v[42:43], v[72:73], v[52:53] op_sel_hi:[1,0]
	v_pk_fma_f32 v[10:11], v[10:11], v[66:67], v[42:43] op_sel:[0,0,0] op_sel_hi:[1,0,1]
	v_pk_fma_f32 v[38:39], v[10:11], v[52:53], v[38:39] op_sel:[0,1,0] op_sel_hi:[1,1,1]
	v_pk_mul_f32 v[44:45], v[72:73], v[54:55] op_sel_hi:[1,0]
	v_pk_fma_f32 v[12:13], v[12:13], v[66:67], v[44:45] op_sel:[0,1,0] op_sel_hi:[1,1,1]
	v_pk_fma_f32 v[38:39], v[12:13], v[54:55], v[38:39] op_sel:[0,1,0] op_sel_hi:[1,1,1]
	s_waitcnt lgkmcnt(1)
	v_pk_mul_f32 v[42:43], v[72:73], v[56:57] op_sel_hi:[1,0]
	v_pk_fma_f32 v[14:15], v[14:15], v[68:69], v[42:43] op_sel:[0,0,0] op_sel_hi:[1,0,1]
	v_pk_fma_f32 v[38:39], v[14:15], v[56:57], v[38:39] op_sel:[0,1,0] op_sel_hi:[1,1,1]
	v_pk_mul_f32 v[44:45], v[72:73], v[58:59] op_sel_hi:[1,0]
	v_pk_fma_f32 v[16:17], v[16:17], v[68:69], v[44:45] op_sel:[0,1,0] op_sel_hi:[1,1,1]
	v_pk_fma_f32 v[38:39], v[16:17], v[58:59], v[38:39] op_sel:[0,1,0] op_sel_hi:[1,1,1]
	s_waitcnt lgkmcnt(0)
	v_pk_mul_f32 v[42:43], v[72:73], v[60:61] op_sel_hi:[1,0]
	v_pk_fma_f32 v[18:19], v[18:19], v[70:71], v[42:43] op_sel:[0,0,0] op_sel_hi:[1,0,1]
	v_pk_fma_f32 v[38:39], v[18:19], v[60:61], v[38:39] op_sel:[0,1,0] op_sel_hi:[1,1,1]
	v_pk_mul_f32 v[44:45], v[72:73], v[62:63] op_sel_hi:[1,0]
	v_pk_fma_f32 v[20:21], v[20:21], v[70:71], v[44:45] op_sel:[0,1,0] op_sel_hi:[1,1,1]
	v_pk_fma_f32 v[38:39], v[20:21], v[62:63], v[38:39] op_sel:[0,1,0] op_sel_hi:[1,1,1]
	s_add_u32 s14, s14, 0x1000
	s_addc_u32 s15, s15, 0
	v_add_f32_dpp v38, v38, v38 row_ror:8 row_mask:0xf bank_mask:0x3 bound_ctrl:1
	v_add_f32_dpp v38, v39, v39 row_ror:8 row_mask:0xf bank_mask:0xc bound_ctrl:1
	ds_read_b64 v[104:105], v3 offset:22016
	ds_read_b128 v[80:83], v2 offset:5376
	v_add_f32_dpp v38, v38, v38 row_half_mirror row_mask:0xf bank_mask:0xf bound_ctrl:1
	ds_read_b128 v[96:99], v2 offset:19200
	ds_read_b128 v[84:87], v2 offset:5632
	v_add_f32_dpp v38, v38, v38 quad_perm:[1,0,3,2] row_mask:0xf bank_mask:0xf bound_ctrl:1
	ds_read_b128 v[88:91], v2 offset:5888
	ds_read_b128 v[100:103], v2 offset:19456
	v_add_f32_dpp v38, v38, v38 quad_perm:[2,3,0,1] row_mask:0xf bank_mask:0xf bound_ctrl:1
	ds_read_b128 v[92:95], v2 offset:6144
	s_nop 0
	v_mov_b32_dpp v39, v38 row_ror:8 row_mask:0xf bank_mask:0xf bound_ctrl:1
	v_pk_mul_f32 v[38:39], v[38:39], v[40:41] op_sel_hi:[1,0]
	v_cvt_pk_bf16_f32 v47, v38, v39
	s_mov_b64 exec, s[2:3]
	global_store_dword v46, v47, s[14:15] offset:-4096
	s_mov_b64 exec, -1
	s_waitcnt lgkmcnt(4)
	v_pk_mul_f32 v[42:43], v[104:105], v[80:81] op_sel_hi:[1,0]
	v_pk_fma_f32 v[6:7], v[6:7], v[96:97], v[42:43] op_sel:[0,0,0] op_sel_hi:[1,0,1]
	v_pk_mul_f32 v[38:39], v[6:7], v[80:81] op_sel:[0,1] op_sel_hi:[1,1]
	v_pk_mul_f32 v[44:45], v[104:105], v[82:83] op_sel_hi:[1,0]
	v_pk_fma_f32 v[8:9], v[8:9], v[96:97], v[44:45] op_sel:[0,1,0] op_sel_hi:[1,1,1]
	v_pk_fma_f32 v[38:39], v[8:9], v[82:83], v[38:39] op_sel:[0,1,0] op_sel_hi:[1,1,1]
	s_waitcnt lgkmcnt(3)
	v_pk_mul_f32 v[42:43], v[104:105], v[84:85] op_sel_hi:[1,0]
	v_pk_fma_f32 v[10:11], v[10:11], v[98:99], v[42:43] op_sel:[0,0,0] op_sel_hi:[1,0,1]
	v_pk_fma_f32 v[38:39], v[10:11], v[84:85], v[38:39] op_sel:[0,1,0] op_sel_hi:[1,1,1]
	v_pk_mul_f32 v[44:45], v[104:105], v[86:87] op_sel_hi:[1,0]
	v_pk_fma_f32 v[12:13], v[12:13], v[98:99], v[44:45] op_sel:[0,1,0] op_sel_hi:[1,1,1]
	v_pk_fma_f32 v[38:39], v[12:13], v[86:87], v[38:39] op_sel:[0,1,0] op_sel_hi:[1,1,1]
	s_waitcnt lgkmcnt(1)
	v_pk_mul_f32 v[42:43], v[104:105], v[88:89] op_sel_hi:[1,0]
	v_pk_fma_f32 v[14:15], v[14:15], v[100:101], v[42:43] op_sel:[0,0,0] op_sel_hi:[1,0,1]
	v_pk_fma_f32 v[38:39], v[14:15], v[88:89], v[38:39] op_sel:[0,1,0] op_sel_hi:[1,1,1]
	v_pk_mul_f32 v[44:45], v[104:105], v[90:91] op_sel_hi:[1,0]
	v_pk_fma_f32 v[16:17], v[16:17], v[100:101], v[44:45] op_sel:[0,1,0] op_sel_hi:[1,1,1]
	v_pk_fma_f32 v[38:39], v[16:17], v[90:91], v[38:39] op_sel:[0,1,0] op_sel_hi:[1,1,1]
	s_waitcnt lgkmcnt(0)
	v_pk_mul_f32 v[42:43], v[104:105], v[92:93] op_sel_hi:[1,0]
	v_pk_fma_f32 v[18:19], v[18:19], v[102:103], v[42:43] op_sel:[0,0,0] op_sel_hi:[1,0,1]
	v_pk_fma_f32 v[38:39], v[18:19], v[92:93], v[38:39] op_sel:[0,1,0] op_sel_hi:[1,1,1]
	v_pk_mul_f32 v[44:45], v[104:105], v[94:95] op_sel_hi:[1,0]
	v_pk_fma_f32 v[20:21], v[20:21], v[102:103], v[44:45] op_sel:[0,1,0] op_sel_hi:[1,1,1]
	v_pk_fma_f32 v[38:39], v[20:21], v[94:95], v[38:39] op_sel:[0,1,0] op_sel_hi:[1,1,1]
	s_add_u32 s14, s14, 0x1000
	s_addc_u32 s15, s15, 0
	v_add_f32_dpp v38, v38, v38 row_ror:8 row_mask:0xf bank_mask:0x3 bound_ctrl:1
	v_add_f32_dpp v38, v39, v39 row_ror:8 row_mask:0xf bank_mask:0xc bound_ctrl:1
	ds_read_b64 v[72:73], v3 offset:22272
	ds_read_b128 v[48:51], v2 offset:6400
	v_add_f32_dpp v38, v38, v38 row_half_mirror row_mask:0xf bank_mask:0xf bound_ctrl:1
	ds_read_b128 v[64:67], v2 offset:19712
	ds_read_b128 v[52:55], v2 offset:6656
	v_add_f32_dpp v38, v38, v38 quad_perm:[1,0,3,2] row_mask:0xf bank_mask:0xf bound_ctrl:1
	ds_read_b128 v[56:59], v2 offset:6912
	ds_read_b128 v[68:71], v2 offset:19968
	v_add_f32_dpp v38, v38, v38 quad_perm:[2,3,0,1] row_mask:0xf bank_mask:0xf bound_ctrl:1
	ds_read_b128 v[60:63], v2 offset:7168
	s_nop 0
	v_mov_b32_dpp v39, v38 row_ror:8 row_mask:0xf bank_mask:0xf bound_ctrl:1
	v_pk_mul_f32 v[38:39], v[38:39], v[40:41] op_sel_hi:[1,0]
	v_cvt_pk_bf16_f32 v47, v38, v39
	s_mov_b64 exec, s[2:3]
	global_store_dword v46, v47, s[14:15] offset:-4096
	s_mov_b64 exec, -1
	s_waitcnt lgkmcnt(4)
	v_pk_mul_f32 v[42:43], v[72:73], v[48:49] op_sel_hi:[1,0]
	v_pk_fma_f32 v[6:7], v[6:7], v[64:65], v[42:43] op_sel:[0,0,0] op_sel_hi:[1,0,1]
	v_pk_mul_f32 v[38:39], v[6:7], v[48:49] op_sel:[0,1] op_sel_hi:[1,1]
	v_pk_mul_f32 v[44:45], v[72:73], v[50:51] op_sel_hi:[1,0]
	v_pk_fma_f32 v[8:9], v[8:9], v[64:65], v[44:45] op_sel:[0,1,0] op_sel_hi:[1,1,1]
	v_pk_fma_f32 v[38:39], v[8:9], v[50:51], v[38:39] op_sel:[0,1,0] op_sel_hi:[1,1,1]
	s_waitcnt lgkmcnt(3)
	v_pk_mul_f32 v[42:43], v[72:73], v[52:53] op_sel_hi:[1,0]
	v_pk_fma_f32 v[10:11], v[10:11], v[66:67], v[42:43] op_sel:[0,0,0] op_sel_hi:[1,0,1]
	v_pk_fma_f32 v[38:39], v[10:11], v[52:53], v[38:39] op_sel:[0,1,0] op_sel_hi:[1,1,1]
	v_pk_mul_f32 v[44:45], v[72:73], v[54:55] op_sel_hi:[1,0]
	v_pk_fma_f32 v[12:13], v[12:13], v[66:67], v[44:45] op_sel:[0,1,0] op_sel_hi:[1,1,1]
	v_pk_fma_f32 v[38:39], v[12:13], v[54:55], v[38:39] op_sel:[0,1,0] op_sel_hi:[1,1,1]
	s_waitcnt lgkmcnt(1)
	v_pk_mul_f32 v[42:43], v[72:73], v[56:57] op_sel_hi:[1,0]
	v_pk_fma_f32 v[14:15], v[14:15], v[68:69], v[42:43] op_sel:[0,0,0] op_sel_hi:[1,0,1]
	v_pk_fma_f32 v[38:39], v[14:15], v[56:57], v[38:39] op_sel:[0,1,0] op_sel_hi:[1,1,1]
	v_pk_mul_f32 v[44:45], v[72:73], v[58:59] op_sel_hi:[1,0]
	v_pk_fma_f32 v[16:17], v[16:17], v[68:69], v[44:45] op_sel:[0,1,0] op_sel_hi:[1,1,1]
	v_pk_fma_f32 v[38:39], v[16:17], v[58:59], v[38:39] op_sel:[0,1,0] op_sel_hi:[1,1,1]
	s_waitcnt lgkmcnt(0)
	v_pk_mul_f32 v[42:43], v[72:73], v[60:61] op_sel_hi:[1,0]
	v_pk_fma_f32 v[18:19], v[18:19], v[70:71], v[42:43] op_sel:[0,0,0] op_sel_hi:[1,0,1]
	v_pk_fma_f32 v[38:39], v[18:19], v[60:61], v[38:39] op_sel:[0,1,0] op_sel_hi:[1,1,1]
	v_pk_mul_f32 v[44:45], v[72:73], v[62:63] op_sel_hi:[1,0]
	v_pk_fma_f32 v[20:21], v[20:21], v[70:71], v[44:45] op_sel:[0,1,0] op_sel_hi:[1,1,1]
	v_pk_fma_f32 v[38:39], v[20:21], v[62:63], v[38:39] op_sel:[0,1,0] op_sel_hi:[1,1,1]
	s_add_u32 s14, s14, 0x1000
	s_addc_u32 s15, s15, 0
	v_add_f32_dpp v38, v38, v38 row_ror:8 row_mask:0xf bank_mask:0x3 bound_ctrl:1
	v_add_f32_dpp v38, v39, v39 row_ror:8 row_mask:0xf bank_mask:0xc bound_ctrl:1
	ds_read_b64 v[104:105], v3 offset:22528
	ds_read_b128 v[80:83], v2 offset:7424
	v_add_f32_dpp v38, v38, v38 row_half_mirror row_mask:0xf bank_mask:0xf bound_ctrl:1
	ds_read_b128 v[96:99], v2 offset:20224
	ds_read_b128 v[84:87], v2 offset:7680
	v_add_f32_dpp v38, v38, v38 quad_perm:[1,0,3,2] row_mask:0xf bank_mask:0xf bound_ctrl:1
	ds_read_b128 v[88:91], v2 offset:7936
	ds_read_b128 v[100:103], v2 offset:20480
	v_add_f32_dpp v38, v38, v38 quad_perm:[2,3,0,1] row_mask:0xf bank_mask:0xf bound_ctrl:1
	ds_read_b128 v[92:95], v2 offset:8192
	s_nop 0
	v_mov_b32_dpp v39, v38 row_ror:8 row_mask:0xf bank_mask:0xf bound_ctrl:1
	v_pk_mul_f32 v[38:39], v[38:39], v[40:41] op_sel_hi:[1,0]
	v_cvt_pk_bf16_f32 v47, v38, v39
	s_mov_b64 exec, s[2:3]
	global_store_dword v46, v47, s[14:15] offset:-4096
	s_mov_b64 exec, -1
	s_waitcnt lgkmcnt(4)
	v_pk_mul_f32 v[42:43], v[104:105], v[80:81] op_sel_hi:[1,0]
	v_pk_fma_f32 v[6:7], v[6:7], v[96:97], v[42:43] op_sel:[0,0,0] op_sel_hi:[1,0,1]
	v_pk_mul_f32 v[38:39], v[6:7], v[80:81] op_sel:[0,1] op_sel_hi:[1,1]
	v_pk_mul_f32 v[44:45], v[104:105], v[82:83] op_sel_hi:[1,0]
	v_pk_fma_f32 v[8:9], v[8:9], v[96:97], v[44:45] op_sel:[0,1,0] op_sel_hi:[1,1,1]
	v_pk_fma_f32 v[38:39], v[8:9], v[82:83], v[38:39] op_sel:[0,1,0] op_sel_hi:[1,1,1]
	s_waitcnt lgkmcnt(3)
	v_pk_mul_f32 v[42:43], v[104:105], v[84:85] op_sel_hi:[1,0]
	v_pk_fma_f32 v[10:11], v[10:11], v[98:99], v[42:43] op_sel:[0,0,0] op_sel_hi:[1,0,1]
	v_pk_fma_f32 v[38:39], v[10:11], v[84:85], v[38:39] op_sel:[0,1,0] op_sel_hi:[1,1,1]
	v_pk_mul_f32 v[44:45], v[104:105], v[86:87] op_sel_hi:[1,0]
	v_pk_fma_f32 v[12:13], v[12:13], v[98:99], v[44:45] op_sel:[0,1,0] op_sel_hi:[1,1,1]
	v_pk_fma_f32 v[38:39], v[12:13], v[86:87], v[38:39] op_sel:[0,1,0] op_sel_hi:[1,1,1]
	s_waitcnt lgkmcnt(1)
	v_pk_mul_f32 v[42:43], v[104:105], v[88:89] op_sel_hi:[1,0]
	v_pk_fma_f32 v[14:15], v[14:15], v[100:101], v[42:43] op_sel:[0,0,0] op_sel_hi:[1,0,1]
	v_pk_fma_f32 v[38:39], v[14:15], v[88:89], v[38:39] op_sel:[0,1,0] op_sel_hi:[1,1,1]
	v_pk_mul_f32 v[44:45], v[104:105], v[90:91] op_sel_hi:[1,0]
	v_pk_fma_f32 v[16:17], v[16:17], v[100:101], v[44:45] op_sel:[0,1,0] op_sel_hi:[1,1,1]
	v_pk_fma_f32 v[38:39], v[16:17], v[90:91], v[38:39] op_sel:[0,1,0] op_sel_hi:[1,1,1]
	s_waitcnt lgkmcnt(0)
	v_pk_mul_f32 v[42:43], v[104:105], v[92:93] op_sel_hi:[1,0]
	v_pk_fma_f32 v[18:19], v[18:19], v[102:103], v[42:43] op_sel:[0,0,0] op_sel_hi:[1,0,1]
	v_pk_fma_f32 v[38:39], v[18:19], v[92:93], v[38:39] op_sel:[0,1,0] op_sel_hi:[1,1,1]
	v_pk_mul_f32 v[44:45], v[104:105], v[94:95] op_sel_hi:[1,0]
	v_pk_fma_f32 v[20:21], v[20:21], v[102:103], v[44:45] op_sel:[0,1,0] op_sel_hi:[1,1,1]
	v_pk_fma_f32 v[38:39], v[20:21], v[94:95], v[38:39] op_sel:[0,1,0] op_sel_hi:[1,1,1]
	s_add_u32 s14, s14, 0x1000
	s_addc_u32 s15, s15, 0
	v_add_f32_dpp v38, v38, v38 row_ror:8 row_mask:0xf bank_mask:0x3 bound_ctrl:1
	v_add_f32_dpp v38, v39, v39 row_ror:8 row_mask:0xf bank_mask:0xc bound_ctrl:1
	ds_read_b64 v[72:73], v3 offset:45312
	ds_read_b128 v[48:51], v2 offset:24832
	v_add_f32_dpp v38, v38, v38 row_half_mirror row_mask:0xf bank_mask:0xf bound_ctrl:1
	ds_read_b128 v[64:67], v2 offset:41216
	ds_read_b128 v[52:55], v2 offset:25088
	v_add_f32_dpp v38, v38, v38 quad_perm:[1,0,3,2] row_mask:0xf bank_mask:0xf bound_ctrl:1
	ds_read_b128 v[56:59], v2 offset:25344
	ds_read_b128 v[68:71], v2 offset:41472
	v_add_f32_dpp v38, v38, v38 quad_perm:[2,3,0,1] row_mask:0xf bank_mask:0xf bound_ctrl:1
	ds_read_b128 v[60:63], v2 offset:25600
	s_nop 0
	v_mov_b32_dpp v39, v38 row_ror:8 row_mask:0xf bank_mask:0xf bound_ctrl:1
	v_pk_mul_f32 v[38:39], v[38:39], v[40:41] op_sel_hi:[1,0]
	v_cvt_pk_bf16_f32 v47, v38, v39
	s_mov_b64 exec, s[2:3]
	global_store_dword v46, v47, s[14:15] offset:-4096
	s_mov_b64 exec, -1
	s_waitcnt vmcnt(8)
	v_lshlrev_b32_e32 v144, 16, v110
	v_lshlrev_b32_e32 v145, 16, v111
	v_and_b32_e32 v146, s17, v110
	v_and_b32_e32 v147, s17, v111
	v_lshlrev_b32_e32 v148, 16, v112
	v_lshlrev_b32_e32 v149, 16, v113
	v_and_b32_e32 v150, s17, v112
	v_and_b32_e32 v151, s17, v113
	v_lshlrev_b32_e32 v152, 16, v114
	v_and_b32_e32 v153, s17, v114
	ds_write_b128 v29, v[144:147] offset:49408
	ds_write_b128 v29, v[148:151] offset:57600
	ds_write_b64 v30, v[116:117] offset:49408
	ds_write_b64 v31, v[152:153] offset:49408
	s_add_i32 s16, s16, 8
	s_waitcnt lgkmcnt(0)
	s_barrier
	s_cmpk_lt_u32 s16, 0x800
	s_cbranch_scc0 .Lgla2_done
	global_load_dword v110, v32, s[10:11]
	global_load_dword v111, v32, s[10:11] offset:-1024
	global_load_dword v112, v33, s[10:11]
	global_load_dword v113, v33, s[10:11] offset:-1024
	global_load_dword v114, v34, s[10:11]
	global_load_dword v116, v35, s[12:13]
	global_load_dword v117, v35, s[12:13] offset:4
	s_add_u32 s10, s10, 0x18000
	s_addc_u32 s11, s11, 0
	s_add_u32 s12, s12, 0x4000
	s_addc_u32 s13, s13, 0
	s_waitcnt lgkmcnt(4)
	v_pk_mul_f32 v[42:43], v[72:73], v[48:49] op_sel_hi:[1,0]
	v_pk_fma_f32 v[6:7], v[6:7], v[64:65], v[42:43] op_sel:[0,0,0] op_sel_hi:[1,0,1]
	v_pk_mul_f32 v[38:39], v[6:7], v[48:49] op_sel:[0,1] op_sel_hi:[1,1]
	v_pk_mul_f32 v[44:45], v[72:73], v[50:51] op_sel_hi:[1,0]
	v_pk_fma_f32 v[8:9], v[8:9], v[64:65], v[44:45] op_sel:[0,1,0] op_sel_hi:[1,1,1]
	v_pk_fma_f32 v[38:39], v[8:9], v[50:51], v[38:39] op_sel:[0,1,0] op_sel_hi:[1,1,1]
	s_waitcnt lgkmcnt(3)
	v_pk_mul_f32 v[42:43], v[72:73], v[52:53] op_sel_hi:[1,0]
	v_pk_fma_f32 v[10:11], v[10:11], v[66:67], v[42:43] op_sel:[0,0,0] op_sel_hi:[1,0,1]
	v_pk_fma_f32 v[38:39], v[10:11], v[52:53], v[38:39] op_sel:[0,1,0] op_sel_hi:[1,1,1]
	v_pk_mul_f32 v[44:45], v[72:73], v[54:55] op_sel_hi:[1,0]
	v_pk_fma_f32 v[12:13], v[12:13], v[66:67], v[44:45] op_sel:[0,1,0] op_sel_hi:[1,1,1]
	v_pk_fma_f32 v[38:39], v[12:13], v[54:55], v[38:39] op_sel:[0,1,0] op_sel_hi:[1,1,1]
	s_waitcnt lgkmcnt(1)
	v_pk_mul_f32 v[42:43], v[72:73], v[56:57] op_sel_hi:[1,0]
	v_pk_fma_f32 v[14:15], v[14:15], v[68:69], v[42:43] op_sel:[0,0,0] op_sel_hi:[1,0,1]
	v_pk_fma_f32 v[38:39], v[14:15], v[56:57], v[38:39] op_sel:[0,1,0] op_sel_hi:[1,1,1]
	v_pk_mul_f32 v[44:45], v[72:73], v[58:59] op_sel_hi:[1,0]
	v_pk_fma_f32 v[16:17], v[16:17], v[68:69], v[44:45] op_sel:[0,1,0] op_sel_hi:[1,1,1]
	v_pk_fma_f32 v[38:39], v[16:17], v[58:59], v[38:39] op_sel:[0,1,0] op_sel_hi:[1,1,1]
	s_waitcnt lgkmcnt(0)
	v_pk_mul_f32 v[42:43], v[72:73], v[60:61] op_sel_hi:[1,0]
	v_pk_fma_f32 v[18:19], v[18:19], v[70:71], v[42:43] op_sel:[0,0,0] op_sel_hi:[1,0,1]
	v_pk_fma_f32 v[38:39], v[18:19], v[60:61], v[38:39] op_sel:[0,1,0] op_sel_hi:[1,1,1]
	v_pk_mul_f32 v[44:45], v[72:73], v[62:63] op_sel_hi:[1,0]
	v_pk_fma_f32 v[20:21], v[20:21], v[70:71], v[44:45] op_sel:[0,1,0] op_sel_hi:[1,1,1]
	v_pk_fma_f32 v[38:39], v[20:21], v[62:63], v[38:39] op_sel:[0,1,0] op_sel_hi:[1,1,1]
	s_add_u32 s14, s14, 0x1000
	s_addc_u32 s15, s15, 0
	v_add_f32_dpp v38, v38, v38 row_ror:8 row_mask:0xf bank_mask:0x3 bound_ctrl:1
	v_add_f32_dpp v38, v39, v39 row_ror:8 row_mask:0xf bank_mask:0xc bound_ctrl:1
	ds_read_b64 v[104:105], v3 offset:45568
	ds_read_b128 v[80:83], v2 offset:25856
	v_add_f32_dpp v38, v38, v38 row_half_mirror row_mask:0xf bank_mask:0xf bound_ctrl:1
	ds_read_b128 v[96:99], v2 offset:41728
	ds_read_b128 v[84:87], v2 offset:26112
	v_add_f32_dpp v38, v38, v38 quad_perm:[1,0,3,2] row_mask:0xf bank_mask:0xf bound_ctrl:1
	ds_read_b128 v[88:91], v2 offset:26368
	ds_read_b128 v[100:103], v2 offset:41984
	v_add_f32_dpp v38, v38, v38 quad_perm:[2,3,0,1] row_mask:0xf bank_mask:0xf bound_ctrl:1
	ds_read_b128 v[92:95], v2 offset:26624
	s_nop 0
	v_mov_b32_dpp v39, v38 row_ror:8 row_mask:0xf bank_mask:0xf bound_ctrl:1
	v_pk_mul_f32 v[38:39], v[38:39], v[40:41] op_sel_hi:[1,0]
	v_cvt_pk_bf16_f32 v47, v38, v39
	s_mov_b64 exec, s[2:3]
	global_store_dword v46, v47, s[14:15] offset:-4096
	s_mov_b64 exec, -1
	s_waitcnt lgkmcnt(4)
	v_pk_mul_f32 v[42:43], v[104:105], v[80:81] op_sel_hi:[1,0]
	v_pk_fma_f32 v[6:7], v[6:7], v[96:97], v[42:43] op_sel:[0,0,0] op_sel_hi:[1,0,1]
	v_pk_mul_f32 v[38:39], v[6:7], v[80:81] op_sel:[0,1] op_sel_hi:[1,1]
	v_pk_mul_f32 v[44:45], v[104:105], v[82:83] op_sel_hi:[1,0]
	v_pk_fma_f32 v[8:9], v[8:9], v[96:97], v[44:45] op_sel:[0,1,0] op_sel_hi:[1,1,1]
	v_pk_fma_f32 v[38:39], v[8:9], v[82:83], v[38:39] op_sel:[0,1,0] op_sel_hi:[1,1,1]
	s_waitcnt lgkmcnt(3)
	v_pk_mul_f32 v[42:43], v[104:105], v[84:85] op_sel_hi:[1,0]
	v_pk_fma_f32 v[10:11], v[10:11], v[98:99], v[42:43] op_sel:[0,0,0] op_sel_hi:[1,0,1]
	v_pk_fma_f32 v[38:39], v[10:11], v[84:85], v[38:39] op_sel:[0,1,0] op_sel_hi:[1,1,1]
	v_pk_mul_f32 v[44:45], v[104:105], v[86:87] op_sel_hi:[1,0]
	v_pk_fma_f32 v[12:13], v[12:13], v[98:99], v[44:45] op_sel:[0,1,0] op_sel_hi:[1,1,1]
	v_pk_fma_f32 v[38:39], v[12:13], v[86:87], v[38:39] op_sel:[0,1,0] op_sel_hi:[1,1,1]
	s_waitcnt lgkmcnt(1)
	v_pk_mul_f32 v[42:43], v[104:105], v[88:89] op_sel_hi:[1,0]
	v_pk_fma_f32 v[14:15], v[14:15], v[100:101], v[42:43] op_sel:[0,0,0] op_sel_hi:[1,0,1]
	v_pk_fma_f32 v[38:39], v[14:15], v[88:89], v[38:39] op_sel:[0,1,0] op_sel_hi:[1,1,1]
	v_pk_mul_f32 v[44:45], v[104:105], v[90:91] op_sel_hi:[1,0]
	v_pk_fma_f32 v[16:17], v[16:17], v[100:101], v[44:45] op_sel:[0,1,0] op_sel_hi:[1,1,1]
	v_pk_fma_f32 v[38:39], v[16:17], v[90:91], v[38:39] op_sel:[0,1,0] op_sel_hi:[1,1,1]
	s_waitcnt lgkmcnt(0)
	v_pk_mul_f32 v[42:43], v[104:105], v[92:93] op_sel_hi:[1,0]
	v_pk_fma_f32 v[18:19], v[18:19], v[102:103], v[42:43] op_sel:[0,0,0] op_sel_hi:[1,0,1]
	v_pk_fma_f32 v[38:39], v[18:19], v[92:93], v[38:39] op_sel:[0,1,0] op_sel_hi:[1,1,1]
	v_pk_mul_f32 v[44:45], v[104:105], v[94:95] op_sel_hi:[1,0]
	v_pk_fma_f32 v[20:21], v[20:21], v[102:103], v[44:45] op_sel:[0,1,0] op_sel_hi:[1,1,1]
	v_pk_fma_f32 v[38:39], v[20:21], v[94:95], v[38:39] op_sel:[0,1,0] op_sel_hi:[1,1,1]
	s_add_u32 s14, s14, 0x1000
	s_addc_u32 s15, s15, 0
	v_add_f32_dpp v38, v38, v38 row_ror:8 row_mask:0xf bank_mask:0x3 bound_ctrl:1
	v_add_f32_dpp v38, v39, v39 row_ror:8 row_mask:0xf bank_mask:0xc bound_ctrl:1
	ds_read_b64 v[72:73], v3 offset:45824
	ds_read_b128 v[48:51], v2 offset:26880
	v_add_f32_dpp v38, v38, v38 row_half_mirror row_mask:0xf bank_mask:0xf bound_ctrl:1
	ds_read_b128 v[64:67], v2 offset:42240
	ds_read_b128 v[52:55], v2 offset:27136
	v_add_f32_dpp v38, v38, v38 quad_perm:[1,0,3,2] row_mask:0xf bank_mask:0xf bound_ctrl:1
	ds_read_b128 v[56:59], v2 offset:27392
	ds_read_b128 v[68:71], v2 offset:42496
	v_add_f32_dpp v38, v38, v38 quad_perm:[2,3,0,1] row_mask:0xf bank_mask:0xf bound_ctrl:1
	ds_read_b128 v[60:63], v2 offset:27648
	s_nop 0
	v_mov_b32_dpp v39, v38 row_ror:8 row_mask:0xf bank_mask:0xf bound_ctrl:1
	v_pk_mul_f32 v[38:39], v[38:39], v[40:41] op_sel_hi:[1,0]
	v_cvt_pk_bf16_f32 v47, v38, v39
	s_mov_b64 exec, s[2:3]
	global_store_dword v46, v47, s[14:15] offset:-4096
	s_mov_b64 exec, -1
	s_waitcnt lgkmcnt(4)
	v_pk_mul_f32 v[42:43], v[72:73], v[48:49] op_sel_hi:[1,0]
	v_pk_fma_f32 v[6:7], v[6:7], v[64:65], v[42:43] op_sel:[0,0,0] op_sel_hi:[1,0,1]
	v_pk_mul_f32 v[38:39], v[6:7], v[48:49] op_sel:[0,1] op_sel_hi:[1,1]
	v_pk_mul_f32 v[44:45], v[72:73], v[50:51] op_sel_hi:[1,0]
	v_pk_fma_f32 v[8:9], v[8:9], v[64:65], v[44:45] op_sel:[0,1,0] op_sel_hi:[1,1,1]
	v_pk_fma_f32 v[38:39], v[8:9], v[50:51], v[38:39] op_sel:[0,1,0] op_sel_hi:[1,1,1]
	s_waitcnt lgkmcnt(3)
	v_pk_mul_f32 v[42:43], v[72:73], v[52:53] op_sel_hi:[1,0]
	v_pk_fma_f32 v[10:11], v[10:11], v[66:67], v[42:43] op_sel:[0,0,0] op_sel_hi:[1,0,1]
	v_pk_fma_f32 v[38:39], v[10:11], v[52:53], v[38:39] op_sel:[0,1,0] op_sel_hi:[1,1,1]
	v_pk_mul_f32 v[44:45], v[72:73], v[54:55] op_sel_hi:[1,0]
	v_pk_fma_f32 v[12:13], v[12:13], v[66:67], v[44:45] op_sel:[0,1,0] op_sel_hi:[1,1,1]
	v_pk_fma_f32 v[38:39], v[12:13], v[54:55], v[38:39] op_sel:[0,1,0] op_sel_hi:[1,1,1]
	s_waitcnt lgkmcnt(1)
	v_pk_mul_f32 v[42:43], v[72:73], v[56:57] op_sel_hi:[1,0]
	v_pk_fma_f32 v[14:15], v[14:15], v[68:69], v[42:43] op_sel:[0,0,0] op_sel_hi:[1,0,1]
	v_pk_fma_f32 v[38:39], v[14:15], v[56:57], v[38:39] op_sel:[0,1,0] op_sel_hi:[1,1,1]
	v_pk_mul_f32 v[44:45], v[72:73], v[58:59] op_sel_hi:[1,0]
	v_pk_fma_f32 v[16:17], v[16:17], v[68:69], v[44:45] op_sel:[0,1,0] op_sel_hi:[1,1,1]
	v_pk_fma_f32 v[38:39], v[16:17], v[58:59], v[38:39] op_sel:[0,1,0] op_sel_hi:[1,1,1]
	s_waitcnt lgkmcnt(0)
	v_pk_mul_f32 v[42:43], v[72:73], v[60:61] op_sel_hi:[1,0]
	v_pk_fma_f32 v[18:19], v[18:19], v[70:71], v[42:43] op_sel:[0,0,0] op_sel_hi:[1,0,1]
	v_pk_fma_f32 v[38:39], v[18:19], v[60:61], v[38:39] op_sel:[0,1,0] op_sel_hi:[1,1,1]
	v_pk_mul_f32 v[44:45], v[72:73], v[62:63] op_sel_hi:[1,0]
	v_pk_fma_f32 v[20:21], v[20:21], v[70:71], v[44:45] op_sel:[0,1,0] op_sel_hi:[1,1,1]
	v_pk_fma_f32 v[38:39], v[20:21], v[62:63], v[38:39] op_sel:[0,1,0] op_sel_hi:[1,1,1]
	s_add_u32 s14, s14, 0x1000
	s_addc_u32 s15, s15, 0
	v_add_f32_dpp v38, v38, v38 row_ror:8 row_mask:0xf bank_mask:0x3 bound_ctrl:1
	v_add_f32_dpp v38, v39, v39 row_ror:8 row_mask:0xf bank_mask:0xc bound_ctrl:1
	ds_read_b64 v[104:105], v3 offset:46080
	ds_read_b128 v[80:83], v2 offset:27904
	v_add_f32_dpp v38, v38, v38 row_half_mirror row_mask:0xf bank_mask:0xf bound_ctrl:1
	ds_read_b128 v[96:99], v2 offset:42752
	ds_read_b128 v[84:87], v2 offset:28160
	v_add_f32_dpp v38, v38, v38 quad_perm:[1,0,3,2] row_mask:0xf bank_mask:0xf bound_ctrl:1
	ds_read_b128 v[88:91], v2 offset:28416
	ds_read_b128 v[100:103], v2 offset:43008
	v_add_f32_dpp v38, v38, v38 quad_perm:[2,3,0,1] row_mask:0xf bank_mask:0xf bound_ctrl:1
	ds_read_b128 v[92:95], v2 offset:28672
	s_nop 0
	v_mov_b32_dpp v39, v38 row_ror:8 row_mask:0xf bank_mask:0xf bound_ctrl:1
	v_pk_mul_f32 v[38:39], v[38:39], v[40:41] op_sel_hi:[1,0]
	v_cvt_pk_bf16_f32 v47, v38, v39
	s_mov_b64 exec, s[2:3]
	global_store_dword v46, v47, s[14:15] offset:-4096
	s_mov_b64 exec, -1
	s_waitcnt lgkmcnt(4)
	v_pk_mul_f32 v[42:43], v[104:105], v[80:81] op_sel_hi:[1,0]
	v_pk_fma_f32 v[6:7], v[6:7], v[96:97], v[42:43] op_sel:[0,0,0] op_sel_hi:[1,0,1]
	v_pk_mul_f32 v[38:39], v[6:7], v[80:81] op_sel:[0,1] op_sel_hi:[1,1]
	v_pk_mul_f32 v[44:45], v[104:105], v[82:83] op_sel_hi:[1,0]
	v_pk_fma_f32 v[8:9], v[8:9], v[96:97], v[44:45] op_sel:[0,1,0] op_sel_hi:[1,1,1]
	v_pk_fma_f32 v[38:39], v[8:9], v[82:83], v[38:39] op_sel:[0,1,0] op_sel_hi:[1,1,1]
	s_waitcnt lgkmcnt(3)
	v_pk_mul_f32 v[42:43], v[104:105], v[84:85] op_sel_hi:[1,0]
	v_pk_fma_f32 v[10:11], v[10:11], v[98:99], v[42:43] op_sel:[0,0,0] op_sel_hi:[1,0,1]
	v_pk_fma_f32 v[38:39], v[10:11], v[84:85], v[38:39] op_sel:[0,1,0] op_sel_hi:[1,1,1]
	v_pk_mul_f32 v[44:45], v[104:105], v[86:87] op_sel_hi:[1,0]
	v_pk_fma_f32 v[12:13], v[12:13], v[98:99], v[44:45] op_sel:[0,1,0] op_sel_hi:[1,1,1]
	v_pk_fma_f32 v[38:39], v[12:13], v[86:87], v[38:39] op_sel:[0,1,0] op_sel_hi:[1,1,1]
	s_waitcnt lgkmcnt(1)
	v_pk_mul_f32 v[42:43], v[104:105], v[88:89] op_sel_hi:[1,0]
	v_pk_fma_f32 v[14:15], v[14:15], v[100:101], v[42:43] op_sel:[0,0,0] op_sel_hi:[1,0,1]
	v_pk_fma_f32 v[38:39], v[14:15], v[88:89], v[38:39] op_sel:[0,1,0] op_sel_hi:[1,1,1]
	v_pk_mul_f32 v[44:45], v[104:105], v[90:91] op_sel_hi:[1,0]
	v_pk_fma_f32 v[16:17], v[16:17], v[100:101], v[44:45] op_sel:[0,1,0] op_sel_hi:[1,1,1]
	v_pk_fma_f32 v[38:39], v[16:17], v[90:91], v[38:39] op_sel:[0,1,0] op_sel_hi:[1,1,1]
	s_waitcnt lgkmcnt(0)
	v_pk_mul_f32 v[42:43], v[104:105], v[92:93] op_sel_hi:[1,0]
	v_pk_fma_f32 v[18:19], v[18:19], v[102:103], v[42:43] op_sel:[0,0,0] op_sel_hi:[1,0,1]
	v_pk_fma_f32 v[38:39], v[18:19], v[92:93], v[38:39] op_sel:[0,1,0] op_sel_hi:[1,1,1]
	v_pk_mul_f32 v[44:45], v[104:105], v[94:95] op_sel_hi:[1,0]
	v_pk_fma_f32 v[20:21], v[20:21], v[102:103], v[44:45] op_sel:[0,1,0] op_sel_hi:[1,1,1]
	v_pk_fma_f32 v[38:39], v[20:21], v[94:95], v[38:39] op_sel:[0,1,0] op_sel_hi:[1,1,1]
	s_add_u32 s14, s14, 0x1000
	s_addc_u32 s15, s15, 0
	v_add_f32_dpp v38, v38, v38 row_ror:8 row_mask:0xf bank_mask:0x3 bound_ctrl:1
	v_add_f32_dpp v38, v39, v39 row_ror:8 row_mask:0xf bank_mask:0xc bound_ctrl:1
	ds_read_b64 v[72:73], v3 offset:46336
	ds_read_b128 v[48:51], v2 offset:28928
	v_add_f32_dpp v38, v38, v38 row_half_mirror row_mask:0xf bank_mask:0xf bound_ctrl:1
	ds_read_b128 v[64:67], v2 offset:43264
	ds_read_b128 v[52:55], v2 offset:29184
	v_add_f32_dpp v38, v38, v38 quad_perm:[1,0,3,2] row_mask:0xf bank_mask:0xf bound_ctrl:1
	ds_read_b128 v[56:59], v2 offset:29440
	ds_read_b128 v[68:71], v2 offset:43520
	v_add_f32_dpp v38, v38, v38 quad_perm:[2,3,0,1] row_mask:0xf bank_mask:0xf bound_ctrl:1
	ds_read_b128 v[60:63], v2 offset:29696
	s_nop 0
	v_mov_b32_dpp v39, v38 row_ror:8 row_mask:0xf bank_mask:0xf bound_ctrl:1
	v_pk_mul_f32 v[38:39], v[38:39], v[40:41] op_sel_hi:[1,0]
	v_cvt_pk_bf16_f32 v47, v38, v39
	s_mov_b64 exec, s[2:3]
	global_store_dword v46, v47, s[14:15] offset:-4096
	s_mov_b64 exec, -1
	s_waitcnt lgkmcnt(4)
	v_pk_mul_f32 v[42:43], v[72:73], v[48:49] op_sel_hi:[1,0]
	v_pk_fma_f32 v[6:7], v[6:7], v[64:65], v[42:43] op_sel:[0,0,0] op_sel_hi:[1,0,1]
	v_pk_mul_f32 v[38:39], v[6:7], v[48:49] op_sel:[0,1] op_sel_hi:[1,1]
	v_pk_mul_f32 v[44:45], v[72:73], v[50:51] op_sel_hi:[1,0]
	v_pk_fma_f32 v[8:9], v[8:9], v[64:65], v[44:45] op_sel:[0,1,0] op_sel_hi:[1,1,1]
	v_pk_fma_f32 v[38:39], v[8:9], v[50:51], v[38:39] op_sel:[0,1,0] op_sel_hi:[1,1,1]
	s_waitcnt lgkmcnt(3)
	v_pk_mul_f32 v[42:43], v[72:73], v[52:53] op_sel_hi:[1,0]
	v_pk_fma_f32 v[10:11], v[10:11], v[66:67], v[42:43] op_sel:[0,0,0] op_sel_hi:[1,0,1]
	v_pk_fma_f32 v[38:39], v[10:11], v[52:53], v[38:39] op_sel:[0,1,0] op_sel_hi:[1,1,1]
	v_pk_mul_f32 v[44:45], v[72:73], v[54:55] op_sel_hi:[1,0]
	v_pk_fma_f32 v[12:13], v[12:13], v[66:67], v[44:45] op_sel:[0,1,0] op_sel_hi:[1,1,1]
	v_pk_fma_f32 v[38:39], v[12:13], v[54:55], v[38:39] op_sel:[0,1,0] op_sel_hi:[1,1,1]
	s_waitcnt lgkmcnt(1)
	v_pk_mul_f32 v[42:43], v[72:73], v[56:57] op_sel_hi:[1,0]
	v_pk_fma_f32 v[14:15], v[14:15], v[68:69], v[42:43] op_sel:[0,0,0] op_sel_hi:[1,0,1]
	v_pk_fma_f32 v[38:39], v[14:15], v[56:57], v[38:39] op_sel:[0,1,0] op_sel_hi:[1,1,1]
	v_pk_mul_f32 v[44:45], v[72:73], v[58:59] op_sel_hi:[1,0]
	v_pk_fma_f32 v[16:17], v[16:17], v[68:69], v[44:45] op_sel:[0,1,0] op_sel_hi:[1,1,1]
	v_pk_fma_f32 v[38:39], v[16:17], v[58:59], v[38:39] op_sel:[0,1,0] op_sel_hi:[1,1,1]
	s_waitcnt lgkmcnt(0)
	v_pk_mul_f32 v[42:43], v[72:73], v[60:61] op_sel_hi:[1,0]
	v_pk_fma_f32 v[18:19], v[18:19], v[70:71], v[42:43] op_sel:[0,0,0] op_sel_hi:[1,0,1]
	v_pk_fma_f32 v[38:39], v[18:19], v[60:61], v[38:39] op_sel:[0,1,0] op_sel_hi:[1,1,1]
	v_pk_mul_f32 v[44:45], v[72:73], v[62:63] op_sel_hi:[1,0]
	v_pk_fma_f32 v[20:21], v[20:21], v[70:71], v[44:45] op_sel:[0,1,0] op_sel_hi:[1,1,1]
	v_pk_fma_f32 v[38:39], v[20:21], v[62:63], v[38:39] op_sel:[0,1,0] op_sel_hi:[1,1,1]
	s_add_u32 s14, s14, 0x1000
	s_addc_u32 s15, s15, 0
	v_add_f32_dpp v38, v38, v38 row_ror:8 row_mask:0xf bank_mask:0x3 bound_ctrl:1
	v_add_f32_dpp v38, v39, v39 row_ror:8 row_mask:0xf bank_mask:0xc bound_ctrl:1
	ds_read_b64 v[104:105], v3 offset:46592
	ds_read_b128 v[80:83], v2 offset:29952
	v_add_f32_dpp v38, v38, v38 row_half_mirror row_mask:0xf bank_mask:0xf bound_ctrl:1
	ds_read_b128 v[96:99], v2 offset:43776
	ds_read_b128 v[84:87], v2 offset:30208
	v_add_f32_dpp v38, v38, v38 quad_perm:[1,0,3,2] row_mask:0xf bank_mask:0xf bound_ctrl:1
	ds_read_b128 v[88:91], v2 offset:30464
	ds_read_b128 v[100:103], v2 offset:44032
	v_add_f32_dpp v38, v38, v38 quad_perm:[2,3,0,1] row_mask:0xf bank_mask:0xf bound_ctrl:1
	ds_read_b128 v[92:95], v2 offset:30720
	s_nop 0
	v_mov_b32_dpp v39, v38 row_ror:8 row_mask:0xf bank_mask:0xf bound_ctrl:1
	v_pk_mul_f32 v[38:39], v[38:39], v[40:41] op_sel_hi:[1,0]
	v_cvt_pk_bf16_f32 v47, v38, v39
	s_mov_b64 exec, s[2:3]
	global_store_dword v46, v47, s[14:15] offset:-4096
	s_mov_b64 exec, -1
	s_waitcnt lgkmcnt(4)
	v_pk_mul_f32 v[42:43], v[104:105], v[80:81] op_sel_hi:[1,0]
	v_pk_fma_f32 v[6:7], v[6:7], v[96:97], v[42:43] op_sel:[0,0,0] op_sel_hi:[1,0,1]
	v_pk_mul_f32 v[38:39], v[6:7], v[80:81] op_sel:[0,1] op_sel_hi:[1,1]
	v_pk_mul_f32 v[44:45], v[104:105], v[82:83] op_sel_hi:[1,0]
	v_pk_fma_f32 v[8:9], v[8:9], v[96:97], v[44:45] op_sel:[0,1,0] op_sel_hi:[1,1,1]
	v_pk_fma_f32 v[38:39], v[8:9], v[82:83], v[38:39] op_sel:[0,1,0] op_sel_hi:[1,1,1]
	s_waitcnt lgkmcnt(3)
	v_pk_mul_f32 v[42:43], v[104:105], v[84:85] op_sel_hi:[1,0]
	v_pk_fma_f32 v[10:11], v[10:11], v[98:99], v[42:43] op_sel:[0,0,0] op_sel_hi:[1,0,1]
	v_pk_fma_f32 v[38:39], v[10:11], v[84:85], v[38:39] op_sel:[0,1,0] op_sel_hi:[1,1,1]
	v_pk_mul_f32 v[44:45], v[104:105], v[86:87] op_sel_hi:[1,0]
	v_pk_fma_f32 v[12:13], v[12:13], v[98:99], v[44:45] op_sel:[0,1,0] op_sel_hi:[1,1,1]
	v_pk_fma_f32 v[38:39], v[12:13], v[86:87], v[38:39] op_sel:[0,1,0] op_sel_hi:[1,1,1]
	s_waitcnt lgkmcnt(1)
	v_pk_mul_f32 v[42:43], v[104:105], v[88:89] op_sel_hi:[1,0]
	v_pk_fma_f32 v[14:15], v[14:15], v[100:101], v[42:43] op_sel:[0,0,0] op_sel_hi:[1,0,1]
	v_pk_fma_f32 v[38:39], v[14:15], v[88:89], v[38:39] op_sel:[0,1,0] op_sel_hi:[1,1,1]
	v_pk_mul_f32 v[44:45], v[104:105], v[90:91] op_sel_hi:[1,0]
	v_pk_fma_f32 v[16:17], v[16:17], v[100:101], v[44:45] op_sel:[0,1,0] op_sel_hi:[1,1,1]
	v_pk_fma_f32 v[38:39], v[16:17], v[90:91], v[38:39] op_sel:[0,1,0] op_sel_hi:[1,1,1]
	s_waitcnt lgkmcnt(0)
	v_pk_mul_f32 v[42:43], v[104:105], v[92:93] op_sel_hi:[1,0]
	v_pk_fma_f32 v[18:19], v[18:19], v[102:103], v[42:43] op_sel:[0,0,0] op_sel_hi:[1,0,1]
	v_pk_fma_f32 v[38:39], v[18:19], v[92:93], v[38:39] op_sel:[0,1,0] op_sel_hi:[1,1,1]
	v_pk_mul_f32 v[44:45], v[104:105], v[94:95] op_sel_hi:[1,0]
	v_pk_fma_f32 v[20:21], v[20:21], v[102:103], v[44:45] op_sel:[0,1,0] op_sel_hi:[1,1,1]
	v_pk_fma_f32 v[38:39], v[20:21], v[94:95], v[38:39] op_sel:[0,1,0] op_sel_hi:[1,1,1]
	s_add_u32 s14, s14, 0x1000
	s_addc_u32 s15, s15, 0
	v_add_f32_dpp v38, v38, v38 row_ror:8 row_mask:0xf bank_mask:0x3 bound_ctrl:1
	v_add_f32_dpp v38, v39, v39 row_ror:8 row_mask:0xf bank_mask:0xc bound_ctrl:1
	ds_read_b64 v[72:73], v3 offset:46848
	ds_read_b128 v[48:51], v2 offset:30976
	v_add_f32_dpp v38, v38, v38 row_half_mirror row_mask:0xf bank_mask:0xf bound_ctrl:1
	ds_read_b128 v[64:67], v2 offset:44288
	ds_read_b128 v[52:55], v2 offset:31232
	v_add_f32_dpp v38, v38, v38 quad_perm:[1,0,3,2] row_mask:0xf bank_mask:0xf bound_ctrl:1
	ds_read_b128 v[56:59], v2 offset:31488
	ds_read_b128 v[68:71], v2 offset:44544
	v_add_f32_dpp v38, v38, v38 quad_perm:[2,3,0,1] row_mask:0xf bank_mask:0xf bound_ctrl:1
	ds_read_b128 v[60:63], v2 offset:31744
	s_nop 0
	v_mov_b32_dpp v39, v38 row_ror:8 row_mask:0xf bank_mask:0xf bound_ctrl:1
	v_pk_mul_f32 v[38:39], v[38:39], v[40:41] op_sel_hi:[1,0]
	v_cvt_pk_bf16_f32 v47, v38, v39
	s_mov_b64 exec, s[2:3]
	global_store_dword v46, v47, s[14:15] offset:-4096
	s_mov_b64 exec, -1
	s_waitcnt lgkmcnt(4)
	v_pk_mul_f32 v[42:43], v[72:73], v[48:49] op_sel_hi:[1,0]
	v_pk_fma_f32 v[6:7], v[6:7], v[64:65], v[42:43] op_sel:[0,0,0] op_sel_hi:[1,0,1]
	v_pk_mul_f32 v[38:39], v[6:7], v[48:49] op_sel:[0,1] op_sel_hi:[1,1]
	v_pk_mul_f32 v[44:45], v[72:73], v[50:51] op_sel_hi:[1,0]
	v_pk_fma_f32 v[8:9], v[8:9], v[64:65], v[44:45] op_sel:[0,1,0] op_sel_hi:[1,1,1]
	v_pk_fma_f32 v[38:39], v[8:9], v[50:51], v[38:39] op_sel:[0,1,0] op_sel_hi:[1,1,1]
	s_waitcnt lgkmcnt(3)
	v_pk_mul_f32 v[42:43], v[72:73], v[52:53] op_sel_hi:[1,0]
	v_pk_fma_f32 v[10:11], v[10:11], v[66:67], v[42:43] op_sel:[0,0,0] op_sel_hi:[1,0,1]
	v_pk_fma_f32 v[38:39], v[10:11], v[52:53], v[38:39] op_sel:[0,1,0] op_sel_hi:[1,1,1]
	v_pk_mul_f32 v[44:45], v[72:73], v[54:55] op_sel_hi:[1,0]
	v_pk_fma_f32 v[12:13], v[12:13], v[66:67], v[44:45] op_sel:[0,1,0] op_sel_hi:[1,1,1]
	v_pk_fma_f32 v[38:39], v[12:13], v[54:55], v[38:39] op_sel:[0,1,0] op_sel_hi:[1,1,1]
	s_waitcnt lgkmcnt(1)
	v_pk_mul_f32 v[42:43], v[72:73], v[56:57] op_sel_hi:[1,0]
	v_pk_fma_f32 v[14:15], v[14:15], v[68:69], v[42:43] op_sel:[0,0,0] op_sel_hi:[1,0,1]
	v_pk_fma_f32 v[38:39], v[14:15], v[56:57], v[38:39] op_sel:[0,1,0] op_sel_hi:[1,1,1]
	v_pk_mul_f32 v[44:45], v[72:73], v[58:59] op_sel_hi:[1,0]
	v_pk_fma_f32 v[16:17], v[16:17], v[68:69], v[44:45] op_sel:[0,1,0] op_sel_hi:[1,1,1]
	v_pk_fma_f32 v[38:39], v[16:17], v[58:59], v[38:39] op_sel:[0,1,0] op_sel_hi:[1,1,1]
	s_waitcnt lgkmcnt(0)
	v_pk_mul_f32 v[42:43], v[72:73], v[60:61] op_sel_hi:[1,0]
	v_pk_fma_f32 v[18:19], v[18:19], v[70:71], v[42:43] op_sel:[0,0,0] op_sel_hi:[1,0,1]
	v_pk_fma_f32 v[38:39], v[18:19], v[60:61], v[38:39] op_sel:[0,1,0] op_sel_hi:[1,1,1]
	v_pk_mul_f32 v[44:45], v[72:73], v[62:63] op_sel_hi:[1,0]
	v_pk_fma_f32 v[20:21], v[20:21], v[70:71], v[44:45] op_sel:[0,1,0] op_sel_hi:[1,1,1]
	v_pk_fma_f32 v[38:39], v[20:21], v[62:63], v[38:39] op_sel:[0,1,0] op_sel_hi:[1,1,1]
	s_add_u32 s14, s14, 0x1000
	s_addc_u32 s15, s15, 0
	v_add_f32_dpp v38, v38, v38 row_ror:8 row_mask:0xf bank_mask:0x3 bound_ctrl:1
	v_add_f32_dpp v38, v39, v39 row_ror:8 row_mask:0xf bank_mask:0xc bound_ctrl:1
	ds_read_b64 v[104:105], v3 offset:47104
	ds_read_b128 v[80:83], v2 offset:32000
	v_add_f32_dpp v38, v38, v38 row_half_mirror row_mask:0xf bank_mask:0xf bound_ctrl:1
	ds_read_b128 v[96:99], v2 offset:44800
	ds_read_b128 v[84:87], v2 offset:32256
	v_add_f32_dpp v38, v38, v38 quad_perm:[1,0,3,2] row_mask:0xf bank_mask:0xf bound_ctrl:1
	ds_read_b128 v[88:91], v2 offset:32512
	ds_read_b128 v[100:103], v2 offset:45056
	v_add_f32_dpp v38, v38, v38 quad_perm:[2,3,0,1] row_mask:0xf bank_mask:0xf bound_ctrl:1
	ds_read_b128 v[92:95], v2 offset:32768
	s_nop 0
	v_mov_b32_dpp v39, v38 row_ror:8 row_mask:0xf bank_mask:0xf bound_ctrl:1
	v_pk_mul_f32 v[38:39], v[38:39], v[40:41] op_sel_hi:[1,0]
	v_cvt_pk_bf16_f32 v47, v38, v39
	s_mov_b64 exec, s[2:3]
	global_store_dword v46, v47, s[14:15] offset:-4096
	s_mov_b64 exec, -1
	s_waitcnt lgkmcnt(4)
	v_pk_mul_f32 v[42:43], v[104:105], v[80:81] op_sel_hi:[1,0]
	v_pk_fma_f32 v[6:7], v[6:7], v[96:97], v[42:43] op_sel:[0,0,0] op_sel_hi:[1,0,1]
	v_pk_mul_f32 v[38:39], v[6:7], v[80:81] op_sel:[0,1] op_sel_hi:[1,1]
	v_pk_mul_f32 v[44:45], v[104:105], v[82:83] op_sel_hi:[1,0]
	v_pk_fma_f32 v[8:9], v[8:9], v[96:97], v[44:45] op_sel:[0,1,0] op_sel_hi:[1,1,1]
	v_pk_fma_f32 v[38:39], v[8:9], v[82:83], v[38:39] op_sel:[0,1,0] op_sel_hi:[1,1,1]
	s_waitcnt lgkmcnt(3)
	v_pk_mul_f32 v[42:43], v[104:105], v[84:85] op_sel_hi:[1,0]
	v_pk_fma_f32 v[10:11], v[10:11], v[98:99], v[42:43] op_sel:[0,0,0] op_sel_hi:[1,0,1]
	v_pk_fma_f32 v[38:39], v[10:11], v[84:85], v[38:39] op_sel:[0,1,0] op_sel_hi:[1,1,1]
	v_pk_mul_f32 v[44:45], v[104:105], v[86:87] op_sel_hi:[1,0]
	v_pk_fma_f32 v[12:13], v[12:13], v[98:99], v[44:45] op_sel:[0,1,0] op_sel_hi:[1,1,1]
	v_pk_fma_f32 v[38:39], v[12:13], v[86:87], v[38:39] op_sel:[0,1,0] op_sel_hi:[1,1,1]
	s_waitcnt lgkmcnt(1)
	v_pk_mul_f32 v[42:43], v[104:105], v[88:89] op_sel_hi:[1,0]
	v_pk_fma_f32 v[14:15], v[14:15], v[100:101], v[42:43] op_sel:[0,0,0] op_sel_hi:[1,0,1]
	v_pk_fma_f32 v[38:39], v[14:15], v[88:89], v[38:39] op_sel:[0,1,0] op_sel_hi:[1,1,1]
	v_pk_mul_f32 v[44:45], v[104:105], v[90:91] op_sel_hi:[1,0]
	v_pk_fma_f32 v[16:17], v[16:17], v[100:101], v[44:45] op_sel:[0,1,0] op_sel_hi:[1,1,1]
	v_pk_fma_f32 v[38:39], v[16:17], v[90:91], v[38:39] op_sel:[0,1,0] op_sel_hi:[1,1,1]
	s_waitcnt lgkmcnt(0)
	v_pk_mul_f32 v[42:43], v[104:105], v[92:93] op_sel_hi:[1,0]
	v_pk_fma_f32 v[18:19], v[18:19], v[102:103], v[42:43] op_sel:[0,0,0] op_sel_hi:[1,0,1]
	v_pk_fma_f32 v[38:39], v[18:19], v[92:93], v[38:39] op_sel:[0,1,0] op_sel_hi:[1,1,1]
	v_pk_mul_f32 v[44:45], v[104:105], v[94:95] op_sel_hi:[1,0]
	v_pk_fma_f32 v[20:21], v[20:21], v[102:103], v[44:45] op_sel:[0,1,0] op_sel_hi:[1,1,1]
	v_pk_fma_f32 v[38:39], v[20:21], v[94:95], v[38:39] op_sel:[0,1,0] op_sel_hi:[1,1,1]
	s_add_u32 s14, s14, 0x1000
	s_addc_u32 s15, s15, 0
	v_add_f32_dpp v38, v38, v38 row_ror:8 row_mask:0xf bank_mask:0x3 bound_ctrl:1
	v_add_f32_dpp v38, v39, v39 row_ror:8 row_mask:0xf bank_mask:0xc bound_ctrl:1
	ds_read_b64 v[72:73], v23 offset:37120
	ds_read_b128 v[48:51], v2 offset:49408
	v_add_f32_dpp v38, v38, v38 row_half_mirror row_mask:0xf bank_mask:0xf bound_ctrl:1
	ds_read_b128 v[64:67], v22 offset:33024
	ds_read_b128 v[52:55], v2 offset:49664
	v_add_f32_dpp v38, v38, v38 quad_perm:[1,0,3,2] row_mask:0xf bank_mask:0xf bound_ctrl:1
	ds_read_b128 v[56:59], v2 offset:49920
	ds_read_b128 v[68:71], v22 offset:33280
	v_add_f32_dpp v38, v38, v38 quad_perm:[2,3,0,1] row_mask:0xf bank_mask:0xf bound_ctrl:1
	ds_read_b128 v[60:63], v2 offset:50176
	s_nop 0
	v_mov_b32_dpp v39, v38 row_ror:8 row_mask:0xf bank_mask:0xf bound_ctrl:1
	v_pk_mul_f32 v[38:39], v[38:39], v[40:41] op_sel_hi:[1,0]
	v_cvt_pk_bf16_f32 v47, v38, v39
	s_mov_b64 exec, s[2:3]
	global_store_dword v46, v47, s[14:15] offset:-4096
	s_mov_b64 exec, -1
	s_waitcnt vmcnt(8)
	v_lshlrev_b32_e32 v144, 16, v110
	v_lshlrev_b32_e32 v145, 16, v111
	v_and_b32_e32 v146, s17, v110
	v_and_b32_e32 v147, s17, v111
	v_lshlrev_b32_e32 v148, 16, v112
	v_lshlrev_b32_e32 v149, 16, v113
	v_and_b32_e32 v150, s17, v112
	v_and_b32_e32 v151, s17, v113
	v_lshlrev_b32_e32 v152, 16, v114
	v_and_b32_e32 v153, s17, v114
	ds_write_b128 v29, v[144:147] offset:256
	ds_write_b128 v29, v[148:151] offset:8448
	ds_write_b64 v30, v[116:117] offset:256
	ds_write_b64 v31, v[152:153] offset:256
	s_add_i32 s16, s16, 8
	s_waitcnt lgkmcnt(0)
	s_barrier
	s_cmpk_lt_u32 s16, 0x800
	s_cbranch_scc0 .Lgla2_done
	global_load_dword v110, v32, s[10:11]
	global_load_dword v111, v32, s[10:11] offset:-1024
	global_load_dword v112, v33, s[10:11]
	global_load_dword v113, v33, s[10:11] offset:-1024
	global_load_dword v114, v34, s[10:11]
	global_load_dword v116, v35, s[12:13]
	global_load_dword v117, v35, s[12:13] offset:4
	s_add_u32 s10, s10, 0x18000
	s_addc_u32 s11, s11, 0
	s_add_u32 s12, s12, 0x4000
	s_addc_u32 s13, s13, 0
	s_waitcnt lgkmcnt(4)
	v_pk_mul_f32 v[42:43], v[72:73], v[48:49] op_sel_hi:[1,0]
	v_pk_fma_f32 v[6:7], v[6:7], v[64:65], v[42:43] op_sel:[0,0,0] op_sel_hi:[1,0,1]
	v_pk_mul_f32 v[38:39], v[6:7], v[48:49] op_sel:[0,1] op_sel_hi:[1,1]
	v_pk_mul_f32 v[44:45], v[72:73], v[50:51] op_sel_hi:[1,0]
	v_pk_fma_f32 v[8:9], v[8:9], v[64:65], v[44:45] op_sel:[0,1,0] op_sel_hi:[1,1,1]
	v_pk_fma_f32 v[38:39], v[8:9], v[50:51], v[38:39] op_sel:[0,1,0] op_sel_hi:[1,1,1]
	s_waitcnt lgkmcnt(3)
	v_pk_mul_f32 v[42:43], v[72:73], v[52:53] op_sel_hi:[1,0]
	v_pk_fma_f32 v[10:11], v[10:11], v[66:67], v[42:43] op_sel:[0,0,0] op_sel_hi:[1,0,1]
	v_pk_fma_f32 v[38:39], v[10:11], v[52:53], v[38:39] op_sel:[0,1,0] op_sel_hi:[1,1,1]
	v_pk_mul_f32 v[44:45], v[72:73], v[54:55] op_sel_hi:[1,0]
	v_pk_fma_f32 v[12:13], v[12:13], v[66:67], v[44:45] op_sel:[0,1,0] op_sel_hi:[1,1,1]
	v_pk_fma_f32 v[38:39], v[12:13], v[54:55], v[38:39] op_sel:[0,1,0] op_sel_hi:[1,1,1]
	s_waitcnt lgkmcnt(1)
	v_pk_mul_f32 v[42:43], v[72:73], v[56:57] op_sel_hi:[1,0]
	v_pk_fma_f32 v[14:15], v[14:15], v[68:69], v[42:43] op_sel:[0,0,0] op_sel_hi:[1,0,1]
	v_pk_fma_f32 v[38:39], v[14:15], v[56:57], v[38:39] op_sel:[0,1,0] op_sel_hi:[1,1,1]
	v_pk_mul_f32 v[44:45], v[72:73], v[58:59] op_sel_hi:[1,0]
	v_pk_fma_f32 v[16:17], v[16:17], v[68:69], v[44:45] op_sel:[0,1,0] op_sel_hi:[1,1,1]
	v_pk_fma_f32 v[38:39], v[16:17], v[58:59], v[38:39] op_sel:[0,1,0] op_sel_hi:[1,1,1]
	s_waitcnt lgkmcnt(0)
	v_pk_mul_f32 v[42:43], v[72:73], v[60:61] op_sel_hi:[1,0]
	v_pk_fma_f32 v[18:19], v[18:19], v[70:71], v[42:43] op_sel:[0,0,0] op_sel_hi:[1,0,1]
	v_pk_fma_f32 v[38:39], v[18:19], v[60:61], v[38:39] op_sel:[0,1,0] op_sel_hi:[1,1,1]
	v_pk_mul_f32 v[44:45], v[72:73], v[62:63] op_sel_hi:[1,0]
	v_pk_fma_f32 v[20:21], v[20:21], v[70:71], v[44:45] op_sel:[0,1,0] op_sel_hi:[1,1,1]
	v_pk_fma_f32 v[38:39], v[20:21], v[62:63], v[38:39] op_sel:[0,1,0] op_sel_hi:[1,1,1]
	s_add_u32 s14, s14, 0x1000
	s_addc_u32 s15, s15, 0
	v_add_f32_dpp v38, v38, v38 row_ror:8 row_mask:0xf bank_mask:0x3 bound_ctrl:1
	v_add_f32_dpp v38, v39, v39 row_ror:8 row_mask:0xf bank_mask:0xc bound_ctrl:1
	ds_read_b64 v[104:105], v23 offset:37376
	ds_read_b128 v[80:83], v2 offset:50432
	v_add_f32_dpp v38, v38, v38 row_half_mirror row_mask:0xf bank_mask:0xf bound_ctrl:1
	ds_read_b128 v[96:99], v22 offset:33536
	ds_read_b128 v[84:87], v2 offset:50688
	v_add_f32_dpp v38, v38, v38 quad_perm:[1,0,3,2] row_mask:0xf bank_mask:0xf bound_ctrl:1
	ds_read_b128 v[88:91], v2 offset:50944
	ds_read_b128 v[100:103], v22 offset:33792
	v_add_f32_dpp v38, v38, v38 quad_perm:[2,3,0,1] row_mask:0xf bank_mask:0xf bound_ctrl:1
	ds_read_b128 v[92:95], v2 offset:51200
	s_nop 0
	v_mov_b32_dpp v39, v38 row_ror:8 row_mask:0xf bank_mask:0xf bound_ctrl:1
	v_pk_mul_f32 v[38:39], v[38:39], v[40:41] op_sel_hi:[1,0]
	v_cvt_pk_bf16_f32 v47, v38, v39
	s_mov_b64 exec, s[2:3]
	global_store_dword v46, v47, s[14:15] offset:-4096
	s_mov_b64 exec, -1
	s_waitcnt lgkmcnt(4)
	v_pk_mul_f32 v[42:43], v[104:105], v[80:81] op_sel_hi:[1,0]
	v_pk_fma_f32 v[6:7], v[6:7], v[96:97], v[42:43] op_sel:[0,0,0] op_sel_hi:[1,0,1]
	v_pk_mul_f32 v[38:39], v[6:7], v[80:81] op_sel:[0,1] op_sel_hi:[1,1]
	v_pk_mul_f32 v[44:45], v[104:105], v[82:83] op_sel_hi:[1,0]
	v_pk_fma_f32 v[8:9], v[8:9], v[96:97], v[44:45] op_sel:[0,1,0] op_sel_hi:[1,1,1]
	v_pk_fma_f32 v[38:39], v[8:9], v[82:83], v[38:39] op_sel:[0,1,0] op_sel_hi:[1,1,1]
	s_waitcnt lgkmcnt(3)
	v_pk_mul_f32 v[42:43], v[104:105], v[84:85] op_sel_hi:[1,0]
	v_pk_fma_f32 v[10:11], v[10:11], v[98:99], v[42:43] op_sel:[0,0,0] op_sel_hi:[1,0,1]
	v_pk_fma_f32 v[38:39], v[10:11], v[84:85], v[38:39] op_sel:[0,1,0] op_sel_hi:[1,1,1]
	v_pk_mul_f32 v[44:45], v[104:105], v[86:87] op_sel_hi:[1,0]
	v_pk_fma_f32 v[12:13], v[12:13], v[98:99], v[44:45] op_sel:[0,1,0] op_sel_hi:[1,1,1]
	v_pk_fma_f32 v[38:39], v[12:13], v[86:87], v[38:39] op_sel:[0,1,0] op_sel_hi:[1,1,1]
	s_waitcnt lgkmcnt(1)
	v_pk_mul_f32 v[42:43], v[104:105], v[88:89] op_sel_hi:[1,0]
	v_pk_fma_f32 v[14:15], v[14:15], v[100:101], v[42:43] op_sel:[0,0,0] op_sel_hi:[1,0,1]
	v_pk_fma_f32 v[38:39], v[14:15], v[88:89], v[38:39] op_sel:[0,1,0] op_sel_hi:[1,1,1]
	v_pk_mul_f32 v[44:45], v[104:105], v[90:91] op_sel_hi:[1,0]
	v_pk_fma_f32 v[16:17], v[16:17], v[100:101], v[44:45] op_sel:[0,1,0] op_sel_hi:[1,1,1]
	v_pk_fma_f32 v[38:39], v[16:17], v[90:91], v[38:39] op_sel:[0,1,0] op_sel_hi:[1,1,1]
	s_waitcnt lgkmcnt(0)
	v_pk_mul_f32 v[42:43], v[104:105], v[92:93] op_sel_hi:[1,0]
	v_pk_fma_f32 v[18:19], v[18:19], v[102:103], v[42:43] op_sel:[0,0,0] op_sel_hi:[1,0,1]
	v_pk_fma_f32 v[38:39], v[18:19], v[92:93], v[38:39] op_sel:[0,1,0] op_sel_hi:[1,1,1]
	v_pk_mul_f32 v[44:45], v[104:105], v[94:95] op_sel_hi:[1,0]
	v_pk_fma_f32 v[20:21], v[20:21], v[102:103], v[44:45] op_sel:[0,1,0] op_sel_hi:[1,1,1]
	v_pk_fma_f32 v[38:39], v[20:21], v[94:95], v[38:39] op_sel:[0,1,0] op_sel_hi:[1,1,1]
	s_add_u32 s14, s14, 0x1000
	s_addc_u32 s15, s15, 0
	v_add_f32_dpp v38, v38, v38 row_ror:8 row_mask:0xf bank_mask:0x3 bound_ctrl:1
	v_add_f32_dpp v38, v39, v39 row_ror:8 row_mask:0xf bank_mask:0xc bound_ctrl:1
	ds_read_b64 v[72:73], v23 offset:37632
	ds_read_b128 v[48:51], v2 offset:51456
	v_add_f32_dpp v38, v38, v38 row_half_mirror row_mask:0xf bank_mask:0xf bound_ctrl:1
	ds_read_b128 v[64:67], v22 offset:34048
	ds_read_b128 v[52:55], v2 offset:51712
	v_add_f32_dpp v38, v38, v38 quad_perm:[1,0,3,2] row_mask:0xf bank_mask:0xf bound_ctrl:1
	ds_read_b128 v[56:59], v2 offset:51968
	ds_read_b128 v[68:71], v22 offset:34304
	v_add_f32_dpp v38, v38, v38 quad_perm:[2,3,0,1] row_mask:0xf bank_mask:0xf bound_ctrl:1
	ds_read_b128 v[60:63], v2 offset:52224
	s_nop 0
	v_mov_b32_dpp v39, v38 row_ror:8 row_mask:0xf bank_mask:0xf bound_ctrl:1
	v_pk_mul_f32 v[38:39], v[38:39], v[40:41] op_sel_hi:[1,0]
	v_cvt_pk_bf16_f32 v47, v38, v39
	s_mov_b64 exec, s[2:3]
	global_store_dword v46, v47, s[14:15] offset:-4096
	s_mov_b64 exec, -1
	s_waitcnt lgkmcnt(4)
	v_pk_mul_f32 v[42:43], v[72:73], v[48:49] op_sel_hi:[1,0]
	v_pk_fma_f32 v[6:7], v[6:7], v[64:65], v[42:43] op_sel:[0,0,0] op_sel_hi:[1,0,1]
	v_pk_mul_f32 v[38:39], v[6:7], v[48:49] op_sel:[0,1] op_sel_hi:[1,1]
	v_pk_mul_f32 v[44:45], v[72:73], v[50:51] op_sel_hi:[1,0]
	v_pk_fma_f32 v[8:9], v[8:9], v[64:65], v[44:45] op_sel:[0,1,0] op_sel_hi:[1,1,1]
	v_pk_fma_f32 v[38:39], v[8:9], v[50:51], v[38:39] op_sel:[0,1,0] op_sel_hi:[1,1,1]
	s_waitcnt lgkmcnt(3)
	v_pk_mul_f32 v[42:43], v[72:73], v[52:53] op_sel_hi:[1,0]
	v_pk_fma_f32 v[10:11], v[10:11], v[66:67], v[42:43] op_sel:[0,0,0] op_sel_hi:[1,0,1]
	v_pk_fma_f32 v[38:39], v[10:11], v[52:53], v[38:39] op_sel:[0,1,0] op_sel_hi:[1,1,1]
	v_pk_mul_f32 v[44:45], v[72:73], v[54:55] op_sel_hi:[1,0]
	v_pk_fma_f32 v[12:13], v[12:13], v[66:67], v[44:45] op_sel:[0,1,0] op_sel_hi:[1,1,1]
	v_pk_fma_f32 v[38:39], v[12:13], v[54:55], v[38:39] op_sel:[0,1,0] op_sel_hi:[1,1,1]
	s_waitcnt lgkmcnt(1)
	v_pk_mul_f32 v[42:43], v[72:73], v[56:57] op_sel_hi:[1,0]
	v_pk_fma_f32 v[14:15], v[14:15], v[68:69], v[42:43] op_sel:[0,0,0] op_sel_hi:[1,0,1]
	v_pk_fma_f32 v[38:39], v[14:15], v[56:57], v[38:39] op_sel:[0,1,0] op_sel_hi:[1,1,1]
	v_pk_mul_f32 v[44:45], v[72:73], v[58:59] op_sel_hi:[1,0]
	v_pk_fma_f32 v[16:17], v[16:17], v[68:69], v[44:45] op_sel:[0,1,0] op_sel_hi:[1,1,1]
	v_pk_fma_f32 v[38:39], v[16:17], v[58:59], v[38:39] op_sel:[0,1,0] op_sel_hi:[1,1,1]
	s_waitcnt lgkmcnt(0)
	v_pk_mul_f32 v[42:43], v[72:73], v[60:61] op_sel_hi:[1,0]
	v_pk_fma_f32 v[18:19], v[18:19], v[70:71], v[42:43] op_sel:[0,0,0] op_sel_hi:[1,0,1]
	v_pk_fma_f32 v[38:39], v[18:19], v[60:61], v[38:39] op_sel:[0,1,0] op_sel_hi:[1,1,1]
	v_pk_mul_f32 v[44:45], v[72:73], v[62:63] op_sel_hi:[1,0]
	v_pk_fma_f32 v[20:21], v[20:21], v[70:71], v[44:45] op_sel:[0,1,0] op_sel_hi:[1,1,1]
	v_pk_fma_f32 v[38:39], v[20:21], v[62:63], v[38:39] op_sel:[0,1,0] op_sel_hi:[1,1,1]
	s_add_u32 s14, s14, 0x1000
	s_addc_u32 s15, s15, 0
	v_add_f32_dpp v38, v38, v38 row_ror:8 row_mask:0xf bank_mask:0x3 bound_ctrl:1
	v_add_f32_dpp v38, v39, v39 row_ror:8 row_mask:0xf bank_mask:0xc bound_ctrl:1
	ds_read_b64 v[104:105], v23 offset:37888
	ds_read_b128 v[80:83], v2 offset:52480
	v_add_f32_dpp v38, v38, v38 row_half_mirror row_mask:0xf bank_mask:0xf bound_ctrl:1
	ds_read_b128 v[96:99], v22 offset:34560
	ds_read_b128 v[84:87], v2 offset:52736
	v_add_f32_dpp v38, v38, v38 quad_perm:[1,0,3,2] row_mask:0xf bank_mask:0xf bound_ctrl:1
	ds_read_b128 v[88:91], v2 offset:52992
	ds_read_b128 v[100:103], v22 offset:34816
	v_add_f32_dpp v38, v38, v38 quad_perm:[2,3,0,1] row_mask:0xf bank_mask:0xf bound_ctrl:1
	ds_read_b128 v[92:95], v2 offset:53248
	s_nop 0
	v_mov_b32_dpp v39, v38 row_ror:8 row_mask:0xf bank_mask:0xf bound_ctrl:1
	v_pk_mul_f32 v[38:39], v[38:39], v[40:41] op_sel_hi:[1,0]
	v_cvt_pk_bf16_f32 v47, v38, v39
	s_mov_b64 exec, s[2:3]
	global_store_dword v46, v47, s[14:15] offset:-4096
	s_mov_b64 exec, -1
	s_waitcnt lgkmcnt(4)
	v_pk_mul_f32 v[42:43], v[104:105], v[80:81] op_sel_hi:[1,0]
	v_pk_fma_f32 v[6:7], v[6:7], v[96:97], v[42:43] op_sel:[0,0,0] op_sel_hi:[1,0,1]
	v_pk_mul_f32 v[38:39], v[6:7], v[80:81] op_sel:[0,1] op_sel_hi:[1,1]
	v_pk_mul_f32 v[44:45], v[104:105], v[82:83] op_sel_hi:[1,0]
	v_pk_fma_f32 v[8:9], v[8:9], v[96:97], v[44:45] op_sel:[0,1,0] op_sel_hi:[1,1,1]
	v_pk_fma_f32 v[38:39], v[8:9], v[82:83], v[38:39] op_sel:[0,1,0] op_sel_hi:[1,1,1]
	s_waitcnt lgkmcnt(3)
	v_pk_mul_f32 v[42:43], v[104:105], v[84:85] op_sel_hi:[1,0]
	v_pk_fma_f32 v[10:11], v[10:11], v[98:99], v[42:43] op_sel:[0,0,0] op_sel_hi:[1,0,1]
	v_pk_fma_f32 v[38:39], v[10:11], v[84:85], v[38:39] op_sel:[0,1,0] op_sel_hi:[1,1,1]
	v_pk_mul_f32 v[44:45], v[104:105], v[86:87] op_sel_hi:[1,0]
	v_pk_fma_f32 v[12:13], v[12:13], v[98:99], v[44:45] op_sel:[0,1,0] op_sel_hi:[1,1,1]
	v_pk_fma_f32 v[38:39], v[12:13], v[86:87], v[38:39] op_sel:[0,1,0] op_sel_hi:[1,1,1]
	s_waitcnt lgkmcnt(1)
	v_pk_mul_f32 v[42:43], v[104:105], v[88:89] op_sel_hi:[1,0]
	v_pk_fma_f32 v[14:15], v[14:15], v[100:101], v[42:43] op_sel:[0,0,0] op_sel_hi:[1,0,1]
	v_pk_fma_f32 v[38:39], v[14:15], v[88:89], v[38:39] op_sel:[0,1,0] op_sel_hi:[1,1,1]
	v_pk_mul_f32 v[44:45], v[104:105], v[90:91] op_sel_hi:[1,0]
	v_pk_fma_f32 v[16:17], v[16:17], v[100:101], v[44:45] op_sel:[0,1,0] op_sel_hi:[1,1,1]
	v_pk_fma_f32 v[38:39], v[16:17], v[90:91], v[38:39] op_sel:[0,1,0] op_sel_hi:[1,1,1]
	s_waitcnt lgkmcnt(0)
	v_pk_mul_f32 v[42:43], v[104:105], v[92:93] op_sel_hi:[1,0]
	v_pk_fma_f32 v[18:19], v[18:19], v[102:103], v[42:43] op_sel:[0,0,0] op_sel_hi:[1,0,1]
	v_pk_fma_f32 v[38:39], v[18:19], v[92:93], v[38:39] op_sel:[0,1,0] op_sel_hi:[1,1,1]
	v_pk_mul_f32 v[44:45], v[104:105], v[94:95] op_sel_hi:[1,0]
	v_pk_fma_f32 v[20:21], v[20:21], v[102:103], v[44:45] op_sel:[0,1,0] op_sel_hi:[1,1,1]
	v_pk_fma_f32 v[38:39], v[20:21], v[94:95], v[38:39] op_sel:[0,1,0] op_sel_hi:[1,1,1]
	s_add_u32 s14, s14, 0x1000
	s_addc_u32 s15, s15, 0
	v_add_f32_dpp v38, v38, v38 row_ror:8 row_mask:0xf bank_mask:0x3 bound_ctrl:1
	v_add_f32_dpp v38, v39, v39 row_ror:8 row_mask:0xf bank_mask:0xc bound_ctrl:1
	ds_read_b64 v[72:73], v23 offset:38144
	ds_read_b128 v[48:51], v2 offset:53504
	v_add_f32_dpp v38, v38, v38 row_half_mirror row_mask:0xf bank_mask:0xf bound_ctrl:1
	ds_read_b128 v[64:67], v22 offset:35072
	ds_read_b128 v[52:55], v2 offset:53760
	v_add_f32_dpp v38, v38, v38 quad_perm:[1,0,3,2] row_mask:0xf bank_mask:0xf bound_ctrl:1
	ds_read_b128 v[56:59], v2 offset:54016
	ds_read_b128 v[68:71], v22 offset:35328
	v_add_f32_dpp v38, v38, v38 quad_perm:[2,3,0,1] row_mask:0xf bank_mask:0xf bound_ctrl:1
	ds_read_b128 v[60:63], v2 offset:54272
	s_nop 0
	v_mov_b32_dpp v39, v38 row_ror:8 row_mask:0xf bank_mask:0xf bound_ctrl:1
	v_pk_mul_f32 v[38:39], v[38:39], v[40:41] op_sel_hi:[1,0]
	v_cvt_pk_bf16_f32 v47, v38, v39
	s_mov_b64 exec, s[2:3]
	global_store_dword v46, v47, s[14:15] offset:-4096
	s_mov_b64 exec, -1
	s_waitcnt lgkmcnt(4)
	v_pk_mul_f32 v[42:43], v[72:73], v[48:49] op_sel_hi:[1,0]
	v_pk_fma_f32 v[6:7], v[6:7], v[64:65], v[42:43] op_sel:[0,0,0] op_sel_hi:[1,0,1]
	v_pk_mul_f32 v[38:39], v[6:7], v[48:49] op_sel:[0,1] op_sel_hi:[1,1]
	v_pk_mul_f32 v[44:45], v[72:73], v[50:51] op_sel_hi:[1,0]
	v_pk_fma_f32 v[8:9], v[8:9], v[64:65], v[44:45] op_sel:[0,1,0] op_sel_hi:[1,1,1]
	v_pk_fma_f32 v[38:39], v[8:9], v[50:51], v[38:39] op_sel:[0,1,0] op_sel_hi:[1,1,1]
	s_waitcnt lgkmcnt(3)
	v_pk_mul_f32 v[42:43], v[72:73], v[52:53] op_sel_hi:[1,0]
	v_pk_fma_f32 v[10:11], v[10:11], v[66:67], v[42:43] op_sel:[0,0,0] op_sel_hi:[1,0,1]
	v_pk_fma_f32 v[38:39], v[10:11], v[52:53], v[38:39] op_sel:[0,1,0] op_sel_hi:[1,1,1]
	v_pk_mul_f32 v[44:45], v[72:73], v[54:55] op_sel_hi:[1,0]
	v_pk_fma_f32 v[12:13], v[12:13], v[66:67], v[44:45] op_sel:[0,1,0] op_sel_hi:[1,1,1]
	v_pk_fma_f32 v[38:39], v[12:13], v[54:55], v[38:39] op_sel:[0,1,0] op_sel_hi:[1,1,1]
	s_waitcnt lgkmcnt(1)
	v_pk_mul_f32 v[42:43], v[72:73], v[56:57] op_sel_hi:[1,0]
	v_pk_fma_f32 v[14:15], v[14:15], v[68:69], v[42:43] op_sel:[0,0,0] op_sel_hi:[1,0,1]
	v_pk_fma_f32 v[38:39], v[14:15], v[56:57], v[38:39] op_sel:[0,1,0] op_sel_hi:[1,1,1]
	v_pk_mul_f32 v[44:45], v[72:73], v[58:59] op_sel_hi:[1,0]
	v_pk_fma_f32 v[16:17], v[16:17], v[68:69], v[44:45] op_sel:[0,1,0] op_sel_hi:[1,1,1]
	v_pk_fma_f32 v[38:39], v[16:17], v[58:59], v[38:39] op_sel:[0,1,0] op_sel_hi:[1,1,1]
	s_waitcnt lgkmcnt(0)
	v_pk_mul_f32 v[42:43], v[72:73], v[60:61] op_sel_hi:[1,0]
	v_pk_fma_f32 v[18:19], v[18:19], v[70:71], v[42:43] op_sel:[0,0,0] op_sel_hi:[1,0,1]
	v_pk_fma_f32 v[38:39], v[18:19], v[60:61], v[38:39] op_sel:[0,1,0] op_sel_hi:[1,1,1]
	v_pk_mul_f32 v[44:45], v[72:73], v[62:63] op_sel_hi:[1,0]
	v_pk_fma_f32 v[20:21], v[20:21], v[70:71], v[44:45] op_sel:[0,1,0] op_sel_hi:[1,1,1]
	v_pk_fma_f32 v[38:39], v[20:21], v[62:63], v[38:39] op_sel:[0,1,0] op_sel_hi:[1,1,1]
	s_add_u32 s14, s14, 0x1000
	s_addc_u32 s15, s15, 0
	v_add_f32_dpp v38, v38, v38 row_ror:8 row_mask:0xf bank_mask:0x3 bound_ctrl:1
	v_add_f32_dpp v38, v39, v39 row_ror:8 row_mask:0xf bank_mask:0xc bound_ctrl:1
	ds_read_b64 v[104:105], v23 offset:38400
	ds_read_b128 v[80:83], v2 offset:54528
	v_add_f32_dpp v38, v38, v38 row_half_mirror row_mask:0xf bank_mask:0xf bound_ctrl:1
	ds_read_b128 v[96:99], v22 offset:35584
	ds_read_b128 v[84:87], v2 offset:54784
	v_add_f32_dpp v38, v38, v38 quad_perm:[1,0,3,2] row_mask:0xf bank_mask:0xf bound_ctrl:1
	ds_read_b128 v[88:91], v2 offset:55040
	ds_read_b128 v[100:103], v22 offset:35840
	v_add_f32_dpp v38, v38, v38 quad_perm:[2,3,0,1] row_mask:0xf bank_mask:0xf bound_ctrl:1
	ds_read_b128 v[92:95], v2 offset:55296
	s_nop 0
	v_mov_b32_dpp v39, v38 row_ror:8 row_mask:0xf bank_mask:0xf bound_ctrl:1
	v_pk_mul_f32 v[38:39], v[38:39], v[40:41] op_sel_hi:[1,0]
	v_cvt_pk_bf16_f32 v47, v38, v39
	s_mov_b64 exec, s[2:3]
	global_store_dword v46, v47, s[14:15] offset:-4096
	s_mov_b64 exec, -1
	s_waitcnt lgkmcnt(4)
	v_pk_mul_f32 v[42:43], v[104:105], v[80:81] op_sel_hi:[1,0]
	v_pk_fma_f32 v[6:7], v[6:7], v[96:97], v[42:43] op_sel:[0,0,0] op_sel_hi:[1,0,1]
	v_pk_mul_f32 v[38:39], v[6:7], v[80:81] op_sel:[0,1] op_sel_hi:[1,1]
	v_pk_mul_f32 v[44:45], v[104:105], v[82:83] op_sel_hi:[1,0]
	v_pk_fma_f32 v[8:9], v[8:9], v[96:97], v[44:45] op_sel:[0,1,0] op_sel_hi:[1,1,1]
	v_pk_fma_f32 v[38:39], v[8:9], v[82:83], v[38:39] op_sel:[0,1,0] op_sel_hi:[1,1,1]
	s_waitcnt lgkmcnt(3)
	v_pk_mul_f32 v[42:43], v[104:105], v[84:85] op_sel_hi:[1,0]
	v_pk_fma_f32 v[10:11], v[10:11], v[98:99], v[42:43] op_sel:[0,0,0] op_sel_hi:[1,0,1]
	v_pk_fma_f32 v[38:39], v[10:11], v[84:85], v[38:39] op_sel:[0,1,0] op_sel_hi:[1,1,1]
	v_pk_mul_f32 v[44:45], v[104:105], v[86:87] op_sel_hi:[1,0]
	v_pk_fma_f32 v[12:13], v[12:13], v[98:99], v[44:45] op_sel:[0,1,0] op_sel_hi:[1,1,1]
	v_pk_fma_f32 v[38:39], v[12:13], v[86:87], v[38:39] op_sel:[0,1,0] op_sel_hi:[1,1,1]
	s_waitcnt lgkmcnt(1)
	v_pk_mul_f32 v[42:43], v[104:105], v[88:89] op_sel_hi:[1,0]
	v_pk_fma_f32 v[14:15], v[14:15], v[100:101], v[42:43] op_sel:[0,0,0] op_sel_hi:[1,0,1]
	v_pk_fma_f32 v[38:39], v[14:15], v[88:89], v[38:39] op_sel:[0,1,0] op_sel_hi:[1,1,1]
	v_pk_mul_f32 v[44:45], v[104:105], v[90:91] op_sel_hi:[1,0]
	v_pk_fma_f32 v[16:17], v[16:17], v[100:101], v[44:45] op_sel:[0,1,0] op_sel_hi:[1,1,1]
	v_pk_fma_f32 v[38:39], v[16:17], v[90:91], v[38:39] op_sel:[0,1,0] op_sel_hi:[1,1,1]
	s_waitcnt lgkmcnt(0)
	v_pk_mul_f32 v[42:43], v[104:105], v[92:93] op_sel_hi:[1,0]
	v_pk_fma_f32 v[18:19], v[18:19], v[102:103], v[42:43] op_sel:[0,0,0] op_sel_hi:[1,0,1]
	v_pk_fma_f32 v[38:39], v[18:19], v[92:93], v[38:39] op_sel:[0,1,0] op_sel_hi:[1,1,1]
	v_pk_mul_f32 v[44:45], v[104:105], v[94:95] op_sel_hi:[1,0]
	v_pk_fma_f32 v[20:21], v[20:21], v[102:103], v[44:45] op_sel:[0,1,0] op_sel_hi:[1,1,1]
	v_pk_fma_f32 v[38:39], v[20:21], v[94:95], v[38:39] op_sel:[0,1,0] op_sel_hi:[1,1,1]
	s_add_u32 s14, s14, 0x1000
	s_addc_u32 s15, s15, 0
	v_add_f32_dpp v38, v38, v38 row_ror:8 row_mask:0xf bank_mask:0x3 bound_ctrl:1
	v_add_f32_dpp v38, v39, v39 row_ror:8 row_mask:0xf bank_mask:0xc bound_ctrl:1
	ds_read_b64 v[72:73], v23 offset:38656
	ds_read_b128 v[48:51], v2 offset:55552
	v_add_f32_dpp v38, v38, v38 row_half_mirror row_mask:0xf bank_mask:0xf bound_ctrl:1
	ds_read_b128 v[64:67], v22 offset:36096
	ds_read_b128 v[52:55], v2 offset:55808
	v_add_f32_dpp v38, v38, v38 quad_perm:[1,0,3,2] row_mask:0xf bank_mask:0xf bound_ctrl:1
	ds_read_b128 v[56:59], v2 offset:56064
	ds_read_b128 v[68:71], v22 offset:36352
	v_add_f32_dpp v38, v38, v38 quad_perm:[2,3,0,1] row_mask:0xf bank_mask:0xf bound_ctrl:1
	ds_read_b128 v[60:63], v2 offset:56320
	s_nop 0
	v_mov_b32_dpp v39, v38 row_ror:8 row_mask:0xf bank_mask:0xf bound_ctrl:1
	v_pk_mul_f32 v[38:39], v[38:39], v[40:41] op_sel_hi:[1,0]
	v_cvt_pk_bf16_f32 v47, v38, v39
	s_mov_b64 exec, s[2:3]
	global_store_dword v46, v47, s[14:15] offset:-4096
	s_mov_b64 exec, -1
	s_waitcnt lgkmcnt(4)
	v_pk_mul_f32 v[42:43], v[72:73], v[48:49] op_sel_hi:[1,0]
	v_pk_fma_f32 v[6:7], v[6:7], v[64:65], v[42:43] op_sel:[0,0,0] op_sel_hi:[1,0,1]
	v_pk_mul_f32 v[38:39], v[6:7], v[48:49] op_sel:[0,1] op_sel_hi:[1,1]
	v_pk_mul_f32 v[44:45], v[72:73], v[50:51] op_sel_hi:[1,0]
	v_pk_fma_f32 v[8:9], v[8:9], v[64:65], v[44:45] op_sel:[0,1,0] op_sel_hi:[1,1,1]
	v_pk_fma_f32 v[38:39], v[8:9], v[50:51], v[38:39] op_sel:[0,1,0] op_sel_hi:[1,1,1]
	s_waitcnt lgkmcnt(3)
	v_pk_mul_f32 v[42:43], v[72:73], v[52:53] op_sel_hi:[1,0]
	v_pk_fma_f32 v[10:11], v[10:11], v[66:67], v[42:43] op_sel:[0,0,0] op_sel_hi:[1,0,1]
	v_pk_fma_f32 v[38:39], v[10:11], v[52:53], v[38:39] op_sel:[0,1,0] op_sel_hi:[1,1,1]
	v_pk_mul_f32 v[44:45], v[72:73], v[54:55] op_sel_hi:[1,0]
	v_pk_fma_f32 v[12:13], v[12:13], v[66:67], v[44:45] op_sel:[0,1,0] op_sel_hi:[1,1,1]
	v_pk_fma_f32 v[38:39], v[12:13], v[54:55], v[38:39] op_sel:[0,1,0] op_sel_hi:[1,1,1]
	s_waitcnt lgkmcnt(1)
	v_pk_mul_f32 v[42:43], v[72:73], v[56:57] op_sel_hi:[1,0]
	v_pk_fma_f32 v[14:15], v[14:15], v[68:69], v[42:43] op_sel:[0,0,0] op_sel_hi:[1,0,1]
	v_pk_fma_f32 v[38:39], v[14:15], v[56:57], v[38:39] op_sel:[0,1,0] op_sel_hi:[1,1,1]
	v_pk_mul_f32 v[44:45], v[72:73], v[58:59] op_sel_hi:[1,0]
	v_pk_fma_f32 v[16:17], v[16:17], v[68:69], v[44:45] op_sel:[0,1,0] op_sel_hi:[1,1,1]
	v_pk_fma_f32 v[38:39], v[16:17], v[58:59], v[38:39] op_sel:[0,1,0] op_sel_hi:[1,1,1]
	s_waitcnt lgkmcnt(0)
	v_pk_mul_f32 v[42:43], v[72:73], v[60:61] op_sel_hi:[1,0]
	v_pk_fma_f32 v[18:19], v[18:19], v[70:71], v[42:43] op_sel:[0,0,0] op_sel_hi:[1,0,1]
	v_pk_fma_f32 v[38:39], v[18:19], v[60:61], v[38:39] op_sel:[0,1,0] op_sel_hi:[1,1,1]
	v_pk_mul_f32 v[44:45], v[72:73], v[62:63] op_sel_hi:[1,0]
	v_pk_fma_f32 v[20:21], v[20:21], v[70:71], v[44:45] op_sel:[0,1,0] op_sel_hi:[1,1,1]
	v_pk_fma_f32 v[38:39], v[20:21], v[62:63], v[38:39] op_sel:[0,1,0] op_sel_hi:[1,1,1]
	s_add_u32 s14, s14, 0x1000
	s_addc_u32 s15, s15, 0
	v_add_f32_dpp v38, v38, v38 row_ror:8 row_mask:0xf bank_mask:0x3 bound_ctrl:1
	v_add_f32_dpp v38, v39, v39 row_ror:8 row_mask:0xf bank_mask:0xc bound_ctrl:1
	ds_read_b64 v[104:105], v23 offset:38912
	ds_read_b128 v[80:83], v2 offset:56576
	v_add_f32_dpp v38, v38, v38 row_half_mirror row_mask:0xf bank_mask:0xf bound_ctrl:1
	ds_read_b128 v[96:99], v22 offset:36608
	ds_read_b128 v[84:87], v2 offset:56832
	v_add_f32_dpp v38, v38, v38 quad_perm:[1,0,3,2] row_mask:0xf bank_mask:0xf bound_ctrl:1
	ds_read_b128 v[88:91], v2 offset:57088
	ds_read_b128 v[100:103], v22 offset:36864
	v_add_f32_dpp v38, v38, v38 quad_perm:[2,3,0,1] row_mask:0xf bank_mask:0xf bound_ctrl:1
	ds_read_b128 v[92:95], v2 offset:57344
	s_nop 0
	v_mov_b32_dpp v39, v38 row_ror:8 row_mask:0xf bank_mask:0xf bound_ctrl:1
	v_pk_mul_f32 v[38:39], v[38:39], v[40:41] op_sel_hi:[1,0]
	v_cvt_pk_bf16_f32 v47, v38, v39
	s_mov_b64 exec, s[2:3]
	global_store_dword v46, v47, s[14:15] offset:-4096
	s_mov_b64 exec, -1
	s_waitcnt lgkmcnt(4)
	v_pk_mul_f32 v[42:43], v[104:105], v[80:81] op_sel_hi:[1,0]
	v_pk_fma_f32 v[6:7], v[6:7], v[96:97], v[42:43] op_sel:[0,0,0] op_sel_hi:[1,0,1]
	v_pk_mul_f32 v[38:39], v[6:7], v[80:81] op_sel:[0,1] op_sel_hi:[1,1]
	v_pk_mul_f32 v[44:45], v[104:105], v[82:83] op_sel_hi:[1,0]
	v_pk_fma_f32 v[8:9], v[8:9], v[96:97], v[44:45] op_sel:[0,1,0] op_sel_hi:[1,1,1]
	v_pk_fma_f32 v[38:39], v[8:9], v[82:83], v[38:39] op_sel:[0,1,0] op_sel_hi:[1,1,1]
	s_waitcnt lgkmcnt(3)
	v_pk_mul_f32 v[42:43], v[104:105], v[84:85] op_sel_hi:[1,0]
	v_pk_fma_f32 v[10:11], v[10:11], v[98:99], v[42:43] op_sel:[0,0,0] op_sel_hi:[1,0,1]
	v_pk_fma_f32 v[38:39], v[10:11], v[84:85], v[38:39] op_sel:[0,1,0] op_sel_hi:[1,1,1]
	v_pk_mul_f32 v[44:45], v[104:105], v[86:87] op_sel_hi:[1,0]
	v_pk_fma_f32 v[12:13], v[12:13], v[98:99], v[44:45] op_sel:[0,1,0] op_sel_hi:[1,1,1]
	v_pk_fma_f32 v[38:39], v[12:13], v[86:87], v[38:39] op_sel:[0,1,0] op_sel_hi:[1,1,1]
	s_waitcnt lgkmcnt(1)
	v_pk_mul_f32 v[42:43], v[104:105], v[88:89] op_sel_hi:[1,0]
	v_pk_fma_f32 v[14:15], v[14:15], v[100:101], v[42:43] op_sel:[0,0,0] op_sel_hi:[1,0,1]
	v_pk_fma_f32 v[38:39], v[14:15], v[88:89], v[38:39] op_sel:[0,1,0] op_sel_hi:[1,1,1]
	v_pk_mul_f32 v[44:45], v[104:105], v[90:91] op_sel_hi:[1,0]
	v_pk_fma_f32 v[16:17], v[16:17], v[100:101], v[44:45] op_sel:[0,1,0] op_sel_hi:[1,1,1]
	v_pk_fma_f32 v[38:39], v[16:17], v[90:91], v[38:39] op_sel:[0,1,0] op_sel_hi:[1,1,1]
	s_waitcnt lgkmcnt(0)
	v_pk_mul_f32 v[42:43], v[104:105], v[92:93] op_sel_hi:[1,0]
	v_pk_fma_f32 v[18:19], v[18:19], v[102:103], v[42:43] op_sel:[0,0,0] op_sel_hi:[1,0,1]
	v_pk_fma_f32 v[38:39], v[18:19], v[92:93], v[38:39] op_sel:[0,1,0] op_sel_hi:[1,1,1]
	v_pk_mul_f32 v[44:45], v[104:105], v[94:95] op_sel_hi:[1,0]
	v_pk_fma_f32 v[20:21], v[20:21], v[102:103], v[44:45] op_sel:[0,1,0] op_sel_hi:[1,1,1]
	v_pk_fma_f32 v[38:39], v[20:21], v[94:95], v[38:39] op_sel:[0,1,0] op_sel_hi:[1,1,1]
	s_add_u32 s14, s14, 0x1000
	s_addc_u32 s15, s15, 0
	v_add_f32_dpp v38, v38, v38 row_ror:8 row_mask:0xf bank_mask:0x3 bound_ctrl:1
	v_add_f32_dpp v38, v39, v39 row_ror:8 row_mask:0xf bank_mask:0xc bound_ctrl:1
	ds_read_b64 v[72:73], v3 offset:20736
	ds_read_b128 v[48:51], v2 offset:256
	v_add_f32_dpp v38, v38, v38 row_half_mirror row_mask:0xf bank_mask:0xf bound_ctrl:1
	ds_read_b128 v[64:67], v2 offset:16640
	ds_read_b128 v[52:55], v2 offset:512
	v_add_f32_dpp v38, v38, v38 quad_perm:[1,0,3,2] row_mask:0xf bank_mask:0xf bound_ctrl:1
	ds_read_b128 v[56:59], v2 offset:768
	ds_read_b128 v[68:71], v2 offset:16896
	v_add_f32_dpp v38, v38, v38 quad_perm:[2,3,0,1] row_mask:0xf bank_mask:0xf bound_ctrl:1
	ds_read_b128 v[60:63], v2 offset:1024
	s_nop 0
	v_mov_b32_dpp v39, v38 row_ror:8 row_mask:0xf bank_mask:0xf bound_ctrl:1
	v_pk_mul_f32 v[38:39], v[38:39], v[40:41] op_sel_hi:[1,0]
	v_cvt_pk_bf16_f32 v47, v38, v39
	s_mov_b64 exec, s[2:3]
	global_store_dword v46, v47, s[14:15] offset:-4096
	s_mov_b64 exec, -1
	s_waitcnt vmcnt(8)
	v_lshlrev_b32_e32 v144, 16, v110
	v_lshlrev_b32_e32 v145, 16, v111
	v_and_b32_e32 v146, s17, v110
	v_and_b32_e32 v147, s17, v111
	v_lshlrev_b32_e32 v148, 16, v112
	v_lshlrev_b32_e32 v149, 16, v113
	v_and_b32_e32 v150, s17, v112
	v_and_b32_e32 v151, s17, v113
	v_lshlrev_b32_e32 v152, 16, v114
	v_and_b32_e32 v153, s17, v114
	ds_write_b128 v29, v[144:147] offset:24832
	ds_write_b128 v29, v[148:151] offset:33024
	ds_write_b64 v30, v[116:117] offset:24832
	ds_write_b64 v31, v[152:153] offset:24832
	s_add_i32 s16, s16, 8
	s_waitcnt lgkmcnt(0)
	s_barrier
	s_cmpk_lt_u32 s16, 0x800
	s_cbranch_scc1 .Lgla2_loop
